# gMLP stats loop: software-prefetch next 4-load group into spare VGPRs (v176-191) to hide load latency
# speedup vs baseline: 1.0127x; 1.0054x over previous
.LBB0_618:
	s_andn2_b64 vcc, exec, s[0:1]
	s_cbranch_vccnz .LBB0_639
	s_cmpk_gt_i32 s10, 0x7f
	s_cbranch_scc0 .LBB0_625
	s_add_i32 s38, s10, 0xffffff80
	s_lshl_b32 s0, s38, 5
	v_mov_b32_e32 v50, v194
	v_readlane_b32 s40, v251, 54
	s_and_b32 s4, s0, 0x7fffff80
	v_readlane_b32 s46, v251, 60
	v_bfe_u32 v31, v50, 1, 7
	v_readlane_b32 s47, v251, 61
	v_and_b32_e32 v18, 1, v50
	v_or_b32_e32 v0, s4, v31
	v_mov_b64_e32 v[2:3], s[46:47]
	v_mad_u64_u32 v[10:11], s[0:1], v0, s3, v[2:3]
	v_lshlrev_b32_e32 v0, 9, v18
	v_mov_b32_e32 v14, 0
	v_lshrrev_b32_e32 v30, 1, v50
	v_lshl_add_u64 v[12:13], v[10:11], 0, v[0:1]
	v_readfirstlane_b32 s64, v194
	s_lshr_b32 s64, s64, 8
	s_lshl_b32 s0, s64, 8
	s_mov_b32 s1, 0
	s_add_i32 s65, s0, 0x100
	v_mov_b32_e32 v15, v14
	v_readlane_b32 s41, v251, 55
	v_readlane_b32 s42, v251, 56
	v_readlane_b32 s43, v251, 57
	v_readlane_b32 s44, v251, 58
	v_readlane_b32 s45, v251, 59
	v_readlane_b32 s48, v251, 62
	v_readlane_b32 s49, v251, 63
	v_readlane_b32 s50, v252, 0
	v_readlane_b32 s51, v252, 1
	v_readlane_b32 s52, v252, 2
	v_readlane_b32 s53, v252, 3
	v_readlane_b32 s54, v252, 4
	v_readlane_b32 s55, v252, 5
	v_lshl_add_u64 v[172:173], v[12:13], 0, s[0:1]
	global_load_dwordx4 v[176:179], v[172:173], off offset:1072
	global_load_dwordx4 v[180:183], v[172:173], off offset:1056
	global_load_dwordx4 v[184:187], v[172:173], off offset:1040
	global_load_dwordx4 v[188:191], v[172:173], off offset:1024
.LBB0_621:
	s_add_u32 s0, s0, 0x80
	s_addc_u32 s1, s1, 0
	s_waitcnt vmcnt(0)
	v_mov_b32_e32 v2, v176
	v_mov_b32_e32 v3, v177
	v_mov_b32_e32 v4, v178
	v_mov_b32_e32 v5, v179
	v_mov_b32_e32 v6, v180
	v_mov_b32_e32 v7, v181
	v_mov_b32_e32 v8, v182
	v_mov_b32_e32 v9, v183
	v_mov_b32_e32 v20, v184
	v_mov_b32_e32 v21, v185
	v_mov_b32_e32 v22, v186
	v_mov_b32_e32 v23, v187
	v_mov_b32_e32 v24, v188
	v_mov_b32_e32 v25, v189
	v_mov_b32_e32 v26, v190
	v_mov_b32_e32 v27, v191
	global_load_dwordx4 v[176:179], v[172:173], off offset:1136
	global_load_dwordx4 v[180:183], v[172:173], off offset:1120
	global_load_dwordx4 v[184:187], v[172:173], off offset:1104
	global_load_dwordx4 v[188:191], v[172:173], off offset:1088
	s_cmp_lg_u32 s0, s65
	v_lshlrev_b32_e32 v0, 16, v24
	v_mul_f32_e32 v19, v0, v0
	v_fmamk_f32 v19, v19, 0xbdd2d3e7, v129
	v_mul_f32_e32 v19, v19, v0
	v_exp_f32_e32 v19, v19
	v_and_b32_e32 v40, 0xffff0000, v27
	v_add_f32_e32 v19, 1.0, v19
	v_rcp_f32_e32 v19, v19
	s_nop 0
	v_mul_f32_e32 v29, v19, v0
	v_and_b32_e32 v0, 0xffff0000, v24
	v_mul_f32_e32 v19, v0, v0
	v_fmamk_f32 v19, v19, 0xbdd2d3e7, v129
	v_mul_f32_e32 v19, v19, v0
	v_exp_f32_e32 v19, v19
	v_mul_f32_e32 v28, v29, v29
	v_add_f32_e32 v19, 1.0, v19
	v_rcp_f32_e32 v19, v19
	s_nop 0
	v_mul_f32_e32 v33, v19, v0
	v_lshlrev_b32_e32 v0, 16, v25
	v_mul_f32_e32 v19, v0, v0
	v_fmamk_f32 v19, v19, 0xbdd2d3e7, v129
	v_mul_f32_e32 v19, v19, v0
	v_exp_f32_e32 v19, v19
	v_mul_f32_e32 v32, v33, v33
	v_add_f32_e32 v19, 1.0, v19
	v_rcp_f32_e32 v19, v19
	s_nop 0
	v_mul_f32_e32 v35, v19, v0
	v_and_b32_e32 v0, 0xffff0000, v25
	v_mul_f32_e32 v19, v0, v0
	v_fmamk_f32 v19, v19, 0xbdd2d3e7, v129
	v_mul_f32_e32 v19, v19, v0
	v_exp_f32_e32 v19, v19
	v_mul_f32_e32 v34, v35, v35
	v_add_f32_e32 v19, 1.0, v19
	v_rcp_f32_e32 v19, v19
	s_nop 0
	v_mul_f32_e32 v25, v19, v0
	v_lshlrev_b32_e32 v0, 16, v26
	v_mul_f32_e32 v19, v0, v0
	v_fmamk_f32 v19, v19, 0xbdd2d3e7, v129
	v_mul_f32_e32 v19, v19, v0
	v_exp_f32_e32 v19, v19
	v_mul_f32_e32 v24, v25, v25
	v_pk_add_f32 v[24:25], v[34:35], v[24:25]
	v_add_f32_e32 v19, 1.0, v19
	v_rcp_f32_e32 v19, v19
	s_nop 0
	v_mul_f32_e32 v37, v19, v0
	v_and_b32_e32 v0, 0xffff0000, v26
	v_mul_f32_e32 v19, v0, v0
	v_fmamk_f32 v19, v19, 0xbdd2d3e7, v129
	v_mul_f32_e32 v19, v19, v0
	v_exp_f32_e32 v19, v19
	v_mul_f32_e32 v26, v40, v40
	v_fmamk_f32 v26, v26, 0xbdd2d3e7, v129
	v_mul_f32_e32 v26, v26, v40
	v_add_f32_e32 v19, 1.0, v19
	v_rcp_f32_e32 v19, v19
	v_exp_f32_e32 v26, v26
	v_mul_f32_e32 v39, v19, v0
	v_lshlrev_b32_e32 v0, 16, v27
	v_mul_f32_e32 v19, v0, v0
	v_fmamk_f32 v19, v19, 0xbdd2d3e7, v129
	v_mul_f32_e32 v19, v19, v0
	v_exp_f32_e32 v19, v19
	v_add_f32_e32 v26, 1.0, v26
	v_rcp_f32_e32 v41, v26
	v_pk_add_f32 v[26:27], v[28:29], v[32:33]
	v_add_f32_e32 v19, 1.0, v19
	v_rcp_f32_e32 v19, v19
	v_mul_f32_e32 v36, v37, v37
	v_mul_f32_e32 v38, v39, v39
	v_pk_add_f32 v[14:15], v[14:15], v[26:27]
	v_mul_f32_e32 v27, v41, v40
	v_pk_add_f32 v[14:15], v[14:15], v[24:25]
	v_pk_add_f32 v[24:25], v[36:37], v[38:39]
	v_mul_f32_e32 v26, v27, v27
	v_pk_add_f32 v[14:15], v[14:15], v[24:25]
	v_mul_f32_e32 v25, v19, v0
	v_lshlrev_b32_e32 v0, 16, v20
	v_mul_f32_e32 v19, v0, v0
	v_fmamk_f32 v19, v19, 0xbdd2d3e7, v129
	v_mul_f32_e32 v19, v19, v0
	v_exp_f32_e32 v19, v19
	v_mul_f32_e32 v24, v25, v25
	v_pk_add_f32 v[24:25], v[24:25], v[26:27]
	v_and_b32_e32 v36, 0xffff0000, v23
	v_add_f32_e32 v19, 1.0, v19
	v_rcp_f32_e32 v19, v19
	v_pk_add_f32 v[14:15], v[14:15], v[24:25]
	v_mul_f32_e32 v25, v19, v0
	v_and_b32_e32 v0, 0xffff0000, v20
	v_mul_f32_e32 v19, v0, v0
	v_fmamk_f32 v19, v19, 0xbdd2d3e7, v129
	v_mul_f32_e32 v19, v19, v0
	v_exp_f32_e32 v19, v19
	v_mul_f32_e32 v24, v25, v25
	v_add_f32_e32 v19, 1.0, v19
	v_rcp_f32_e32 v19, v19
	s_nop 0
	v_mul_f32_e32 v27, v19, v0
	v_lshlrev_b32_e32 v0, 16, v21
	v_mul_f32_e32 v19, v0, v0
	v_fmamk_f32 v19, v19, 0xbdd2d3e7, v129
	v_mul_f32_e32 v19, v19, v0
	v_exp_f32_e32 v19, v19
	v_mul_f32_e32 v26, v27, v27
	v_add_f32_e32 v19, 1.0, v19
	v_rcp_f32_e32 v19, v19
	s_nop 0
	v_mul_f32_e32 v29, v19, v0
	v_and_b32_e32 v0, 0xffff0000, v21
	v_mul_f32_e32 v19, v0, v0
	v_fmamk_f32 v19, v19, 0xbdd2d3e7, v129
	v_mul_f32_e32 v19, v19, v0
	v_exp_f32_e32 v19, v19
	v_mul_f32_e32 v28, v29, v29
	v_add_f32_e32 v19, 1.0, v19
	v_rcp_f32_e32 v19, v19
	s_nop 0
	v_mul_f32_e32 v21, v19, v0
	v_lshlrev_b32_e32 v0, 16, v22
	v_mul_f32_e32 v19, v0, v0
	v_fmamk_f32 v19, v19, 0xbdd2d3e7, v129
	v_mul_f32_e32 v19, v19, v0
	v_exp_f32_e32 v19, v19
	v_mul_f32_e32 v20, v21, v21
	v_pk_add_f32 v[20:21], v[28:29], v[20:21]
	v_add_f32_e32 v19, 1.0, v19
	v_rcp_f32_e32 v19, v19
	s_nop 0
	v_mul_f32_e32 v33, v19, v0
	v_and_b32_e32 v0, 0xffff0000, v22
	v_mul_f32_e32 v19, v0, v0
	v_fmamk_f32 v19, v19, 0xbdd2d3e7, v129
	v_mul_f32_e32 v19, v19, v0
	v_exp_f32_e32 v19, v19
	v_mul_f32_e32 v22, v36, v36
	v_fmamk_f32 v22, v22, 0xbdd2d3e7, v129
	v_mul_f32_e32 v22, v22, v36
	v_add_f32_e32 v19, 1.0, v19
	v_rcp_f32_e32 v19, v19
	v_exp_f32_e32 v22, v22
	v_mul_f32_e32 v35, v19, v0
	v_lshlrev_b32_e32 v0, 16, v23
	v_mul_f32_e32 v19, v0, v0
	v_fmamk_f32 v19, v19, 0xbdd2d3e7, v129
	v_mul_f32_e32 v19, v19, v0
	v_exp_f32_e32 v19, v19
	v_add_f32_e32 v22, 1.0, v22
	v_rcp_f32_e32 v37, v22
	v_pk_add_f32 v[22:23], v[24:25], v[26:27]
	v_add_f32_e32 v19, 1.0, v19
	v_rcp_f32_e32 v19, v19
	v_mul_f32_e32 v32, v33, v33
	v_mul_f32_e32 v34, v35, v35
	v_pk_add_f32 v[14:15], v[14:15], v[22:23]
	v_mul_f32_e32 v23, v37, v36
	v_pk_add_f32 v[14:15], v[14:15], v[20:21]
	v_pk_add_f32 v[20:21], v[32:33], v[34:35]
	v_mul_f32_e32 v22, v23, v23
	v_pk_add_f32 v[14:15], v[14:15], v[20:21]
	v_mul_f32_e32 v21, v19, v0
	v_lshlrev_b32_e32 v0, 16, v6
	v_mul_f32_e32 v19, v0, v0
	v_fmamk_f32 v19, v19, 0xbdd2d3e7, v129
	v_mul_f32_e32 v19, v19, v0
	v_exp_f32_e32 v19, v19
	v_mul_f32_e32 v20, v21, v21
	v_pk_add_f32 v[20:21], v[20:21], v[22:23]
	v_and_b32_e32 v32, 0xffff0000, v9
	v_add_f32_e32 v19, 1.0, v19
	v_rcp_f32_e32 v19, v19
	v_pk_add_f32 v[14:15], v[14:15], v[20:21]
	v_mul_f32_e32 v21, v19, v0
	v_and_b32_e32 v0, 0xffff0000, v6
	v_mul_f32_e32 v6, v0, v0
	v_fmamk_f32 v6, v6, 0xbdd2d3e7, v129
	v_mul_f32_e32 v6, v6, v0
	v_exp_f32_e32 v6, v6
	v_mul_f32_e32 v20, v21, v21
	v_add_f32_e32 v6, 1.0, v6
	v_rcp_f32_e32 v6, v6
	s_nop 0
	v_mul_f32_e32 v23, v6, v0
	v_lshlrev_b32_e32 v0, 16, v7
	v_mul_f32_e32 v6, v0, v0
	v_fmamk_f32 v6, v6, 0xbdd2d3e7, v129
	v_mul_f32_e32 v6, v6, v0
	v_exp_f32_e32 v6, v6
	v_mul_f32_e32 v22, v23, v23
	v_add_f32_e32 v6, 1.0, v6
	v_rcp_f32_e32 v6, v6
	s_nop 0
	v_mul_f32_e32 v25, v6, v0
	v_and_b32_e32 v0, 0xffff0000, v7
	v_mul_f32_e32 v6, v0, v0
	v_fmamk_f32 v6, v6, 0xbdd2d3e7, v129
	v_mul_f32_e32 v6, v6, v0
	v_exp_f32_e32 v6, v6
	v_mul_f32_e32 v24, v25, v25
	v_add_f32_e32 v6, 1.0, v6
	v_rcp_f32_e32 v6, v6
	s_nop 0
	v_mul_f32_e32 v7, v6, v0
	v_lshlrev_b32_e32 v0, 16, v8
	v_mul_f32_e32 v19, v0, v0
	v_fmamk_f32 v19, v19, 0xbdd2d3e7, v129
	v_mul_f32_e32 v19, v19, v0
	v_exp_f32_e32 v19, v19
	v_mul_f32_e32 v6, v7, v7
	v_pk_add_f32 v[6:7], v[24:25], v[6:7]
	v_add_f32_e32 v19, 1.0, v19
	v_rcp_f32_e32 v19, v19
	s_nop 0
	v_mul_f32_e32 v27, v19, v0
	v_and_b32_e32 v0, 0xffff0000, v8
	v_mul_f32_e32 v8, v0, v0
	v_fmamk_f32 v8, v8, 0xbdd2d3e7, v129
	v_mul_f32_e32 v8, v8, v0
	v_exp_f32_e32 v8, v8
	v_mul_f32_e32 v26, v27, v27
	v_add_f32_e32 v8, 1.0, v8
	v_rcp_f32_e32 v8, v8
	s_nop 0
	v_mul_f32_e32 v29, v8, v0
	v_lshlrev_b32_e32 v0, 16, v9
	v_mul_f32_e32 v8, v0, v0
	v_fmamk_f32 v8, v8, 0xbdd2d3e7, v129
	v_mul_f32_e32 v8, v8, v0
	v_exp_f32_e32 v8, v8
	v_mul_f32_e32 v28, v29, v29
	v_add_f32_e32 v8, 1.0, v8
	v_rcp_f32_e32 v19, v8
	v_mul_f32_e32 v8, v32, v32
	v_fmamk_f32 v8, v8, 0xbdd2d3e7, v129
	v_mul_f32_e32 v8, v8, v32
	v_exp_f32_e32 v8, v8
	s_nop 0
	v_add_f32_e32 v8, 1.0, v8
	v_rcp_f32_e32 v33, v8
	v_pk_add_f32 v[8:9], v[20:21], v[22:23]
	s_nop 0
	v_pk_add_f32 v[8:9], v[14:15], v[8:9]
	v_mul_f32_e32 v15, v33, v32
	v_pk_add_f32 v[6:7], v[8:9], v[6:7]
	v_pk_add_f32 v[8:9], v[26:27], v[28:29]
	v_mul_f32_e32 v14, v15, v15
	v_pk_add_f32 v[6:7], v[6:7], v[8:9]
	v_mul_f32_e32 v9, v19, v0
	v_mul_f32_e32 v8, v9, v9
	v_pk_add_f32 v[8:9], v[8:9], v[14:15]
	v_lshlrev_b32_e32 v0, 16, v2
	v_pk_add_f32 v[6:7], v[6:7], v[8:9]
	v_mul_f32_e32 v8, v0, v0
	v_fmamk_f32 v8, v8, 0xbdd2d3e7, v129
	v_mul_f32_e32 v8, v8, v0
	v_exp_f32_e32 v8, v8
	v_and_b32_e32 v26, 0xffff0000, v5
	v_add_f32_e32 v8, 1.0, v8
	v_rcp_f32_e32 v8, v8
	s_nop 0
	v_mul_f32_e32 v9, v8, v0
	v_and_b32_e32 v0, 0xffff0000, v2
	v_mul_f32_e32 v2, v0, v0
	v_fmamk_f32 v2, v2, 0xbdd2d3e7, v129
	v_mul_f32_e32 v2, v2, v0
	v_exp_f32_e32 v2, v2
	v_mul_f32_e32 v8, v9, v9
	v_add_f32_e32 v2, 1.0, v2
	v_rcp_f32_e32 v2, v2
	s_nop 0
	v_mul_f32_e32 v15, v2, v0
	v_lshlrev_b32_e32 v0, 16, v3
	v_mul_f32_e32 v2, v0, v0
	v_fmamk_f32 v2, v2, 0xbdd2d3e7, v129
	v_mul_f32_e32 v2, v2, v0
	v_exp_f32_e32 v2, v2
	v_mul_f32_e32 v14, v15, v15
	v_add_f32_e32 v2, 1.0, v2
	v_rcp_f32_e32 v2, v2
	s_nop 0
	v_mul_f32_e32 v21, v2, v0
	v_and_b32_e32 v0, 0xffff0000, v3
	v_mul_f32_e32 v2, v0, v0
	v_fmamk_f32 v2, v2, 0xbdd2d3e7, v129
	v_mul_f32_e32 v2, v2, v0
	v_exp_f32_e32 v2, v2
	v_mul_f32_e32 v20, v21, v21
	v_add_f32_e32 v2, 1.0, v2
	v_rcp_f32_e32 v2, v2
	s_nop 0
	v_mul_f32_e32 v3, v2, v0
	v_lshlrev_b32_e32 v0, 16, v4
	v_mul_f32_e32 v19, v0, v0
	v_fmamk_f32 v19, v19, 0xbdd2d3e7, v129
	v_mul_f32_e32 v19, v19, v0
	v_exp_f32_e32 v19, v19
	v_mul_f32_e32 v2, v3, v3
	v_pk_add_f32 v[2:3], v[20:21], v[2:3]
	v_add_f32_e32 v19, 1.0, v19
	v_rcp_f32_e32 v19, v19
	s_nop 0
	v_mul_f32_e32 v23, v19, v0
	v_and_b32_e32 v0, 0xffff0000, v4
	v_mul_f32_e32 v4, v0, v0
	v_fmamk_f32 v4, v4, 0xbdd2d3e7, v129
	v_mul_f32_e32 v4, v4, v0
	v_exp_f32_e32 v4, v4
	v_mul_f32_e32 v22, v23, v23
	v_add_f32_e32 v4, 1.0, v4
	v_rcp_f32_e32 v4, v4
	s_nop 0
	v_mul_f32_e32 v25, v4, v0
	v_lshlrev_b32_e32 v0, 16, v5
	v_mul_f32_e32 v4, v0, v0
	v_fmamk_f32 v4, v4, 0xbdd2d3e7, v129
	v_mul_f32_e32 v4, v4, v0
	v_exp_f32_e32 v4, v4
	v_mul_f32_e32 v24, v25, v25
	v_add_f32_e32 v4, 1.0, v4
	v_rcp_f32_e32 v19, v4
	v_mul_f32_e32 v4, v26, v26
	v_fmamk_f32 v4, v4, 0xbdd2d3e7, v129
	v_mul_f32_e32 v4, v4, v26
	v_exp_f32_e32 v4, v4
	s_nop 0
	v_add_f32_e32 v4, 1.0, v4
	v_rcp_f32_e32 v27, v4
	v_pk_add_f32 v[4:5], v[8:9], v[14:15]
	s_nop 0
	v_pk_add_f32 v[4:5], v[6:7], v[4:5]
	v_mul_f32_e32 v7, v27, v26
	v_pk_add_f32 v[2:3], v[4:5], v[2:3]
	v_pk_add_f32 v[4:5], v[22:23], v[24:25]
	v_mul_f32_e32 v6, v7, v7
	v_pk_add_f32 v[2:3], v[2:3], v[4:5]
	v_mul_f32_e32 v5, v19, v0
	v_mul_f32_e32 v4, v5, v5
	v_pk_add_f32 v[4:5], v[4:5], v[6:7]
	s_nop 0
	v_pk_add_f32 v[24:25], v[2:3], v[4:5]
	s_waitcnt vmcnt(0)
	v_mov_b32_e32 v2, v176
	v_mov_b32_e32 v3, v177
	v_mov_b32_e32 v4, v178
	v_mov_b32_e32 v5, v179
	v_mov_b32_e32 v6, v180
	v_mov_b32_e32 v7, v181
	v_mov_b32_e32 v8, v182
	v_mov_b32_e32 v9, v183
	v_mov_b32_e32 v20, v184
	v_mov_b32_e32 v21, v185
	v_mov_b32_e32 v22, v186
	v_mov_b32_e32 v23, v187
	v_mov_b32_e32 v14, v188
	v_mov_b32_e32 v15, v189
	v_mov_b32_e32 v16, v190
	v_mov_b32_e32 v17, v191
	v_lshl_add_u64 v[172:173], v[12:13], 0, s[0:1]
	global_load_dwordx4 v[176:179], v[172:173], off offset:1072
	global_load_dwordx4 v[180:183], v[172:173], off offset:1056
	global_load_dwordx4 v[184:187], v[172:173], off offset:1040
	global_load_dwordx4 v[188:191], v[172:173], off offset:1024
	v_lshlrev_b32_e32 v0, 16, v14
	v_mul_f32_e32 v19, v0, v0
	v_fmamk_f32 v19, v19, 0xbdd2d3e7, v129
	v_mul_f32_e32 v19, v19, v0
	v_exp_f32_e32 v19, v19
	v_and_b32_e32 v38, 0xffff0000, v17
	v_add_f32_e32 v19, 1.0, v19
	v_rcp_f32_e32 v19, v19
	s_nop 0
	v_mul_f32_e32 v27, v19, v0
	v_and_b32_e32 v0, 0xffff0000, v14
	v_mul_f32_e32 v14, v0, v0
	v_fmamk_f32 v14, v14, 0xbdd2d3e7, v129
	v_mul_f32_e32 v14, v14, v0
	v_exp_f32_e32 v14, v14
	v_mul_f32_e32 v26, v27, v27
	v_add_f32_e32 v14, 1.0, v14
	v_rcp_f32_e32 v14, v14
	s_nop 0
	v_mul_f32_e32 v29, v14, v0
	v_lshlrev_b32_e32 v0, 16, v15
	v_mul_f32_e32 v14, v0, v0
	v_fmamk_f32 v14, v14, 0xbdd2d3e7, v129
	v_mul_f32_e32 v14, v14, v0
	v_exp_f32_e32 v14, v14
	v_mul_f32_e32 v28, v29, v29
	v_add_f32_e32 v14, 1.0, v14
	v_rcp_f32_e32 v14, v14
	s_nop 0
	v_mul_f32_e32 v33, v14, v0
	v_and_b32_e32 v0, 0xffff0000, v15
	v_mul_f32_e32 v14, v0, v0
	v_fmamk_f32 v14, v14, 0xbdd2d3e7, v129
	v_mul_f32_e32 v14, v14, v0
	v_exp_f32_e32 v14, v14
	v_mul_f32_e32 v32, v33, v33
	v_add_f32_e32 v14, 1.0, v14
	v_rcp_f32_e32 v14, v14
	s_nop 0
	v_mul_f32_e32 v15, v14, v0
	v_lshlrev_b32_e32 v0, 16, v16
	v_mul_f32_e32 v19, v0, v0
	v_fmamk_f32 v19, v19, 0xbdd2d3e7, v129
	v_mul_f32_e32 v19, v19, v0
	v_exp_f32_e32 v19, v19
	v_mul_f32_e32 v14, v15, v15
	v_pk_add_f32 v[14:15], v[32:33], v[14:15]
	v_add_f32_e32 v19, 1.0, v19
	v_rcp_f32_e32 v19, v19
	s_nop 0
	v_mul_f32_e32 v35, v19, v0
	v_and_b32_e32 v0, 0xffff0000, v16
	v_mul_f32_e32 v16, v0, v0
	v_fmamk_f32 v16, v16, 0xbdd2d3e7, v129
	v_mul_f32_e32 v16, v16, v0
	v_exp_f32_e32 v16, v16
	v_mul_f32_e32 v34, v35, v35
	v_add_f32_e32 v16, 1.0, v16
	v_rcp_f32_e32 v16, v16
	s_nop 0
	v_mul_f32_e32 v37, v16, v0
	v_lshlrev_b32_e32 v0, 16, v17
	v_mul_f32_e32 v16, v0, v0
	v_fmamk_f32 v16, v16, 0xbdd2d3e7, v129
	v_mul_f32_e32 v16, v16, v0
	v_exp_f32_e32 v16, v16
	v_mul_f32_e32 v36, v37, v37
	v_add_f32_e32 v16, 1.0, v16
	v_rcp_f32_e32 v19, v16
	v_mul_f32_e32 v16, v38, v38
	v_fmamk_f32 v16, v16, 0xbdd2d3e7, v129
	v_mul_f32_e32 v16, v16, v38
	v_exp_f32_e32 v16, v16
	s_nop 0
	v_add_f32_e32 v16, 1.0, v16
	v_rcp_f32_e32 v39, v16
	v_pk_add_f32 v[16:17], v[26:27], v[28:29]
	s_nop 0
	v_pk_add_f32 v[16:17], v[24:25], v[16:17]
	v_mul_f32_e32 v25, v39, v38
	v_pk_add_f32 v[14:15], v[16:17], v[14:15]
	v_pk_add_f32 v[16:17], v[34:35], v[36:37]
	v_mul_f32_e32 v24, v25, v25
	v_pk_add_f32 v[14:15], v[14:15], v[16:17]
	v_mul_f32_e32 v17, v19, v0
	v_mul_f32_e32 v16, v17, v17
	v_pk_add_f32 v[16:17], v[16:17], v[24:25]
	v_lshlrev_b32_e32 v0, 16, v20
	v_pk_add_f32 v[14:15], v[14:15], v[16:17]
	v_mul_f32_e32 v16, v0, v0
	v_fmamk_f32 v16, v16, 0xbdd2d3e7, v129
	v_mul_f32_e32 v16, v16, v0
	v_exp_f32_e32 v16, v16
	s_nop 0
	v_add_f32_e32 v16, 1.0, v16
	v_rcp_f32_e32 v16, v16
	s_nop 0
	v_mul_f32_e32 v17, v16, v0
	v_and_b32_e32 v0, 0xffff0000, v20
	v_mul_f32_e32 v16, v0, v0
	v_fmamk_f32 v16, v16, 0xbdd2d3e7, v129
	v_mul_f32_e32 v16, v16, v0
	v_exp_f32_e32 v16, v16
	s_nop 0
	v_add_f32_e32 v16, 1.0, v16
	v_rcp_f32_e32 v16, v16
	s_nop 0
	v_mul_f32_e32 v25, v16, v0
	v_lshlrev_b32_e32 v0, 16, v21
	v_mul_f32_e32 v19, v0, v0
	v_fmamk_f32 v19, v19, 0xbdd2d3e7, v129
	v_mul_f32_e32 v19, v19, v0
	v_exp_f32_e32 v19, v19
	v_mul_f32_e32 v16, v17, v17
	v_mul_f32_e32 v24, v25, v25
	v_pk_add_f32 v[16:17], v[16:17], v[24:25]
	v_add_f32_e32 v19, 1.0, v19
	v_rcp_f32_e32 v19, v19
	v_pk_add_f32 v[14:15], v[14:15], v[16:17]
	v_mul_f32_e32 v27, v19, v0
	v_and_b32_e32 v0, 0xffff0000, v21
	v_mul_f32_e32 v19, v0, v0
	v_fmamk_f32 v19, v19, 0xbdd2d3e7, v129
	v_mul_f32_e32 v19, v19, v0
	v_exp_f32_e32 v19, v19
	v_mul_f32_e32 v26, v27, v27
	v_add_f32_e32 v19, 1.0, v19
	v_rcp_f32_e32 v19, v19
	s_nop 0
	v_mul_f32_e32 v21, v19, v0
	v_lshlrev_b32_e32 v0, 16, v22
	v_mul_f32_e32 v19, v0, v0
	v_fmamk_f32 v19, v19, 0xbdd2d3e7, v129
	v_mul_f32_e32 v19, v19, v0
	v_exp_f32_e32 v19, v19
	v_mul_f32_e32 v20, v21, v21
	v_pk_add_f32 v[16:17], v[26:27], v[20:21]
	v_add_f32_e32 v19, 1.0, v19
	v_rcp_f32_e32 v19, v19
	v_pk_add_f32 v[14:15], v[14:15], v[16:17]
	v_mul_f32_e32 v29, v19, v0
	v_and_b32_e32 v0, 0xffff0000, v22
	v_mul_f32_e32 v19, v0, v0
	v_fmamk_f32 v19, v19, 0xbdd2d3e7, v129
	v_mul_f32_e32 v19, v19, v0
	v_exp_f32_e32 v19, v19
	v_and_b32_e32 v22, 0xffff0000, v23
	v_mul_f32_e32 v28, v29, v29
	v_add_f32_e32 v19, 1.0, v19
	v_rcp_f32_e32 v19, v19
	s_nop 0
	v_mul_f32_e32 v33, v19, v0
	v_lshlrev_b32_e32 v0, 16, v23
	v_mul_f32_e32 v19, v0, v0
	v_mul_f32_e32 v23, v22, v22
	v_fmamk_f32 v19, v19, 0xbdd2d3e7, v129
	v_fmamk_f32 v23, v23, 0xbdd2d3e7, v129
	v_mul_f32_e32 v19, v19, v0
	v_mul_f32_e32 v23, v23, v22
	v_exp_f32_e32 v19, v19
	v_exp_f32_e32 v23, v23
	v_mul_f32_e32 v32, v33, v33
	v_pk_add_f32 v[16:17], v[28:29], v[32:33]
	v_add_f32_e32 v19, 1.0, v19
	v_add_f32_e32 v23, 1.0, v23
	v_rcp_f32_e32 v19, v19
	v_rcp_f32_e32 v23, v23
	v_pk_add_f32 v[14:15], v[14:15], v[16:17]
	v_and_b32_e32 v28, 0xffff0000, v9
	v_mul_f32_e32 v17, v19, v0
	v_mul_f32_e32 v21, v23, v22
	v_mul_f32_e32 v16, v17, v17
	v_mul_f32_e32 v20, v21, v21
	v_pk_add_f32 v[16:17], v[16:17], v[20:21]
	v_lshlrev_b32_e32 v0, 16, v6
	v_pk_add_f32 v[14:15], v[14:15], v[16:17]
	v_mul_f32_e32 v16, v0, v0
	v_fmamk_f32 v16, v16, 0xbdd2d3e7, v129
	v_mul_f32_e32 v16, v16, v0
	v_exp_f32_e32 v16, v16
	s_nop 0
	v_add_f32_e32 v16, 1.0, v16
	v_rcp_f32_e32 v16, v16
	s_nop 0
	v_mul_f32_e32 v17, v16, v0
	v_and_b32_e32 v0, 0xffff0000, v6
	v_mul_f32_e32 v6, v0, v0
	v_fmamk_f32 v6, v6, 0xbdd2d3e7, v129
	v_mul_f32_e32 v6, v6, v0
	v_exp_f32_e32 v6, v6
	v_mul_f32_e32 v16, v17, v17
	v_add_f32_e32 v6, 1.0, v6
	v_rcp_f32_e32 v6, v6
	s_nop 0
	v_mul_f32_e32 v21, v6, v0
	v_lshlrev_b32_e32 v0, 16, v7
	v_mul_f32_e32 v6, v0, v0
	v_fmamk_f32 v6, v6, 0xbdd2d3e7, v129
	v_mul_f32_e32 v6, v6, v0
	v_exp_f32_e32 v6, v6
	v_mul_f32_e32 v20, v21, v21
	v_add_f32_e32 v6, 1.0, v6
	v_rcp_f32_e32 v6, v6
	s_nop 0
	v_mul_f32_e32 v23, v6, v0
	v_and_b32_e32 v0, 0xffff0000, v7
	v_mul_f32_e32 v6, v0, v0
	v_fmamk_f32 v6, v6, 0xbdd2d3e7, v129
	v_mul_f32_e32 v6, v6, v0
	v_exp_f32_e32 v6, v6
	v_mul_f32_e32 v22, v23, v23
	v_add_f32_e32 v6, 1.0, v6
	v_rcp_f32_e32 v6, v6
	s_nop 0
	v_mul_f32_e32 v7, v6, v0
	v_lshlrev_b32_e32 v0, 16, v8
	v_mul_f32_e32 v19, v0, v0
	v_fmamk_f32 v19, v19, 0xbdd2d3e7, v129
	v_mul_f32_e32 v19, v19, v0
	v_exp_f32_e32 v19, v19
	v_mul_f32_e32 v6, v7, v7
	v_pk_add_f32 v[6:7], v[22:23], v[6:7]
	v_add_f32_e32 v19, 1.0, v19
	v_rcp_f32_e32 v19, v19
	s_nop 0
	v_mul_f32_e32 v25, v19, v0
	v_and_b32_e32 v0, 0xffff0000, v8
	v_mul_f32_e32 v8, v0, v0
	v_fmamk_f32 v8, v8, 0xbdd2d3e7, v129
	v_mul_f32_e32 v8, v8, v0
	v_exp_f32_e32 v8, v8
	v_mul_f32_e32 v24, v25, v25
	v_add_f32_e32 v8, 1.0, v8
	v_rcp_f32_e32 v8, v8
	s_nop 0
	v_mul_f32_e32 v27, v8, v0
	v_lshlrev_b32_e32 v0, 16, v9
	v_mul_f32_e32 v8, v0, v0
	v_fmamk_f32 v8, v8, 0xbdd2d3e7, v129
	v_mul_f32_e32 v8, v8, v0
	v_exp_f32_e32 v8, v8
	v_mul_f32_e32 v26, v27, v27
	v_add_f32_e32 v8, 1.0, v8
	v_rcp_f32_e32 v19, v8
	v_mul_f32_e32 v8, v28, v28
	v_fmamk_f32 v8, v8, 0xbdd2d3e7, v129
	v_mul_f32_e32 v8, v8, v28
	v_exp_f32_e32 v8, v8
	s_nop 0
	v_add_f32_e32 v8, 1.0, v8
	v_rcp_f32_e32 v29, v8
	v_pk_add_f32 v[8:9], v[16:17], v[20:21]
	s_nop 0
	v_pk_add_f32 v[8:9], v[14:15], v[8:9]
	v_mul_f32_e32 v15, v29, v28
	v_pk_add_f32 v[6:7], v[8:9], v[6:7]
	v_pk_add_f32 v[8:9], v[24:25], v[26:27]
	v_mul_f32_e32 v14, v15, v15
	v_pk_add_f32 v[6:7], v[6:7], v[8:9]
	v_mul_f32_e32 v9, v19, v0
	v_mul_f32_e32 v8, v9, v9
	v_pk_add_f32 v[8:9], v[8:9], v[14:15]
	v_lshlrev_b32_e32 v0, 16, v2
	v_pk_add_f32 v[6:7], v[6:7], v[8:9]
	v_mul_f32_e32 v8, v0, v0
	v_fmamk_f32 v8, v8, 0xbdd2d3e7, v129
	v_mul_f32_e32 v8, v8, v0
	v_exp_f32_e32 v8, v8
	v_and_b32_e32 v24, 0xffff0000, v5
	v_add_f32_e32 v8, 1.0, v8
	v_rcp_f32_e32 v8, v8
	s_nop 0
	v_mul_f32_e32 v9, v8, v0
	v_and_b32_e32 v0, 0xffff0000, v2
	v_mul_f32_e32 v2, v0, v0
	v_fmamk_f32 v2, v2, 0xbdd2d3e7, v129
	v_mul_f32_e32 v2, v2, v0
	v_exp_f32_e32 v2, v2
	v_mul_f32_e32 v8, v9, v9
	v_add_f32_e32 v2, 1.0, v2
	v_rcp_f32_e32 v2, v2
	s_nop 0
	v_mul_f32_e32 v15, v2, v0
	v_lshlrev_b32_e32 v0, 16, v3
	v_mul_f32_e32 v2, v0, v0
	v_fmamk_f32 v2, v2, 0xbdd2d3e7, v129
	v_mul_f32_e32 v2, v2, v0
	v_exp_f32_e32 v2, v2
	v_mul_f32_e32 v14, v15, v15
	v_add_f32_e32 v2, 1.0, v2
	v_rcp_f32_e32 v2, v2
	s_nop 0
	v_mul_f32_e32 v17, v2, v0
	v_and_b32_e32 v0, 0xffff0000, v3
	v_mul_f32_e32 v2, v0, v0
	v_fmamk_f32 v2, v2, 0xbdd2d3e7, v129
	v_mul_f32_e32 v2, v2, v0
	v_exp_f32_e32 v2, v2
	v_mul_f32_e32 v16, v17, v17
	v_add_f32_e32 v2, 1.0, v2
	v_rcp_f32_e32 v2, v2
	s_nop 0
	v_mul_f32_e32 v3, v2, v0
	v_lshlrev_b32_e32 v0, 16, v4
	v_mul_f32_e32 v19, v0, v0
	v_fmamk_f32 v19, v19, 0xbdd2d3e7, v129
	v_mul_f32_e32 v19, v19, v0
	v_exp_f32_e32 v19, v19
	v_mul_f32_e32 v2, v3, v3
	v_pk_add_f32 v[2:3], v[16:17], v[2:3]
	v_add_f32_e32 v19, 1.0, v19
	v_rcp_f32_e32 v19, v19
	s_nop 0
	v_mul_f32_e32 v21, v19, v0
	v_and_b32_e32 v0, 0xffff0000, v4
	v_mul_f32_e32 v4, v0, v0
	v_fmamk_f32 v4, v4, 0xbdd2d3e7, v129
	v_mul_f32_e32 v4, v4, v0
	v_exp_f32_e32 v4, v4
	v_mul_f32_e32 v20, v21, v21
	v_add_f32_e32 v4, 1.0, v4
	v_rcp_f32_e32 v4, v4
	s_nop 0
	v_mul_f32_e32 v23, v4, v0
	v_lshlrev_b32_e32 v0, 16, v5
	v_mul_f32_e32 v4, v0, v0
	v_fmamk_f32 v4, v4, 0xbdd2d3e7, v129
	v_mul_f32_e32 v4, v4, v0
	v_exp_f32_e32 v4, v4
	v_mul_f32_e32 v22, v23, v23
	v_add_f32_e32 v4, 1.0, v4
	v_rcp_f32_e32 v19, v4
	v_mul_f32_e32 v4, v24, v24
	v_fmamk_f32 v4, v4, 0xbdd2d3e7, v129
	v_mul_f32_e32 v4, v4, v24
	v_exp_f32_e32 v4, v4
	s_nop 0
	v_add_f32_e32 v4, 1.0, v4
	v_rcp_f32_e32 v25, v4
	v_pk_add_f32 v[4:5], v[8:9], v[14:15]
	s_nop 0
	v_pk_add_f32 v[4:5], v[6:7], v[4:5]
	v_mul_f32_e32 v7, v25, v24
	v_pk_add_f32 v[2:3], v[4:5], v[2:3]
	v_pk_add_f32 v[4:5], v[20:21], v[22:23]
	v_mul_f32_e32 v6, v7, v7
	v_pk_add_f32 v[2:3], v[2:3], v[4:5]
	v_mul_f32_e32 v5, v19, v0
	v_mul_f32_e32 v4, v5, v5
	v_pk_add_f32 v[4:5], v[4:5], v[6:7]
	s_nop 0
	v_pk_add_f32 v[14:15], v[2:3], v[4:5]
	s_cbranch_scc1 .LBB0_621
	v_and_b32_e32 v171, 0xff, v194
	v_lshlrev_b32_e32 v171, 3, v171
	s_mul_i32 s66, s64, 0x12000
	s_add_i32 s66, s66, 0x11000
	s_xor_b32 s67, s64, 1
	s_mul_i32 s67, s67, 0x12000
	s_add_i32 s67, s67, 0x11000
	v_add_u32_e32 v172, s66, v171
	v_add_u32_e32 v173, s67, v171
	ds_write_b64 v172, v[14:15]
	s_waitcnt lgkmcnt(0)
	s_barrier
	ds_read_b64 v[174:175], v173
	s_waitcnt lgkmcnt(0)
	v_add_f32_e32 v14, v14, v174
	v_add_f32_e32 v15, v15, v175
	v_readlane_b32 s0, v254, 51
	s_lshl_b32 s88, s0, 9
	v_readlane_b32 s40, v251, 6
	s_lshl_b64 s[6:7], s[88:89], 2
	v_readlane_b32 s52, v251, 18
	v_readlane_b32 s53, v251, 19
	s_add_u32 s1, s52, s6
	s_addc_u32 s2, s53, s7
	s_lshl_b32 s0, s10, 7
	s_and_b32 s0, s0, 0x180
	s_lshl_b32 s5, s0, 2
	s_add_u32 s16, s1, s5
	v_readlane_b32 s54, v251, 20
	s_addc_u32 s17, s2, 0
	v_readlane_b32 s55, v251, 21
	s_add_u32 s1, s54, s6
	s_addc_u32 s2, s55, s7
	s_add_u32 s20, s1, s5
	s_addc_u32 s21, s2, 0
	s_lshl_b32 s8, s0, 1
	s_mov_b32 s9, s89
	v_lshl_add_u64 v[2:3], v[10:11], 0, s[8:9]
	v_lshlrev_b32_e32 v0, 7, v18
	v_lshl_add_u64 v[22:23], v[2:3], 0, v[0:1]
	global_load_dwordx4 v[10:13], v[22:23], off offset:1024
	v_lshlrev_b32_e32 v20, 8, v18
	global_load_dwordx2 v[28:29], v20, s[16:17]
	global_load_dwordx2 v[36:37], v20, s[20:21]
	global_load_dwordx2 v[40:41], v20, s[16:17] offset:16
	global_load_dwordx2 v[42:43], v20, s[16:17] offset:32
	global_load_dwordx2 v[24:25], v20, s[16:17] offset:48
	global_load_dwordx2 v[44:45], v20, s[20:21] offset:16
	global_load_dwordx2 v[46:47], v20, s[20:21] offset:32
	global_load_dwordx2 v[26:27], v20, s[20:21] offset:48
	v_xor_b32_e32 v2, 1, v234
	v_cmp_lt_i32_e32 vcc, v2, v235
	s_mov_b32 s2, 0x3b000000
	v_lshlrev_b32_e32 v34, 6, v18
	v_cndmask_b32_e32 v2, v234, v2, vcc
	v_lshlrev_b32_e32 v80, 2, v2
	ds_bpermute_b32 v3, v80, v15
	ds_bpermute_b32 v2, v80, v14
	v_mul_u32_u24_e32 v4, 0x4400, v18
	v_lshlrev_b32_e32 v33, 1, v31
	s_mov_b32 s11, 0x800000
	v_add3_u32 v38, s15, v4, v33
	s_waitcnt lgkmcnt(0)
	v_pk_add_f32 v[2:3], v[14:15], v[2:3]
	v_or_b32_e32 v4, 1, v34
	v_pk_mul_f32 v[18:19], v[2:3], s[2:3] op_sel_hi:[1,0]
	v_mul_u32_u24_e32 v4, 0x110, v4
	v_fma_f32 v2, -v19, v19, v18
	v_max_f32_e32 v2, 0, v2
	v_add_f32_e32 v2, 0x358637bd, v2
	v_mul_f32_e32 v3, 0x4b800000, v2
	v_cmp_gt_f32_e32 vcc, s11, v2
	v_add3_u32 v35, s15, v4, v33
	v_or_b32_e32 v78, 7, v34
	v_cndmask_b32_e32 v2, v2, v3, vcc
	v_rsq_f32_e32 v18, v2
	global_load_dwordx4 v[14:17], v[22:23], off offset:1040
	global_load_dwordx4 v[2:5], v[22:23], off offset:1072
	global_load_dwordx4 v[6:9], v[22:23], off offset:1056
	v_or_b32_e32 v81, 10, v34
	v_or_b32_e32 v79, 11, v34
	v_mul_f32_e32 v39, 0x45800000, v18
	v_cndmask_b32_e32 v39, v18, v39, vcc
	v_readlane_b32 s41, v251, 7
	v_readlane_b32 s42, v251, 8
	v_readlane_b32 s43, v251, 9
	v_readlane_b32 s44, v251, 10
	v_readlane_b32 s45, v251, 11
	v_readlane_b32 s46, v251, 12
	v_readlane_b32 s47, v251, 13
	v_readlane_b32 s48, v251, 14
	v_readlane_b32 s49, v251, 15
	v_readlane_b32 s50, v251, 16
	v_readlane_b32 s51, v251, 17
	s_or_b32 s88, s0, s88
	v_readlane_b32 s40, v251, 22
	v_readlane_b32 s41, v251, 23
	v_mov_b32_e32 v21, v1
	v_mul_u32_u24_e32 v84, 0x110, v31
	v_add3_u32 v0, s15, v84, v0
	v_or_b32_e32 v101, 31, v34
	v_cmp_gt_u32_e32 vcc, v31, v34
	v_or_b32_e32 v57, 48, v34
	v_and_b32_e32 v32, 15, v50
	v_readlane_b32 s44, v251, 26
	v_readlane_b32 s45, v251, 27
	v_readlane_b32 s46, v251, 28
	v_readlane_b32 s47, v251, 29
	v_readlane_b32 s48, v251, 30
	v_readlane_b32 s49, v251, 31
	v_readlane_b32 s50, v251, 32
	v_readlane_b32 s51, v251, 33
	v_readlane_b32 s52, v251, 34
	v_readlane_b32 s53, v251, 35
	v_readlane_b32 s54, v251, 36
	v_readlane_b32 s55, v251, 37
	v_readlane_b32 s44, v251, 54
	v_readlane_b32 s50, v251, 60
	v_readlane_b32 s51, v251, 61
	s_add_u32 s6, s50, s8
	s_addc_u32 s7, s51, 0
	v_readlane_b32 s42, v251, 24
	v_readlane_b32 s43, v251, 25
	v_readlane_b32 s52, v251, 62
	v_readlane_b32 s53, v251, 63
	v_readlane_b32 s54, v252, 0
	v_readlane_b32 s55, v252, 1
	v_readlane_b32 s45, v251, 55
	s_waitcnt vmcnt(11)
	v_lshlrev_b32_e32 v48, 16, v11
	v_and_b32_e32 v11, 0xffff0000, v11
	v_mul_f32_e32 v54, v11, v11
	v_fmamk_f32 v54, v54, 0xbdd2d3e7, v129
	v_mul_f32_e32 v54, v54, v11
	v_lshlrev_b32_e32 v18, 16, v10
	v_and_b32_e32 v10, 0xffff0000, v10
	v_mul_f32_e32 v51, v18, v18
	v_mul_f32_e32 v52, v10, v10
	v_fmamk_f32 v51, v51, 0xbdd2d3e7, v129
	v_exp_f32_e32 v54, v54
	v_fmamk_f32 v52, v52, 0xbdd2d3e7, v129
	v_mul_f32_e32 v51, v51, v18
	v_mul_f32_e32 v52, v52, v10
	v_exp_f32_e32 v51, v51
	v_add_f32_e32 v54, 1.0, v54
	v_exp_f32_e32 v52, v52
	v_rcp_f32_e32 v54, v54
	v_lshlrev_b32_e32 v49, 16, v12
	v_mul_f32_e32 v55, v49, v49
	v_fmamk_f32 v55, v55, 0xbdd2d3e7, v129
	v_add_f32_e32 v51, 1.0, v51
	v_mul_f32_e32 v55, v55, v49
	v_add_f32_e32 v52, 1.0, v52
	v_rcp_f32_e32 v51, v51
	v_fma_f32 v11, v54, v11, -v19
	v_rcp_f32_e32 v52, v52
	v_mul_f32_e32 v59, v39, v11
	v_and_b32_e32 v11, 0xffff0000, v12
	v_mul_f32_e32 v12, v11, v11
	v_exp_f32_e32 v55, v55
	v_fmamk_f32 v12, v12, 0xbdd2d3e7, v129
	v_fma_f32 v18, v51, v18, -v19
	v_mul_f32_e32 v12, v12, v11
	v_fma_f32 v10, v52, v10, -v19
	v_mul_f32_e32 v18, v39, v18
	v_mul_f32_e32 v10, v39, v10
	s_waitcnt vmcnt(9)
	v_fma_f32 v18, v28, v18, v36
	v_lshlrev_b32_e32 v28, 16, v13
	v_add_f32_e32 v55, 1.0, v55
	v_fmac_f32_e32 v37, v29, v10
	v_exp_f32_e32 v12, v12
	v_mul_f32_e32 v29, v28, v28
	v_rcp_f32_e32 v55, v55
	v_fmamk_f32 v29, v29, 0xbdd2d3e7, v129
	v_mul_f32_e32 v29, v29, v28
	v_cvt_pk_bf16_f32 v10, v18, s0
	v_add_f32_e32 v12, 1.0, v12
	v_cvt_pk_bf16_f32 v18, v37, s0
	ds_write_b16 v38, v10 offset:34816
	ds_write_b16 v35, v18 offset:34816
	v_fma_f32 v10, v55, v49, -v19
	v_rcp_f32_e32 v12, v12
	v_exp_f32_e32 v29, v29
	v_mul_f32_e32 v10, v39, v10
	s_waitcnt vmcnt(5)
	v_fma_f32 v10, v40, v10, v44
	v_cvt_pk_bf16_f32 v10, v10, s0
	ds_write_b16 v35, v10 offset:35632
	v_fma_f32 v10, v12, v11, -v19
	v_add_f32_e32 v11, 1.0, v29
	v_rcp_f32_e32 v11, v11
	v_mul_f32_e32 v10, v39, v10
	v_fmac_f32_e32 v45, v10, v41
	v_cvt_pk_bf16_f32 v10, v45, s0
	ds_write_b16 v35, v10 offset:35904
	v_fma_f32 v10, v11, v28, -v19
	v_and_b32_e32 v11, 0xffff0000, v13
	v_mul_f32_e32 v12, v11, v11
	v_fmamk_f32 v12, v12, 0xbdd2d3e7, v129
	v_mul_f32_e32 v12, v12, v11
	v_exp_f32_e32 v12, v12
	s_waitcnt vmcnt(2)
	v_lshlrev_b32_e32 v13, 16, v14
	v_mul_f32_e32 v28, v13, v13
	v_fmamk_f32 v28, v28, 0xbdd2d3e7, v129
	v_add_f32_e32 v12, 1.0, v12
	v_rcp_f32_e32 v12, v12
	v_mul_f32_e32 v28, v28, v13
	v_fma_f32 v11, v12, v11, -v19
	v_exp_f32_e32 v28, v28
	v_mul_f32_e32 v44, v39, v11
	v_and_b32_e32 v11, 0xffff0000, v14
	v_mul_f32_e32 v12, v11, v11
	v_fmamk_f32 v12, v12, 0xbdd2d3e7, v129
	v_mul_f32_e32 v12, v12, v11
	v_mul_f32_e32 v45, v39, v10
	v_add_f32_e32 v10, 1.0, v28
	v_rcp_f32_e32 v10, v10
	v_exp_f32_e32 v12, v12
	v_lshlrev_b32_e32 v29, 16, v16
	v_fma_f32 v10, v10, v13, -v19
	v_lshlrev_b32_e32 v13, 16, v15
	v_add_f32_e32 v12, 1.0, v12
	v_mul_f32_e32 v14, v13, v13
	v_rcp_f32_e32 v12, v12
	v_fmamk_f32 v14, v14, 0xbdd2d3e7, v129
	v_mul_f32_e32 v10, v39, v10
	v_mul_f32_e32 v14, v14, v13
	v_fma_f32 v10, v42, v10, v46
	v_cvt_pk_bf16_f32 v10, v10, s0
	v_exp_f32_e32 v14, v14
	ds_write_b16 v35, v10 offset:36720
	v_fma_f32 v10, v12, v11, -v19
	v_mul_f32_e32 v10, v39, v10
	v_fmac_f32_e32 v47, v43, v10
	v_cvt_pk_bf16_f32 v10, v47, s0
	v_and_b32_e32 v15, 0xffff0000, v15
	v_add_f32_e32 v11, 1.0, v14
	ds_write_b16 v35, v10 offset:36992
	v_mul_f32_e32 v10, v15, v15
	v_rcp_f32_e32 v11, v11
	v_fmamk_f32 v10, v10, 0xbdd2d3e7, v129
	v_mul_f32_e32 v10, v10, v15
	v_fma_f32 v14, v11, v13, -v19
	v_exp_f32_e32 v28, v10
	global_load_dwordx2 v[10:11], v20, s[16:17] offset:64
	global_load_dwordx2 v[12:13], v20, s[20:21] offset:64
	v_mul_f32_e32 v37, v29, v29
	v_fmamk_f32 v37, v37, 0xbdd2d3e7, v129
	v_add_f32_e32 v28, 1.0, v28
	v_mul_f32_e32 v37, v37, v29
	v_rcp_f32_e32 v28, v28
	v_exp_f32_e32 v37, v37
	v_fma_f32 v15, v28, v15, -v19
	v_mul_f32_e32 v46, v39, v15
	v_and_b32_e32 v15, 0xffff0000, v16
	v_mul_f32_e32 v16, v15, v15
	v_mul_f32_e32 v47, v39, v14
	v_add_f32_e32 v14, 1.0, v37
	v_fmamk_f32 v16, v16, 0xbdd2d3e7, v129
	v_rcp_f32_e32 v14, v14
	v_mul_f32_e32 v16, v16, v15
	v_exp_f32_e32 v16, v16
	v_fma_f32 v14, v14, v29, -v19
	v_mul_f32_e32 v14, v39, v14
	v_fma_f32 v14, v24, v14, v26
	v_lshlrev_b32_e32 v24, 16, v17
	v_add_f32_e32 v16, 1.0, v16
	v_mul_f32_e32 v26, v24, v24
	v_rcp_f32_e32 v16, v16
	v_fmamk_f32 v26, v26, 0xbdd2d3e7, v129
	v_mul_f32_e32 v26, v26, v24
	v_cvt_pk_bf16_f32 v14, v14, s0
	v_exp_f32_e32 v26, v26
	ds_write_b16 v35, v14 offset:37808
	v_fma_f32 v14, v16, v15, -v19
	v_mul_f32_e32 v14, v39, v14
	v_fmac_f32_e32 v27, v14, v25
	v_cvt_pk_bf16_f32 v14, v27, s0
	v_and_b32_e32 v25, 0xffff0000, v17
	v_add_f32_e32 v15, 1.0, v26
	ds_write_b16 v35, v14 offset:38080
	v_mul_f32_e32 v14, v25, v25
	v_rcp_f32_e32 v15, v15
	v_fmamk_f32 v14, v14, 0xbdd2d3e7, v129
	v_mul_f32_e32 v14, v14, v25
	v_fma_f32 v24, v15, v24, -v19
	v_exp_f32_e32 v26, v14
	global_load_dwordx2 v[14:15], v20, s[16:17] offset:80
	global_load_dwordx2 v[16:17], v20, s[20:21] offset:80
	s_waitcnt vmcnt(4)
	v_lshlrev_b32_e32 v27, 16, v6
	v_mul_f32_e32 v28, v27, v27
	v_fmamk_f32 v28, v28, 0xbdd2d3e7, v129
	v_mul_f32_e32 v28, v28, v27
	v_exp_f32_e32 v28, v28
	v_mul_f32_e32 v55, v39, v24
	v_mul_f32_e32 v53, v48, v48
	v_fmamk_f32 v53, v53, 0xbdd2d3e7, v129
	v_add_f32_e32 v24, 1.0, v28
	v_rcp_f32_e32 v24, v24
	v_and_b32_e32 v6, 0xffff0000, v6
	v_mul_f32_e32 v53, v53, v48
	v_fma_f32 v24, v24, v27, -v19
	v_mul_f32_e32 v40, v39, v24
	v_mul_f32_e32 v24, v6, v6
	v_fmamk_f32 v24, v24, 0xbdd2d3e7, v129
	v_mul_f32_e32 v24, v24, v6
	v_exp_f32_e32 v53, v53
	v_exp_f32_e32 v41, v24
	v_add_f32_e32 v53, 1.0, v53
	v_add_f32_e32 v26, 1.0, v26
	v_rcp_f32_e32 v53, v53
	v_rcp_f32_e32 v26, v26
	s_waitcnt vmcnt(2)
	v_fma_f32 v10, v10, v40, v12
	v_lshlrev_b32_e32 v40, 16, v7
	v_add_f32_e32 v12, 1.0, v41
	v_mul_f32_e32 v41, v40, v40
	v_fmamk_f32 v41, v41, 0xbdd2d3e7, v129
	v_mul_f32_e32 v41, v41, v40
	v_fma_f32 v48, v53, v48, -v19
	v_fma_f32 v25, v26, v25, -v19
	v_mul_f32_e32 v65, v39, v48
	v_mul_f32_e32 v54, v39, v25
	global_load_dwordx2 v[24:25], v20, s[16:17] offset:96
	global_load_dwordx2 v[28:29], v20, s[16:17] offset:112
	global_load_dwordx2 v[26:27], v20, s[20:21] offset:96
	global_load_dwordx2 v[48:49], v20, s[20:21] offset:112
	v_exp_f32_e32 v41, v41
	v_rcp_f32_e32 v12, v12
	v_cvt_pk_bf16_f32 v10, v10, s0
	ds_write_b16 v35, v10 offset:38896
	v_add_f32_e32 v10, 1.0, v41
	v_fma_f32 v6, v12, v6, -v19
	v_rcp_f32_e32 v10, v10
	v_mul_f32_e32 v6, v39, v6
	v_fmac_f32_e32 v13, v11, v6
	v_cvt_pk_bf16_f32 v6, v13, s0
	v_and_b32_e32 v7, 0xffff0000, v7
	ds_write_b16 v35, v6 offset:39168
	v_fma_f32 v6, v10, v40, -v19
	v_mul_f32_e32 v10, v7, v7
	v_fmamk_f32 v10, v10, 0xbdd2d3e7, v129
	v_mul_f32_e32 v10, v10, v7
	v_exp_f32_e32 v10, v10
	v_lshlrev_b32_e32 v11, 16, v8
	v_mul_f32_e32 v12, v11, v11
	v_fmamk_f32 v12, v12, 0xbdd2d3e7, v129
	v_mul_f32_e32 v12, v12, v11
	v_add_f32_e32 v10, 1.0, v10
	v_rcp_f32_e32 v10, v10
	v_exp_f32_e32 v12, v12
	v_mul_f32_e32 v53, v39, v6
	v_fma_f32 v7, v10, v7, -v19
	v_mul_f32_e32 v52, v39, v7
	v_and_b32_e32 v7, 0xffff0000, v8
	v_add_f32_e32 v6, 1.0, v12
	v_mul_f32_e32 v8, v7, v7
	v_rcp_f32_e32 v6, v6
	v_fmamk_f32 v8, v8, 0xbdd2d3e7, v129
	v_mul_f32_e32 v8, v8, v7
	v_lshlrev_b32_e32 v10, 16, v9
	v_fma_f32 v6, v6, v11, -v19
	v_exp_f32_e32 v8, v8
	v_mul_f32_e32 v11, v10, v10
	v_fmamk_f32 v11, v11, 0xbdd2d3e7, v129
	v_mul_f32_e32 v11, v11, v10
	v_add_f32_e32 v8, 1.0, v8
	v_rcp_f32_e32 v8, v8
	v_exp_f32_e32 v11, v11
	v_mul_f32_e32 v6, v39, v6
	s_waitcnt vmcnt(4)
	v_fma_f32 v6, v14, v6, v16
	v_cvt_pk_bf16_f32 v6, v6, s0
	ds_write_b16 v35, v6 offset:39984
	v_fma_f32 v6, v8, v7, -v19
	v_add_f32_e32 v7, 1.0, v11
	v_rcp_f32_e32 v7, v7
	v_mul_f32_e32 v6, v39, v6
	v_fmac_f32_e32 v17, v6, v15
	v_cvt_pk_bf16_f32 v6, v17, s0
	ds_write_b16 v35, v6 offset:40256
	v_fma_f32 v6, v7, v10, -v19
	v_and_b32_e32 v7, 0xffff0000, v9
	v_lshlrev_b32_e32 v9, 16, v2
	v_mul_f32_e32 v10, v9, v9
	v_fmamk_f32 v10, v10, 0xbdd2d3e7, v129
	v_mul_f32_e32 v8, v7, v7
	v_mul_f32_e32 v10, v10, v9
	v_fmamk_f32 v8, v8, 0xbdd2d3e7, v129
	v_mul_f32_e32 v8, v8, v7
	v_exp_f32_e32 v10, v10
	v_exp_f32_e32 v8, v8
	v_mul_f32_e32 v58, v39, v6
	v_add_f32_e32 v6, 1.0, v10
	global_load_dwordx4 v[10:13], v[22:23], off offset:1104
	global_load_dwordx4 v[14:17], v[22:23], off offset:1088
	v_add_f32_e32 v8, 1.0, v8
	v_rcp_f32_e32 v8, v8
	v_and_b32_e32 v2, 0xffff0000, v2
	v_rcp_f32_e32 v6, v6
	v_or_b32_e32 v18, 4, v34
	v_fma_f32 v7, v8, v7, -v19
	v_mul_f32_e32 v56, v39, v7
	v_mul_f32_e32 v7, v2, v2
	v_fmamk_f32 v7, v7, 0xbdd2d3e7, v129
	v_mul_f32_e32 v7, v7, v2
	v_exp_f32_e32 v7, v7
	v_lshlrev_b32_e32 v8, 16, v3
	v_fma_f32 v6, v6, v9, -v19
	v_mul_f32_e32 v9, v8, v8
	v_add_f32_e32 v7, 1.0, v7
	v_rcp_f32_e32 v7, v7
	v_fmamk_f32 v9, v9, 0xbdd2d3e7, v129
	v_mul_f32_e32 v9, v9, v8
	v_fma_f32 v2, v7, v2, -v19
	v_mul_f32_e32 v6, v39, v6
	v_mul_f32_e32 v2, v39, v2
	s_waitcnt vmcnt(3)
	v_fma_f32 v6, v24, v6, v26
	v_exp_f32_e32 v9, v9
	v_fmac_f32_e32 v27, v25, v2
	v_cvt_pk_bf16_f32 v6, v6, s0
	v_cvt_pk_bf16_f32 v2, v27, s0
	ds_write_b16 v35, v6 offset:41072
	ds_write_b16 v35, v2 offset:41344
	global_load_dwordx2 v[24:25], v20, s[16:17] offset:128
	global_load_dwordx2 v[26:27], v20, s[20:21] offset:128
	v_add_f32_e32 v6, 1.0, v9
	v_rcp_f32_e32 v6, v6
	v_and_b32_e32 v3, 0xffff0000, v3
	v_lshlrev_b32_e32 v7, 16, v4
	v_or_b32_e32 v36, 8, v34
	v_fma_f32 v2, v6, v8, -v19
	v_mul_f32_e32 v6, v3, v3
	v_fmamk_f32 v6, v6, 0xbdd2d3e7, v129
	v_mul_f32_e32 v6, v6, v3
	v_exp_f32_e32 v6, v6
	v_mul_f32_e32 v8, v7, v7
	v_fmamk_f32 v8, v8, 0xbdd2d3e7, v129
	v_mul_f32_e32 v8, v8, v7
	v_add_f32_e32 v6, 1.0, v6
	v_rcp_f32_e32 v6, v6
	v_exp_f32_e32 v8, v8
	v_mul_f32_e32 v64, v39, v2
	v_fma_f32 v3, v6, v3, -v19
	v_mul_f32_e32 v63, v39, v3
	v_and_b32_e32 v3, 0xffff0000, v4
	v_add_f32_e32 v2, 1.0, v8
	v_mul_f32_e32 v4, v3, v3
	v_rcp_f32_e32 v2, v2
	v_fmamk_f32 v4, v4, 0xbdd2d3e7, v129
	v_mul_f32_e32 v4, v4, v3
	v_fma_f32 v2, v2, v7, -v19
	v_exp_f32_e32 v4, v4
	v_mul_f32_e32 v2, v39, v2
	s_waitcnt vmcnt(4)
	v_fma_f32 v2, v28, v2, v48
	v_cvt_pk_bf16_f32 v2, v2, s0
	ds_write_b16 v35, v2 offset:42160
	v_add_f32_e32 v2, 1.0, v4
	v_lshlrev_b32_e32 v4, 16, v5
	v_mul_f32_e32 v6, v4, v4
	v_fmamk_f32 v6, v6, 0xbdd2d3e7, v129
	v_rcp_f32_e32 v2, v2
	v_mul_f32_e32 v6, v6, v4
	v_exp_f32_e32 v6, v6
	v_fma_f32 v2, v2, v3, -v19
	v_mul_f32_e32 v2, v39, v2
	v_fmac_f32_e32 v49, v2, v29
	v_add_f32_e32 v2, 1.0, v6
	v_cvt_pk_bf16_f32 v6, v49, s0
	ds_write_b16 v35, v6 offset:42432
	global_load_dwordx2 v[60:61], v20, s[16:17] offset:144
	global_load_dwordx2 v[66:67], v20, s[20:21] offset:144
	v_and_b32_e32 v3, 0xffff0000, v5
	v_mul_f32_e32 v5, v3, v3
	v_fmamk_f32 v5, v5, 0xbdd2d3e7, v129
	v_mul_f32_e32 v5, v5, v3
	v_rcp_f32_e32 v2, v2
	v_exp_f32_e32 v5, v5
	s_waitcnt vmcnt(4)
	v_lshlrev_b32_e32 v28, 16, v14
	v_and_b32_e32 v14, 0xffff0000, v14
	v_fma_f32 v2, v2, v4, -v19
	v_add_f32_e32 v4, 1.0, v5
	v_mul_f32_e32 v5, v28, v28
	v_fmamk_f32 v5, v5, 0xbdd2d3e7, v129
	v_mul_f32_e32 v5, v5, v28
	v_rcp_f32_e32 v4, v4
	v_exp_f32_e32 v5, v5
	v_mul_f32_e32 v69, v39, v2
	v_fma_f32 v2, v4, v3, -v19
	v_mul_f32_e32 v68, v39, v2
	v_add_f32_e32 v2, 1.0, v5
	v_rcp_f32_e32 v29, v2
	global_load_dwordx4 v[2:5], v[22:23], off offset:1136
	global_load_dwordx4 v[6:9], v[22:23], off offset:1120
	v_or_b32_e32 v37, 12, v34
	v_or_b32_e32 v38, 16, v34
	v_fma_f32 v22, v29, v28, -v19
	v_mul_f32_e32 v48, v39, v22
	v_mul_f32_e32 v22, v14, v14
	v_fmamk_f32 v22, v22, 0xbdd2d3e7, v129
	v_mul_f32_e32 v22, v22, v14
	v_exp_f32_e32 v49, v22
	global_load_dwordx2 v[74:75], v20, s[16:17] offset:160
	global_load_dwordx2 v[22:23], v20, s[16:17] offset:176
	global_load_dwordx2 v[76:77], v20, s[20:21] offset:160
	global_load_dwordx2 v[28:29], v20, s[20:21] offset:176
	s_waitcnt vmcnt(8)
	v_fma_f32 v24, v24, v48, v26
	v_lshlrev_b32_e32 v48, 16, v15
	v_add_f32_e32 v26, 1.0, v49
	v_mul_f32_e32 v49, v48, v48
	v_fmamk_f32 v49, v49, 0xbdd2d3e7, v129
	v_mul_f32_e32 v49, v49, v48
	v_exp_f32_e32 v49, v49
	v_rcp_f32_e32 v26, v26
	v_cvt_pk_bf16_f32 v24, v24, s0
	ds_write_b16 v35, v24 offset:43248
	v_add_f32_e32 v24, 1.0, v49
	v_fma_f32 v14, v26, v14, -v19
	v_rcp_f32_e32 v24, v24
	v_mul_f32_e32 v14, v39, v14
	v_fmac_f32_e32 v27, v25, v14
	v_cvt_pk_bf16_f32 v14, v27, s0
	v_and_b32_e32 v15, 0xffff0000, v15
	ds_write_b16 v35, v14 offset:43520
	v_fma_f32 v14, v24, v48, -v19
	v_mul_f32_e32 v24, v15, v15
	v_fmamk_f32 v24, v24, 0xbdd2d3e7, v129
	v_mul_f32_e32 v24, v24, v15
	v_exp_f32_e32 v24, v24
	v_lshlrev_b32_e32 v25, 16, v16
	v_mul_f32_e32 v26, v25, v25
	v_fmamk_f32 v26, v26, 0xbdd2d3e7, v129
	v_mul_f32_e32 v26, v26, v25
	v_add_f32_e32 v24, 1.0, v24
	v_rcp_f32_e32 v24, v24
	v_exp_f32_e32 v26, v26
	v_mul_f32_e32 v73, v39, v14
	v_fma_f32 v15, v24, v15, -v19
	v_mul_f32_e32 v72, v39, v15
	v_and_b32_e32 v15, 0xffff0000, v16
	v_add_f32_e32 v14, 1.0, v26
	v_mul_f32_e32 v16, v15, v15
	v_rcp_f32_e32 v14, v14
	v_fmamk_f32 v16, v16, 0xbdd2d3e7, v129
	v_mul_f32_e32 v16, v16, v15
	v_lshlrev_b32_e32 v24, 16, v17
	v_fma_f32 v14, v14, v25, -v19
	v_exp_f32_e32 v16, v16
	v_mul_f32_e32 v25, v24, v24
	v_fmamk_f32 v25, v25, 0xbdd2d3e7, v129
	v_mul_f32_e32 v25, v25, v24
	v_add_f32_e32 v16, 1.0, v16
	v_rcp_f32_e32 v16, v16
	v_exp_f32_e32 v25, v25
	v_mul_f32_e32 v14, v39, v14
	s_waitcnt vmcnt(6)
	v_fma_f32 v14, v60, v14, v66
	v_cvt_pk_bf16_f32 v14, v14, s0
	ds_write_b16 v35, v14 offset:44336
	v_fma_f32 v14, v16, v15, -v19
	v_add_f32_e32 v15, 1.0, v25
	v_rcp_f32_e32 v15, v15
	v_mul_f32_e32 v14, v39, v14
	v_fmac_f32_e32 v67, v14, v61
	v_cvt_pk_bf16_f32 v14, v67, s0
	ds_write_b16 v35, v14 offset:44608
	v_fma_f32 v14, v15, v24, -v19
	v_and_b32_e32 v15, 0xffff0000, v17
	v_mul_f32_e32 v16, v15, v15
	v_fmamk_f32 v16, v16, 0xbdd2d3e7, v129
	v_mul_f32_e32 v16, v16, v15
	v_exp_f32_e32 v16, v16
	v_lshlrev_b32_e32 v17, 16, v10
	v_mul_f32_e32 v24, v17, v17
	v_fmamk_f32 v24, v24, 0xbdd2d3e7, v129
	v_mul_f32_e32 v24, v24, v17
	v_add_f32_e32 v16, 1.0, v16
	v_rcp_f32_e32 v16, v16
	v_exp_f32_e32 v24, v24
	v_and_b32_e32 v10, 0xffff0000, v10
	v_mul_f32_e32 v71, v39, v14
	v_fma_f32 v15, v16, v15, -v19
	v_add_f32_e32 v14, 1.0, v24
	v_mul_f32_e32 v70, v39, v15
	v_mul_f32_e32 v15, v10, v10
	v_rcp_f32_e32 v14, v14
	v_fmamk_f32 v15, v15, 0xbdd2d3e7, v129
	v_mul_f32_e32 v15, v15, v10
	v_fma_f32 v14, v14, v17, -v19
	v_exp_f32_e32 v15, v15
	v_mul_f32_e32 v14, v39, v14
	s_waitcnt vmcnt(1)
	v_fma_f32 v14, v74, v14, v76
	v_cvt_pk_bf16_f32 v14, v14, s0
	ds_write_b16 v35, v14 offset:45424
	v_add_f32_e32 v14, 1.0, v15
	v_lshlrev_b32_e32 v15, 16, v11
	v_rcp_f32_e32 v14, v14
	v_mul_f32_e32 v16, v15, v15
	v_fmamk_f32 v16, v16, 0xbdd2d3e7, v129
	v_mul_f32_e32 v16, v16, v15
	v_and_b32_e32 v11, 0xffff0000, v11
	v_fma_f32 v10, v14, v10, -v19
	v_mul_f32_e32 v14, v11, v11
	v_exp_f32_e32 v16, v16
	v_fmamk_f32 v14, v14, 0xbdd2d3e7, v129
	v_mul_f32_e32 v14, v14, v11
	v_mul_f32_e32 v10, v39, v10
	v_fmac_f32_e32 v77, v75, v10
	v_add_f32_e32 v10, 1.0, v16
	v_exp_f32_e32 v14, v14
	v_rcp_f32_e32 v10, v10
	v_cvt_pk_bf16_f32 v16, v77, s0
	ds_write_b16 v35, v16 offset:45696
	v_add_f32_e32 v14, 1.0, v14
	v_fma_f32 v10, v10, v15, -v19
	v_rcp_f32_e32 v14, v14
	v_lshlrev_b32_e32 v15, 16, v12
	v_mul_f32_e32 v16, v15, v15
	v_fmamk_f32 v16, v16, 0xbdd2d3e7, v129
	v_mul_f32_e32 v16, v16, v15
	v_mul_f32_e32 v67, v39, v10
	v_fma_f32 v10, v14, v11, -v19
	v_and_b32_e32 v11, 0xffff0000, v12
	v_mul_f32_e32 v12, v11, v11
	v_exp_f32_e32 v16, v16
	v_fmamk_f32 v12, v12, 0xbdd2d3e7, v129
	v_mul_f32_e32 v12, v12, v11
	v_mul_f32_e32 v66, v39, v10
	v_add_f32_e32 v10, 1.0, v16
	v_exp_f32_e32 v12, v12
	v_rcp_f32_e32 v10, v10
	v_or_b32_e32 v76, 2, v34
	v_lshlrev_b32_e32 v14, 2, v76
	v_add_f32_e32 v12, 1.0, v12
	v_fma_f32 v10, v10, v15, -v19
	v_rcp_f32_e32 v12, v12
	v_mul_f32_e32 v10, v39, v10
	s_waitcnt vmcnt(0)
	v_fma_f32 v10, v22, v10, v28
	v_cvt_pk_bf16_f32 v10, v10, s0
	ds_write_b16 v35, v10 offset:46512
	v_fma_f32 v10, v12, v11, -v19
	v_lshlrev_b32_e32 v11, 16, v13
	v_mul_f32_e32 v12, v11, v11
	v_fmamk_f32 v12, v12, 0xbdd2d3e7, v129
	v_mul_f32_e32 v12, v12, v11
	v_exp_f32_e32 v12, v12
	v_mul_f32_e32 v10, v39, v10
	v_fmac_f32_e32 v29, v10, v23
	v_cvt_pk_bf16_f32 v10, v29, s0
	global_load_dword v15, v14, s[16:17]
	s_nop 0
	global_load_dword v14, v14, s[20:21]
	ds_write_b16 v35, v10 offset:46784
	v_add_f32_e32 v10, 1.0, v12
	v_rcp_f32_e32 v10, v10
	v_or_b32_e32 v77, 3, v34
	v_lshlrev_b32_e32 v12, 2, v77
	global_load_dword v16, v12, s[16:17]
	global_load_dword v17, v12, s[20:21]
	v_fma_f32 v10, v10, v11, -v19
	v_and_b32_e32 v11, 0xffff0000, v13
	v_mul_f32_e32 v12, v11, v11
	v_fmamk_f32 v12, v12, 0xbdd2d3e7, v129
	v_mul_f32_e32 v12, v12, v11
	v_lshlrev_b32_e32 v13, 16, v6
	v_exp_f32_e32 v12, v12
	v_mul_f32_e32 v22, v13, v13
	v_fmamk_f32 v22, v22, 0xbdd2d3e7, v129
	v_mul_f32_e32 v22, v22, v13
	v_add_f32_e32 v12, 1.0, v12
	v_exp_f32_e32 v22, v22
	v_rcp_f32_e32 v12, v12
	v_mul_f32_e32 v75, v39, v10
	v_and_b32_e32 v6, 0xffff0000, v6
	v_add_f32_e32 v10, 1.0, v22
	v_fma_f32 v11, v12, v11, -v19
	v_rcp_f32_e32 v10, v10
	v_mul_f32_e32 v74, v39, v11
	v_mul_f32_e32 v11, v6, v6
	v_fmamk_f32 v11, v11, 0xbdd2d3e7, v129
	v_mul_f32_e32 v11, v11, v6
	v_fma_f32 v10, v10, v13, -v19
	v_exp_f32_e32 v22, v11
	v_mul_f32_e32 v82, v39, v10
	global_load_dwordx2 v[10:11], v20, s[16:17] offset:192
	global_load_dwordx2 v[12:13], v20, s[20:21] offset:192
	v_lshlrev_b32_e32 v23, 16, v7
	v_mul_f32_e32 v24, v23, v23
	v_and_b32_e32 v7, 0xffff0000, v7
	v_fmamk_f32 v24, v24, 0xbdd2d3e7, v129
	v_mul_f32_e32 v25, v7, v7
	v_mul_f32_e32 v24, v24, v23
	v_fmamk_f32 v25, v25, 0xbdd2d3e7, v129
	v_mul_f32_e32 v25, v25, v7
	v_add_f32_e32 v22, 1.0, v22
	v_rcp_f32_e32 v22, v22
	v_exp_f32_e32 v24, v24
	v_exp_f32_e32 v25, v25
	v_fma_f32 v6, v22, v6, -v19
	v_add_f32_e32 v22, 1.0, v24
	v_rcp_f32_e32 v22, v22
	v_add_f32_e32 v24, 1.0, v25
	v_rcp_f32_e32 v24, v24
	v_mul_f32_e32 v83, v39, v6
	v_fma_f32 v6, v22, v23, -v19
	v_mul_f32_e32 v62, v39, v6
	v_fma_f32 v6, v24, v7, -v19
	v_lshlrev_b32_e32 v91, 16, v8
	v_mul_f32_e32 v61, v39, v6
	v_or_b32_e32 v6, s88, v31
	v_lshlrev_b32_e32 v6, 7, v6
	v_mov_b32_e32 v7, v1
	v_lshl_add_u64 v[6:7], v[6:7], 2, s[40:41]
	v_lshl_add_u64 v[6:7], v[6:7], 0, v[20:21]
	v_and_b32_e32 v8, 0xffff0000, v8
	v_mul_f32_e32 v98, v8, v8
	v_fmamk_f32 v98, v98, 0xbdd2d3e7, v129
	v_mul_f32_e32 v98, v98, v8
	v_exp_f32_e32 v98, v98
	v_and_b32_e32 v99, 0xffff0000, v9
	v_and_b32_e32 v105, 0xffff0000, v5
	s_waitcnt vmcnt(4)
	v_fmac_f32_e32 v14, v15, v65
	v_mul_u32_u24_e32 v15, 0x110, v76
	v_cvt_pk_bf16_f32 v14, v14, s0
	v_add3_u32 v15, s15, v15, v33
	v_or_b32_e32 v65, 6, v34
	ds_write_b16 v15, v14 offset:34816
	v_lshlrev_b32_e32 v14, 2, v65
	global_load_dword v85, v14, s[16:17]
	global_load_dword v86, v14, s[20:21]
	s_waitcnt vmcnt(4)
	v_fmac_f32_e32 v17, v16, v59
	v_lshlrev_b32_e32 v14, 2, v78
	v_mul_u32_u24_e32 v15, 0x110, v77
	global_load_dword v87, v14, s[16:17]
	global_load_dword v88, v14, s[20:21]
	v_cvt_pk_bf16_f32 v14, v17, s0
	v_add3_u32 v15, s15, v15, v33
	ds_write_b16 v15, v14 offset:34816
	v_lshlrev_b32_e32 v14, 2, v81
	global_load_dwordx2 v[22:23], v20, s[16:17] offset:208
	global_load_dwordx2 v[24:25], v20, s[20:21] offset:208
	global_load_dword v89, v14, s[16:17]
	global_load_dword v90, v14, s[20:21]
	v_lshlrev_b32_e32 v14, 2, v79
	global_load_dword v92, v14, s[16:17]
	global_load_dword v93, v14, s[20:21]
	v_mul_f32_e32 v14, v91, v91
	v_fmamk_f32 v14, v14, 0xbdd2d3e7, v129
	v_mul_f32_e32 v14, v14, v91
	v_or_b32_e32 v59, 14, v34
	v_lshlrev_b32_e32 v15, 2, v59
	global_load_dword v94, v15, s[16:17]
	global_load_dword v95, v15, s[20:21]
	v_exp_f32_e32 v96, v14
	global_load_dwordx2 v[14:15], v20, s[16:17] offset:224
	global_load_dwordx2 v[16:17], v20, s[16:17] offset:240
	global_load_dwordx2 v[26:27], v20, s[20:21] offset:224
	s_nop 0
	global_load_dwordx2 v[20:21], v20, s[20:21] offset:240
	v_or_b32_e32 v40, 20, v34
	v_or_b32_e32 v41, 24, v34
	v_or_b32_e32 v42, 28, v34
	v_or_b32_e32 v43, 32, v34
	v_or_b32_e32 v48, 36, v34
	v_or_b32_e32 v49, 40, v34
	v_or_b32_e32 v51, 44, v34
	v_or_b32_e32 v60, 52, v34
	s_waitcnt vmcnt(16)
	v_fma_f32 v10, v10, v82, v12
	v_cvt_pk_bf16_f32 v12, v10, s0
	v_or_b32_e32 v10, 15, v34
	v_add_f32_e32 v82, 1.0, v96
	v_lshlrev_b32_e32 v96, 2, v10
	global_load_dword v97, v96, s[16:17]
	s_nop 0
	global_load_dword v96, v96, s[20:21]
	v_rcp_f32_e32 v82, v82
	ds_write_b16 v35, v12 offset:47600
	v_fmac_f32_e32 v13, v11, v83
	v_cvt_pk_bf16_f32 v11, v13, s0
	v_fma_f32 v12, v82, v91, -v19
	v_lshlrev_b32_e32 v91, 16, v9
	v_add_f32_e32 v82, 1.0, v98
	v_mul_f32_e32 v98, v91, v91
	v_fmamk_f32 v98, v98, 0xbdd2d3e7, v129
	v_mul_f32_e32 v98, v98, v91
	v_rcp_f32_e32 v82, v82
	v_exp_f32_e32 v98, v98
	v_mul_f32_e32 v12, v39, v12
	v_mul_u32_u24_e32 v13, 0x110, v81
	v_fma_f32 v8, v82, v8, -v19
	v_add_f32_e32 v82, 1.0, v98
	v_rcp_f32_e32 v82, v82
	v_mul_f32_e32 v100, v39, v8
	v_add3_u32 v13, s15, v13, v33
	v_mul_f32_e32 v9, v99, v99
	v_fma_f32 v8, v82, v91, -v19
	v_mul_u32_u24_e32 v82, 0x110, v65
	v_add3_u32 v82, s15, v82, v33
	v_fmamk_f32 v9, v9, 0xbdd2d3e7, v129
	v_mul_f32_e32 v9, v9, v99
	v_exp_f32_e32 v9, v9
	v_or_b32_e32 v91, 26, v34
	v_or_b32_e32 v29, 56, v34
	v_or_b32_e32 v28, 60, v34
	v_add_f32_e32 v9, 1.0, v9
	v_rcp_f32_e32 v98, v9
	v_mul_f32_e32 v9, v39, v8
	v_readlane_b32 s46, v251, 56
	v_readlane_b32 s47, v251, 57
	v_fma_f32 v8, v98, v99, -v19
	v_or_b32_e32 v98, 30, v34
	v_mul_f32_e32 v8, v39, v8
	v_readlane_b32 s48, v251, 58
	v_readlane_b32 s49, v251, 59
	s_waitcnt vmcnt(16)
	v_fmac_f32_e32 v86, v45, v85
	v_cvt_pk_bf16_f32 v45, v86, s0
	ds_write_b16 v82, v45 offset:34816
	v_mul_u32_u24_e32 v45, 0x110, v78
	s_waitcnt vmcnt(14)
	v_fmac_f32_e32 v88, v44, v87
	v_cvt_pk_bf16_f32 v44, v88, s0
	v_add3_u32 v45, s15, v45, v33
	ds_write_b16 v45, v44 offset:34816
	ds_write_b16 v35, v11 offset:47872
	s_waitcnt vmcnt(12)
	v_fma_f32 v11, v22, v12, v24
	s_waitcnt vmcnt(10)
	v_fmac_f32_e32 v90, v89, v47
	v_cvt_pk_bf16_f32 v12, v90, s0
	ds_write_b16 v13, v12 offset:34816
	s_waitcnt vmcnt(8)
	v_fmac_f32_e32 v93, v92, v46
	v_mul_u32_u24_e32 v13, 0x110, v79
	v_cvt_pk_bf16_f32 v12, v93, s0
	v_add3_u32 v13, s15, v13, v33
	v_cvt_pk_bf16_f32 v11, v11, s0
	ds_write_b16 v13, v12 offset:34816
	ds_write_b16 v35, v11 offset:48688
	v_lshlrev_b32_e32 v13, 16, v2
	v_mul_f32_e32 v22, v13, v13
	v_fmamk_f32 v22, v22, 0xbdd2d3e7, v129
	v_mul_f32_e32 v22, v22, v13
	v_exp_f32_e32 v22, v22
	v_fmac_f32_e32 v25, v100, v23
	v_cvt_pk_bf16_f32 v11, v25, s0
	s_waitcnt vmcnt(6)
	v_fmac_f32_e32 v95, v55, v94
	v_mul_u32_u24_e32 v12, 0x110, v59
	ds_write_b16 v35, v11 offset:48960
	v_cvt_pk_bf16_f32 v11, v95, s0
	v_add3_u32 v12, s15, v12, v33
	ds_write_b16 v12, v11 offset:34816
	v_add_f32_e32 v12, 1.0, v22
	v_rcp_f32_e32 v12, v12
	s_waitcnt vmcnt(0)
	v_fmac_f32_e32 v96, v54, v97
	v_mul_u32_u24_e32 v22, 0x110, v10
	v_cvt_pk_bf16_f32 v11, v96, s0
	v_add3_u32 v22, s15, v22, v33
	v_and_b32_e32 v2, 0xffff0000, v2
	ds_write_b16 v22, v11 offset:34816
	v_fma_f32 v11, v12, v13, -v19
	v_mul_f32_e32 v12, v2, v2
	v_lshlrev_b32_e32 v13, 16, v3
	v_fmamk_f32 v12, v12, 0xbdd2d3e7, v129
	v_mul_f32_e32 v22, v13, v13
	v_mul_f32_e32 v12, v12, v2
	v_fmamk_f32 v22, v22, 0xbdd2d3e7, v129
	v_mul_f32_e32 v22, v22, v13
	v_exp_f32_e32 v12, v12
	v_exp_f32_e32 v22, v22
	v_mul_f32_e32 v11, v39, v11
	v_add_f32_e32 v12, 1.0, v12
	v_fma_f32 v11, v14, v11, v26
	v_rcp_f32_e32 v12, v12
	v_add_f32_e32 v14, 1.0, v22
	v_rcp_f32_e32 v14, v14
	v_and_b32_e32 v3, 0xffff0000, v3
	v_fma_f32 v2, v12, v2, -v19
	v_mul_f32_e32 v12, v39, v2
	v_fma_f32 v2, v14, v13, -v19
	v_mul_f32_e32 v13, v3, v3
	v_fmamk_f32 v13, v13, 0xbdd2d3e7, v129
	v_mul_f32_e32 v13, v13, v3
	v_or_b32_e32 v86, 18, v34
	v_or_b32_e32 v87, 19, v34
	v_lshlrev_b32_e32 v14, 2, v86
	v_lshlrev_b32_e32 v22, 2, v87
	global_load_dword v26, v14, s[16:17]
	s_nop 0
	global_load_dword v14, v14, s[20:21]
	s_nop 0
	global_load_dword v54, v22, s[16:17]
	global_load_dword v55, v22, s[20:21]
	v_lshlrev_b32_e32 v22, 16, v4
	v_exp_f32_e32 v13, v13
	v_mul_f32_e32 v23, v22, v22
	v_fmamk_f32 v23, v23, 0xbdd2d3e7, v129
	v_mul_f32_e32 v23, v23, v22
	v_add_f32_e32 v13, 1.0, v13
	v_rcp_f32_e32 v13, v13
	v_exp_f32_e32 v23, v23
	v_or_b32_e32 v88, 22, v34
	v_lshlrev_b32_e32 v24, 2, v88
	v_fma_f32 v3, v13, v3, -v19
	v_add_f32_e32 v13, 1.0, v23
	global_load_dword v82, v24, s[16:17]
	global_load_dword v83, v24, s[20:21]
	v_or_b32_e32 v89, 23, v34
	v_rcp_f32_e32 v13, v13
	v_and_b32_e32 v4, 0xffff0000, v4
	v_lshlrev_b32_e32 v24, 2, v89
	v_mul_f32_e32 v23, v4, v4
	global_load_dword v84, v24, s[16:17]
	global_load_dword v85, v24, s[20:21]
	v_fmamk_f32 v23, v23, 0xbdd2d3e7, v129
	v_mul_f32_e32 v23, v23, v4
	v_fma_f32 v13, v13, v22, -v19
	v_lshlrev_b32_e32 v22, 2, v91
	global_load_dword v92, v22, s[16:17]
	global_load_dword v93, v22, s[20:21]
	v_or_b32_e32 v94, 27, v34
	v_exp_f32_e32 v23, v23
	v_lshlrev_b32_e32 v22, 2, v94
	global_load_dword v95, v22, s[16:17]
	global_load_dword v96, v22, s[20:21]
	v_lshlrev_b32_e32 v97, 16, v5
	v_lshlrev_b32_e32 v22, 2, v98
	global_load_dword v99, v22, s[16:17]
	global_load_dword v100, v22, s[20:21]
	v_mul_f32_e32 v22, 0x3d372713, v97
	v_mul_f32_e32 v90, v39, v13
	v_add_f32_e32 v13, 1.0, v23
	v_lshlrev_b32_e32 v23, 2, v101
	v_mul_f32_e32 v22, v22, v97
	global_load_dword v102, v23, s[16:17]
	global_load_dword v103, v23, s[20:21]
	v_fma_f32 v22, v22, v97, v97
	v_mul_f32_e32 v22, 0xbfcc422a, v22
	v_mul_f32_e32 v104, 0x3fb8aa3b, v22
	global_load_dwordx4 v[22:25], v[6:7], off offset:16
	global_load_dwordx4 v[44:47], v[6:7], off
	v_rcp_f32_e32 v13, v13
	v_exp_f32_e32 v104, v104
	v_mul_f32_e32 v5, v105, v105
	v_fmamk_f32 v5, v5, 0xbdd2d3e7, v129
	v_mul_f32_e32 v5, v5, v105
	v_fma_f32 v4, v13, v4, -v19
	v_add_f32_e32 v13, 1.0, v104
	v_rcp_f32_e32 v13, v13
	v_exp_f32_e32 v5, v5
	v_mul_f32_e32 v106, v39, v4
	v_cvt_pk_bf16_f32 v11, v11, s0
	v_fma_f32 v4, v13, v97, -v19
	v_add_f32_e32 v5, 1.0, v5
	v_rcp_f32_e32 v104, v5
	v_fmac_f32_e32 v27, v15, v12
	v_mul_f32_e32 v5, v39, v4
	v_fma_f32 v16, v16, v90, v20
	v_fma_f32 v4, v104, v105, -v19
	v_mul_u32_u24_e32 v19, 0x110, v88
	v_add3_u32 v19, s15, v19, v33
	v_cvt_pk_bf16_f32 v16, v16, s0
	v_fmac_f32_e32 v21, v106, v17
	v_mul_f32_e32 v2, v39, v2
	v_mul_f32_e32 v3, v39, v3
	v_mul_f32_e32 v4, v39, v4
	v_mul_u32_u24_e32 v17, 0x110, v91
	v_add3_u32 v17, s15, v17, v33
	v_readlane_b32 s56, v252, 2
	v_readlane_b32 s57, v252, 3
	v_readlane_b32 s58, v252, 4
	v_readlane_b32 s59, v252, 5
	s_waitcnt vmcnt(16)
	v_fmac_f32_e32 v14, v26, v53
	v_cvt_pk_bf16_f32 v13, v14, s0
	v_mul_u32_u24_e32 v14, 0x110, v86
	v_add3_u32 v14, s15, v14, v33
	ds_write_b16 v14, v13 offset:34816
	s_waitcnt vmcnt(14)
	v_fmac_f32_e32 v55, v54, v52
	v_mul_u32_u24_e32 v14, 0x110, v87
	v_cvt_pk_bf16_f32 v13, v55, s0
	v_add3_u32 v14, s15, v14, v33
	ds_write_b16 v14, v13 offset:34816
	ds_write_b16 v35, v11 offset:49776
	v_cvt_pk_bf16_f32 v11, v27, s0
	ds_write_b16 v35, v11 offset:50048
	global_load_dwordx4 v[12:15], v[6:7], off offset:48
	global_load_dwordx4 v[52:55], v[6:7], off offset:32
	s_waitcnt vmcnt(14)
	v_fmac_f32_e32 v83, v58, v82
	v_cvt_pk_bf16_f32 v11, v83, s0
	ds_write_b16 v19, v11 offset:34816
	v_mul_u32_u24_e32 v19, 0x110, v89
	v_add3_u32 v19, s15, v19, v33
	v_or_b32_e32 v58, 35, v34
	s_waitcnt vmcnt(12)
	v_fmac_f32_e32 v85, v56, v84
	v_cvt_pk_bf16_f32 v11, v85, s0
	v_or_b32_e32 v56, 34, v34
	ds_write_b16 v19, v11 offset:34816
	v_lshlrev_b32_e32 v11, 2, v56
	v_lshlrev_b32_e32 v19, 2, v58
	global_load_dword v39, v11, s[16:17]
	s_nop 0
	global_load_dword v11, v11, s[20:21]
	s_nop 0
	global_load_dword v90, v19, s[16:17]
	global_load_dword v97, v19, s[20:21]
	ds_write_b16 v35, v16 offset:50864
	v_cvt_pk_bf16_f32 v16, v21, s0
	s_waitcnt vmcnt(14)
	v_fmac_f32_e32 v93, v92, v64
	ds_write_b16 v35, v16 offset:51136
	v_cvt_pk_bf16_f32 v16, v93, s0
	ds_write_b16 v17, v16 offset:34816
	s_waitcnt vmcnt(12)
	v_fmac_f32_e32 v96, v95, v63
	v_mul_u32_u24_e32 v17, 0x110, v94
	v_cvt_pk_bf16_f32 v16, v96, s0
	v_add3_u32 v17, s15, v17, v33
	ds_write_b16 v17, v16 offset:34816
	s_waitcnt vmcnt(10)
	v_fmac_f32_e32 v100, v69, v99
	v_mul_u32_u24_e32 v17, 0x110, v98
	v_cvt_pk_bf16_f32 v16, v100, s0
	v_add3_u32 v17, s15, v17, v33
	ds_write_b16 v17, v16 offset:34816
	s_waitcnt vmcnt(8)
	v_fmac_f32_e32 v103, v68, v102
	v_mul_u32_u24_e32 v17, 0x110, v101
	v_cvt_pk_bf16_f32 v16, v103, s0
	v_add3_u32 v17, s15, v17, v33
	ds_write_b16 v17, v16 offset:34816
	s_waitcnt vmcnt(6)
	v_cndmask_b32_e32 v16, 0, v45, vcc
	v_cmp_le_u32_e32 vcc, v34, v31
	v_or_b32_e32 v35, 38, v34
	v_or_b32_e32 v68, 39, v34
	v_cndmask_b32_e32 v17, 0, v44, vcc
	v_cvt_pk_bf16_f32 v16, v17, v16
	v_lshlrev_b32_e32 v17, 2, v35
	global_load_dword v63, v17, s[16:17]
	global_load_dword v64, v17, s[20:21]
	v_lshlrev_b32_e32 v19, 2, v68
	global_load_dword v69, v19, s[16:17]
	global_load_dword v92, v19, s[20:21]
	v_cvt_pk_bf16_f32 v17, v46, v47
	v_cmp_le_u32_e32 vcc, v76, v31
	global_load_dwordx4 v[44:47], v[6:7], off offset:80
	global_load_dwordx4 v[82:85], v[6:7], off offset:64
	v_cndmask_b32_e32 v19, 0, v17, vcc
	v_lshrrev_b32_e32 v17, 16, v17
	v_cmp_le_u32_e32 vcc, v77, v31
	v_or_b32_e32 v77, 47, v34
	s_waitcnt vmcnt(8)
	v_fmac_f32_e32 v11, v39, v73
	v_cndmask_b32_e32 v17, 0, v17, vcc
	v_cmp_gt_u32_e32 vcc, v31, v18
	v_perm_b32 v17, v17, v19, s19
	v_cvt_pk_bf16_f32 v11, v11, s0
	v_cndmask_b32_e32 v19, 0, v23, vcc
	v_cmp_le_u32_e32 vcc, v18, v31
	s_waitcnt vmcnt(6)
	v_fmac_f32_e32 v97, v90, v72
	s_waitcnt vmcnt(4)
	v_fmac_f32_e32 v64, v71, v63
	v_cndmask_b32_e32 v18, 0, v22, vcc
	v_cvt_pk_bf16_f32 v18, v18, v19
	v_cvt_pk_bf16_f32 v19, v24, v25
	v_cmp_le_u32_e32 vcc, v65, v31
	s_waitcnt vmcnt(2)
	v_fmac_f32_e32 v92, v70, v69
	v_cndmask_b32_e32 v20, 0, v19, vcc
	v_lshrrev_b32_e32 v19, 16, v19
	v_cmp_le_u32_e32 vcc, v78, v31
	s_nop 1
	v_cndmask_b32_e32 v19, 0, v19, vcc
	v_perm_b32 v19, v19, v20, s19
	ds_write_b128 v0, v[16:19]
	global_load_dwordx4 v[20:23], v[6:7], off offset:112
	global_load_dwordx4 v[24:27], v[6:7], off offset:96
	v_cmp_gt_u32_e32 vcc, v31, v36
	s_nop 1
	v_cndmask_b32_e32 v16, 0, v53, vcc
	v_cmp_le_u32_e32 vcc, v36, v31
	s_nop 1
	v_cndmask_b32_e32 v17, 0, v52, vcc
	v_cvt_pk_bf16_f32 v16, v17, v16
	v_cvt_pk_bf16_f32 v17, v54, v55
	v_cmp_le_u32_e32 vcc, v81, v31
	v_or_b32_e32 v52, 42, v34
	v_or_b32_e32 v55, 43, v34
	v_cndmask_b32_e32 v18, 0, v17, vcc
	v_lshrrev_b32_e32 v17, 16, v17
	v_cmp_le_u32_e32 vcc, v79, v31
	v_lshlrev_b32_e32 v19, 2, v55
	v_and_or_b32 v81, v30, 64, v32
	v_cndmask_b32_e32 v17, 0, v17, vcc
	v_perm_b32 v17, v17, v18, s19
	v_mul_u32_u24_e32 v18, 0x110, v56
	v_add3_u32 v18, s15, v18, v33
	ds_write_b16 v18, v11 offset:34816
	v_lshlrev_b32_e32 v18, 2, v52
	global_load_dword v53, v18, s[16:17]
	global_load_dword v54, v18, s[20:21]
	v_mul_u32_u24_e32 v18, 0x110, v58
	v_cvt_pk_bf16_f32 v11, v97, s0
	v_add3_u32 v18, s15, v18, v33
	v_cmp_gt_u32_e32 vcc, v31, v37
	global_load_dword v65, v19, s[16:17]
	global_load_dword v72, v19, s[20:21]
	ds_write_b16 v18, v11 offset:34816
	v_cndmask_b32_e32 v11, 0, v13, vcc
	v_cmp_le_u32_e32 vcc, v37, v31
	s_waitcnt vmcnt(2)
	v_fmac_f32_e32 v54, v53, v67
	v_cndmask_b32_e32 v12, 0, v12, vcc
	v_cvt_pk_bf16_f32 v18, v12, v11
	v_cvt_pk_bf16_f32 v11, v14, v15
	v_cmp_le_u32_e32 vcc, v59, v31
	v_or_b32_e32 v59, 46, v34
	s_waitcnt vmcnt(0)
	v_fmac_f32_e32 v72, v65, v66
	v_cndmask_b32_e32 v12, 0, v11, vcc
	v_lshrrev_b32_e32 v11, 16, v11
	v_cmp_le_u32_e32 vcc, v10, v31
	s_nop 1
	v_cndmask_b32_e32 v10, 0, v11, vcc
	v_perm_b32 v19, v10, v12, s19
	v_lshlrev_b32_e32 v10, 2, v59
	global_load_dword v73, v10, s[16:17]
	global_load_dword v76, v10, s[20:21]
	ds_write_b128 v0, v[16:19] offset:16
	v_lshlrev_b32_e32 v10, 2, v77
	v_mul_u32_u24_e32 v11, 0x110, v35
	global_load_dword v78, v10, s[16:17]
	global_load_dword v79, v10, s[20:21]
	v_cvt_pk_bf16_f32 v10, v64, s0
	v_add3_u32 v11, s15, v11, v33
	ds_write_b16 v11, v10 offset:34816
	global_load_dwordx4 v[10:13], v[6:7], off offset:144
	global_load_dwordx4 v[14:17], v[6:7], off offset:128
	v_mul_u32_u24_e32 v19, 0x110, v68
	v_cvt_pk_bf16_f32 v18, v92, s0
	v_add3_u32 v19, s15, v19, v33
	v_cmp_gt_u32_e32 vcc, v31, v38
	ds_write_b16 v19, v18 offset:34816
	s_waitcnt vmcnt(4)
	v_fmac_f32_e32 v76, v75, v73
	v_cndmask_b32_e32 v18, 0, v83, vcc
	v_cmp_le_u32_e32 vcc, v38, v31
	s_waitcnt vmcnt(2)
	v_fmac_f32_e32 v79, v74, v78
	v_cndmask_b32_e32 v19, 0, v82, vcc
	v_cvt_pk_bf16_f32 v36, v19, v18
	v_cvt_pk_bf16_f32 v18, v84, v85
	v_cmp_le_u32_e32 vcc, v86, v31
	v_or_b32_e32 v82, s4, v81
	s_nop 0
	v_cndmask_b32_e32 v19, 0, v18, vcc
	v_lshrrev_b32_e32 v18, 16, v18
	v_cmp_le_u32_e32 vcc, v87, v31
	s_nop 1
	v_cndmask_b32_e32 v18, 0, v18, vcc
	v_cmp_gt_u32_e32 vcc, v31, v40
	v_perm_b32 v37, v18, v19, s19
	s_nop 0
	v_cndmask_b32_e32 v18, 0, v45, vcc
	v_cmp_le_u32_e32 vcc, v40, v31
	s_nop 1
	v_cndmask_b32_e32 v19, 0, v44, vcc
	v_cvt_pk_bf16_f32 v38, v19, v18
	v_cvt_pk_bf16_f32 v18, v46, v47
	v_cmp_le_u32_e32 vcc, v88, v31
	s_nop 1
	v_cndmask_b32_e32 v19, 0, v18, vcc
	v_lshrrev_b32_e32 v18, 16, v18
	v_cmp_le_u32_e32 vcc, v89, v31
	s_nop 1
	v_cndmask_b32_e32 v18, 0, v18, vcc
	v_cmp_gt_u32_e32 vcc, v31, v41
	v_perm_b32 v39, v18, v19, s19
	ds_write_b128 v0, v[36:39] offset:32
	v_cndmask_b32_e32 v18, 0, v25, vcc
	v_cmp_le_u32_e32 vcc, v41, v31
	v_mul_u32_u24_e32 v41, 0x110, v52
	v_add3_u32 v41, s15, v41, v33
	v_cndmask_b32_e32 v19, 0, v24, vcc
	v_cvt_pk_bf16_f32 v18, v19, v18
	v_cvt_pk_bf16_f32 v19, v26, v27
	global_load_dwordx4 v[24:27], v[6:7], off offset:176
	global_load_dwordx4 v[36:39], v[6:7], off offset:160
	v_cmp_le_u32_e32 vcc, v91, v31
	s_nop 1
	v_cndmask_b32_e32 v40, 0, v19, vcc
	v_lshrrev_b32_e32 v19, 16, v19
	v_cmp_le_u32_e32 vcc, v94, v31
	s_nop 1
	v_cndmask_b32_e32 v19, 0, v19, vcc
	v_cmp_gt_u32_e32 vcc, v31, v42
	v_perm_b32 v19, v19, v40, s19
	v_cvt_pk_bf16_f32 v40, v54, s0
	v_cndmask_b32_e32 v21, 0, v21, vcc
	v_cmp_le_u32_e32 vcc, v42, v31
	ds_write_b16 v41, v40 offset:34816
	v_mul_u32_u24_e32 v41, 0x110, v55
	v_cndmask_b32_e32 v20, 0, v20, vcc
	v_cvt_pk_bf16_f32 v20, v20, v21
	v_cvt_pk_bf16_f32 v21, v22, v23
	v_cmp_le_u32_e32 vcc, v98, v31
	v_cvt_pk_bf16_f32 v40, v72, s0
	v_add3_u32 v41, s15, v41, v33
	v_cndmask_b32_e32 v22, 0, v21, vcc
	v_lshrrev_b32_e32 v21, 16, v21
	v_cmp_le_u32_e32 vcc, v101, v31
	ds_write_b16 v41, v40 offset:34816
	v_mul_u32_u24_e32 v23, 0x110, v77
	v_cndmask_b32_e32 v21, 0, v21, vcc
	v_perm_b32 v21, v21, v22, s19
	ds_write_b128 v0, v[18:21] offset:48
	v_mul_u32_u24_e32 v19, 0x110, v59
	v_cvt_pk_bf16_f32 v18, v76, s0
	v_add3_u32 v19, s15, v19, v33
	v_cmp_gt_u32_e32 vcc, v31, v43
	ds_write_b16 v19, v18 offset:34816
	v_cvt_pk_bf16_f32 v22, v79, s0
	v_add3_u32 v23, s15, v23, v33
	s_waitcnt vmcnt(2)
	v_cndmask_b32_e32 v15, 0, v15, vcc
	v_cmp_le_u32_e32 vcc, v43, v31
	global_load_dwordx4 v[18:21], v[6:7], off offset:208
	global_load_dwordx4 v[44:47], v[6:7], off offset:192
	ds_write_b16 v23, v22 offset:34816
	v_cndmask_b32_e32 v14, 0, v14, vcc
	v_or_b32_e32 v23, 50, v34
	v_cvt_pk_bf16_f32 v14, v14, v15
	v_cvt_pk_bf16_f32 v15, v16, v17
	v_or_b32_e32 v22, 51, v34
	v_lshlrev_b32_e32 v17, 2, v23
	v_cmp_le_u32_e32 vcc, v56, v31
	global_load_dword v40, v17, s[16:17]
	global_load_dword v41, v17, s[20:21]
	v_lshlrev_b32_e32 v17, 2, v22
	v_cndmask_b32_e32 v16, 0, v15, vcc
	v_lshrrev_b32_e32 v15, 16, v15
	global_load_dword v42, v17, s[16:17]
	global_load_dword v43, v17, s[20:21]
	v_cmp_le_u32_e32 vcc, v58, v31
	s_waitcnt vmcnt(2)
	v_fmac_f32_e32 v41, v40, v62
	v_cndmask_b32_e32 v15, 0, v15, vcc
	v_cmp_gt_u32_e32 vcc, v31, v48
	v_perm_b32 v15, v15, v16, s19
	s_waitcnt vmcnt(0)
	v_fmac_f32_e32 v43, v42, v61
	v_cndmask_b32_e32 v11, 0, v11, vcc
	v_cmp_le_u32_e32 vcc, v48, v31
	v_or_b32_e32 v48, 54, v34
	s_nop 0
	v_cndmask_b32_e32 v10, 0, v10, vcc
	v_cvt_pk_bf16_f32 v16, v10, v11
	v_cvt_pk_bf16_f32 v10, v12, v13
	v_cmp_le_u32_e32 vcc, v35, v31
	v_or_b32_e32 v35, 55, v34
	s_nop 0
	v_cndmask_b32_e32 v11, 0, v10, vcc
	v_lshrrev_b32_e32 v10, 16, v10
	v_cmp_le_u32_e32 vcc, v68, v31
	s_nop 1
	v_cndmask_b32_e32 v10, 0, v10, vcc
	v_perm_b32 v17, v10, v11, s19
	v_lshlrev_b32_e32 v10, 2, v48
	global_load_dword v53, v10, s[16:17]
	global_load_dword v54, v10, s[20:21]
	v_lshlrev_b32_e32 v10, 2, v35
	global_load_dword v56, v10, s[16:17]
	global_load_dword v58, v10, s[20:21]
	v_cmp_gt_u32_e32 vcc, v31, v49
	ds_write_b128 v0, v[14:17] offset:64
	s_waitcnt vmcnt(2)
	v_fmac_f32_e32 v54, v9, v53
	v_cndmask_b32_e32 v10, 0, v37, vcc
	v_cmp_le_u32_e32 vcc, v49, v31
	v_or_b32_e32 v49, 59, v34
	v_cvt_pk_bf16_f32 v9, v54, s0
	v_cndmask_b32_e32 v11, 0, v36, vcc
	v_cvt_pk_bf16_f32 v10, v11, v10
	v_cvt_pk_bf16_f32 v11, v38, v39
	v_cmp_le_u32_e32 vcc, v52, v31
	global_load_dwordx4 v[14:17], v[6:7], off offset:240
	global_load_dwordx4 v[36:39], v[6:7], off offset:224
	v_cndmask_b32_e32 v12, 0, v11, vcc
	v_lshrrev_b32_e32 v11, 16, v11
	v_cmp_le_u32_e32 vcc, v55, v31
	v_or_b32_e32 v52, 58, v34
	s_waitcnt vmcnt(2)
	v_fmac_f32_e32 v58, v8, v56
	v_cndmask_b32_e32 v6, 0, v11, vcc
	v_perm_b32 v11, v6, v12, s19
	v_lshlrev_b32_e32 v6, 2, v52
	global_load_dword v55, v6, s[16:17]
	global_load_dword v63, v6, s[20:21]
	v_lshlrev_b32_e32 v6, 2, v49
	v_cmp_gt_u32_e32 vcc, v31, v51
	global_load_dword v64, v6, s[16:17]
	global_load_dword v65, v6, s[20:21]
	v_cndmask_b32_e32 v6, 0, v25, vcc
	v_cmp_le_u32_e32 vcc, v51, v31
	s_waitcnt vmcnt(2)
	v_fmac_f32_e32 v63, v55, v2
	v_cndmask_b32_e32 v7, 0, v24, vcc
	v_cvt_pk_bf16_f32 v12, v7, v6
	v_cvt_pk_bf16_f32 v6, v26, v27
	v_cmp_le_u32_e32 vcc, v59, v31
	v_mul_u32_u24_e32 v26, 0x110, v22
	v_cvt_pk_bf16_f32 v27, v41, s0
	v_cndmask_b32_e32 v7, 0, v6, vcc
	v_lshrrev_b32_e32 v6, 16, v6
	v_cmp_le_u32_e32 vcc, v77, v31
	v_add3_u32 v26, s15, v26, v33
	v_cvt_pk_bf16_f32 v2, v63, s0
	v_cndmask_b32_e32 v6, 0, v6, vcc
	v_perm_b32 v13, v6, v7, s19
	ds_write_b128 v0, v[10:13] offset:80
	v_or_b32_e32 v11, 62, v34
	v_or_b32_e32 v10, 63, v34
	v_lshlrev_b32_e32 v7, 2, v11
	global_load_dword v12, v7, s[16:17]
	global_load_dword v13, v7, s[20:21]
	v_lshlrev_b32_e32 v7, 2, v10
	global_load_dword v24, v7, s[16:17]
	global_load_dword v25, v7, s[20:21]
	v_cmp_gt_u32_e32 vcc, v31, v57
	s_waitcnt vmcnt(4)
	v_fmac_f32_e32 v65, v64, v3
	s_waitcnt vmcnt(2)
	v_fmac_f32_e32 v13, v5, v12
	v_cndmask_b32_e32 v6, 0, v45, vcc
	v_cmp_le_u32_e32 vcc, v57, v31
	v_cvt_pk_bf16_f32 v5, v13, s0
	s_waitcnt vmcnt(0)
	v_fmac_f32_e32 v25, v4, v24
	v_cndmask_b32_e32 v7, 0, v44, vcc
	v_cvt_pk_bf16_f32 v6, v7, v6
	v_mul_u32_u24_e32 v7, 0x110, v23
	v_add3_u32 v7, s15, v7, v33
	ds_write_b16 v7, v27 offset:34816
	v_cvt_pk_bf16_f32 v7, v43, s0
	ds_write_b16 v26, v7 offset:34816
	v_cvt_pk_bf16_f32 v7, v46, v47
	v_cmp_le_u32_e32 vcc, v23, v31
	s_nop 1
	v_cndmask_b32_e32 v23, 0, v7, vcc
	v_lshrrev_b32_e32 v7, 16, v7
	v_cmp_le_u32_e32 vcc, v22, v31
	s_nop 1
	v_cndmask_b32_e32 v7, 0, v7, vcc
	v_perm_b32 v7, v7, v23, s19
	v_cmp_gt_u32_e32 vcc, v31, v60
	ds_write_b64 v0, v[6:7] offset:96
	s_nop 0
	v_cndmask_b32_e32 v6, 0, v19, vcc
	v_cmp_le_u32_e32 vcc, v60, v31
	s_nop 1
	v_cndmask_b32_e32 v7, 0, v18, vcc
	v_cvt_pk_bf16_f32 v6, v7, v6
	v_mul_u32_u24_e32 v7, 0x110, v48
	v_add3_u32 v7, s15, v7, v33
	v_mul_u32_u24_e32 v18, 0x110, v35
	v_add3_u32 v18, s15, v18, v33
	ds_write_b16 v7, v9 offset:34816
	v_cvt_pk_bf16_f32 v7, v58, s0
	ds_write_b16 v18, v7 offset:34816
	v_cvt_pk_bf16_f32 v7, v20, v21
	v_cmp_le_u32_e32 vcc, v48, v31
	s_nop 1
	v_cndmask_b32_e32 v8, 0, v7, vcc
	v_lshrrev_b32_e32 v7, 16, v7
	v_cmp_le_u32_e32 vcc, v35, v31
	s_nop 1
	v_cndmask_b32_e32 v7, 0, v7, vcc
	v_perm_b32 v7, v7, v8, s19
	v_cmp_gt_u32_e32 vcc, v31, v29
	ds_write_b64 v0, v[6:7] offset:104
	v_mul_u32_u24_e32 v8, 0x110, v49
	v_cndmask_b32_e32 v6, 0, v37, vcc
	v_cmp_le_u32_e32 vcc, v29, v31
	v_add3_u32 v8, s15, v8, v33
	s_nop 0
	v_cndmask_b32_e32 v7, 0, v36, vcc
	v_cvt_pk_bf16_f32 v6, v7, v6
	v_mul_u32_u24_e32 v7, 0x110, v52
	v_add3_u32 v7, s15, v7, v33
	ds_write_b16 v7, v2 offset:34816
	v_cvt_pk_bf16_f32 v2, v65, s0
	ds_write_b16 v8, v2 offset:34816
	v_cvt_pk_bf16_f32 v2, v38, v39
	v_cmp_le_u32_e32 vcc, v52, v31
	s_nop 1
	v_cndmask_b32_e32 v3, 0, v2, vcc
	v_lshrrev_b32_e32 v2, 16, v2
	v_cmp_le_u32_e32 vcc, v49, v31
	s_nop 1
	v_cndmask_b32_e32 v2, 0, v2, vcc
	v_cmp_gt_u32_e32 vcc, v31, v28
	v_perm_b32 v7, v2, v3, s19
	ds_write_b64 v0, v[6:7] offset:112
	v_cndmask_b32_e32 v2, 0, v15, vcc
	v_cmp_le_u32_e32 vcc, v28, v31
	v_mul_u32_u24_e32 v6, 0x110, v10
	v_add3_u32 v6, s15, v6, v33
	v_cndmask_b32_e32 v3, 0, v14, vcc
	v_cvt_pk_bf16_f32 v2, v3, v2
	v_mul_u32_u24_e32 v3, 0x110, v11
	v_add3_u32 v3, s15, v3, v33
	ds_write_b16 v3, v5 offset:34816
	v_cvt_pk_bf16_f32 v3, v25, s0
	ds_write_b16 v6, v3 offset:34816
	v_cvt_pk_bf16_f32 v3, v16, v17
	v_cmp_le_u32_e32 vcc, v11, v31
	v_mul_u32_u24_e32 v7, 0x88, v81
	v_lshlrev_b32_e32 v81, 2, v81
	v_cndmask_b32_e32 v4, 0, v3, vcc
	v_lshrrev_b32_e32 v3, 16, v3
	v_cmp_le_u32_e32 vcc, v10, v31
	s_nop 1
	v_cndmask_b32_e32 v3, 0, v3, vcc
	v_perm_b32 v3, v3, v4, s19
	ds_write_b64 v0, v[2:3] offset:120
	v_bfe_u32 v0, v50, 4, 2
	v_and_b32_e32 v2, 0x4f, v50
	v_lshl_add_u32 v6, v0, 4, s15
	v_mul_u32_u24_e32 v2, 0x88, v2
	v_lshl_add_u32 v51, v2, 1, v6
	s_waitcnt lgkmcnt(0)
	s_barrier
	ds_read_b128 v[2:5], v51 offset:34816
	ds_read_b128 v[72:75], v51 offset:34880
	ds_read_b128 v[14:17], v51 offset:39168
	ds_read_b128 v[76:79], v51 offset:39232
	ds_read_b128 v[22:25], v51 offset:43520
	ds_read_b128 v[84:87], v51 offset:43584
	ds_read_b128 v[30:33], v51 offset:47872
	ds_read_b128 v[88:91], v51 offset:47936
	v_lshl_add_u32 v83, v7, 1, v6
	ds_read_b128 v[6:9], v83
	ds_read_b128 v[34:37], v83 offset:4352
	ds_read_b128 v[52:55], v83 offset:8704
	ds_read_b128 v[68:71], v83 offset:13056
	s_waitcnt lgkmcnt(3)
	v_mfma_f32_16x16x32_bf16 v[10:13], v[2:5], v[6:9], 0
	ds_read_b128 v[100:103], v51 offset:48000
	v_and_b32_e32 v50, 64, v50
	v_mfma_f32_16x16x32_bf16 v[18:21], v[14:17], v[6:9], 0
	v_mfma_f32_16x16x32_bf16 v[26:29], v[22:25], v[6:9], 0
	v_mfma_f32_16x16x32_bf16 v[6:9], v[30:33], v[6:9], 0
	s_waitcnt lgkmcnt(3)
	v_mfma_f32_16x16x32_bf16 v[38:41], v[2:5], v[34:37], 0
	v_mfma_f32_16x16x32_bf16 v[42:45], v[14:17], v[34:37], 0
	v_mfma_f32_16x16x32_bf16 v[46:49], v[22:25], v[34:37], 0
	v_mfma_f32_16x16x32_bf16 v[34:37], v[30:33], v[34:37], 0
	s_waitcnt lgkmcnt(2)
	v_mfma_f32_16x16x32_bf16 v[56:59], v[2:5], v[52:55], 0
	v_mfma_f32_16x16x32_bf16 v[60:63], v[14:17], v[52:55], 0
	v_mfma_f32_16x16x32_bf16 v[64:67], v[22:25], v[52:55], 0
	v_mfma_f32_16x16x32_bf16 v[52:55], v[30:33], v[52:55], 0
	s_waitcnt lgkmcnt(1)
	v_mfma_f32_16x16x32_bf16 v[2:5], v[2:5], v[68:71], 0
	v_mfma_f32_16x16x32_bf16 v[14:17], v[14:17], v[68:71], 0
	v_mfma_f32_16x16x32_bf16 v[22:25], v[22:25], v[68:71], 0
	v_mfma_f32_16x16x32_bf16 v[30:33], v[30:33], v[68:71], 0
	ds_read_b128 v[68:71], v83 offset:64
	s_waitcnt lgkmcnt(0)
	v_mfma_f32_16x16x32_bf16 v[10:13], v[72:75], v[68:71], v[10:13]
	v_mfma_f32_16x16x32_bf16 v[18:21], v[76:79], v[68:71], v[18:21]
	v_mfma_f32_16x16x32_bf16 v[26:29], v[84:87], v[68:71], v[26:29]
	v_mfma_f32_16x16x32_bf16 v[6:9], v[88:91], v[68:71], v[6:9]
	ds_read_b128 v[68:71], v83 offset:4416
	s_waitcnt lgkmcnt(0)
	v_mfma_f32_16x16x32_bf16 v[38:41], v[72:75], v[68:71], v[38:41]
	v_mfma_f32_16x16x32_bf16 v[42:45], v[76:79], v[68:71], v[42:45]
	v_mfma_f32_16x16x32_bf16 v[46:49], v[84:87], v[68:71], v[46:49]
	v_mfma_f32_16x16x32_bf16 v[34:37], v[88:91], v[68:71], v[34:37]
	ds_read_b128 v[68:71], v83 offset:8768
	s_waitcnt lgkmcnt(0)
	v_mfma_f32_16x16x32_bf16 v[92:95], v[76:79], v[68:71], v[60:63]
	s_nop 2
	ds_read_b128 v[60:63], v83 offset:13120
	v_mfma_f32_16x16x32_bf16 v[56:59], v[72:75], v[68:71], v[56:59]
	v_mfma_f32_16x16x32_bf16 v[96:99], v[84:87], v[68:71], v[64:67]
	v_mfma_f32_16x16x32_bf16 v[52:55], v[88:91], v[68:71], v[52:55]
	s_nop 1
	ds_read_b128 v[66:69], v51 offset:34944
	s_waitcnt lgkmcnt(1)
	v_mfma_f32_16x16x32_bf16 v[2:5], v[72:75], v[60:63], v[2:5]
	v_mfma_f32_16x16x32_bf16 v[70:73], v[88:91], v[60:63], v[30:33]
	s_nop 2
	ds_read_b128 v[30:33], v83 offset:128
	v_mfma_f32_16x16x32_bf16 v[14:17], v[76:79], v[60:63], v[14:17]
	s_waitcnt lgkmcnt(0)
	v_mfma_f32_16x16x32_bf16 v[74:77], v[66:69], v[30:33], v[10:13]
	s_nop 2
	ds_read_b128 v[10:13], v51 offset:39296
	v_mfma_f32_16x16x32_bf16 v[22:25], v[84:87], v[60:63], v[22:25]
	v_mfma_f32_16x16x32_bf16 v[104:107], v[100:103], v[30:33], v[6:9]
	s_nop 2
	ds_read_b128 v[6:9], v83 offset:4480
	s_waitcnt lgkmcnt(1)
	v_mfma_f32_16x16x32_bf16 v[84:87], v[10:13], v[30:33], v[18:21]
	s_nop 2
	ds_read_b128 v[18:21], v51 offset:43648
	s_waitcnt lgkmcnt(1)
	v_mfma_f32_16x16x32_bf16 v[108:111], v[66:69], v[6:9], v[38:41]
	v_mfma_f32_16x16x32_bf16 v[112:115], v[10:13], v[6:9], v[42:45]
	s_waitcnt lgkmcnt(0)
	v_mfma_f32_16x16x32_bf16 v[116:119], v[18:21], v[6:9], v[46:49]
	v_mfma_f32_16x16x32_bf16 v[62:65], v[100:103], v[6:9], v[34:37]
	ds_read_b128 v[6:9], v83 offset:8832
	s_waitcnt lgkmcnt(0)
	v_mfma_f32_16x16x32_bf16 v[42:45], v[100:103], v[6:9], v[52:55]
	s_nop 2
	ds_read_b128 v[52:55], v83 offset:13184
	v_mfma_f32_16x16x32_bf16 v[88:91], v[18:21], v[30:33], v[26:29]
	ds_read_b128 v[30:33], v51 offset:35008
	v_mfma_f32_16x16x32_bf16 v[46:49], v[18:21], v[6:9], v[96:99]
	s_waitcnt lgkmcnt(1)
	v_mfma_f32_16x16x32_bf16 v[26:29], v[66:69], v[52:55], v[2:5]
	v_mfma_f32_16x16x32_bf16 v[2:5], v[18:21], v[52:55], v[22:25]
	ds_read_b128 v[18:21], v51 offset:39360
	v_mfma_f32_16x16x32_bf16 v[38:41], v[66:69], v[6:9], v[56:59]
	v_mfma_f32_16x16x32_bf16 v[34:37], v[10:13], v[6:9], v[92:95]
	v_mfma_f32_16x16x32_bf16 v[6:9], v[10:13], v[52:55], v[14:17]
	v_mfma_f32_16x16x32_bf16 v[10:13], v[100:103], v[52:55], v[70:73]
	ds_read_b128 v[52:55], v83 offset:192
	ds_read_b128 v[22:25], v51 offset:43712
	ds_read_b128 v[14:17], v51 offset:48064
	v_lshlrev_b32_e32 v70, 3, v0
	v_lshlrev_b32_e32 v0, 1, v50
	v_lshl_add_u64 v[50:51], s[6:7], 0, v[0:1]
	v_mov_b32_e32 v71, v1
	s_waitcnt lgkmcnt(2)
	v_mfma_f32_16x16x32_bf16 v[92:95], v[30:33], v[52:55], v[74:77]
	ds_read_b128 v[100:103], v83 offset:4544
	s_nop 1
	v_lshl_add_u64 v[74:75], v[50:51], 0, v[70:71]
	v_mad_u64_u32 v[72:73], s[0:1], v82, s3, v[74:75]
	v_mfma_f32_16x16x32_bf16 v[96:99], v[18:21], v[52:55], v[84:87]
	s_lshl_b64 s[0:1], s[88:89], 2
	s_add_u32 s12, s42, s0
	s_addc_u32 s13, s43, s1
	s_waitcnt lgkmcnt(2)
	v_mfma_f32_16x16x32_bf16 v[86:89], v[22:25], v[52:55], v[88:91]
	global_load_dword v85, v81, s[12:13]
	v_or_b32_e32 v84, 16, v82
	v_mad_u64_u32 v[78:79], s[0:1], v84, s3, v[74:75]
	global_load_dwordx2 v[90:91], v[72:73], off
	s_waitcnt lgkmcnt(1)
	v_mfma_f32_16x16x32_bf16 v[66:69], v[14:17], v[52:55], v[104:107]
	s_cmpk_gt_u32 s10, 0xff
	s_waitcnt vmcnt(1)
	v_add_f32_e32 v87, v87, v85
	global_load_dwordx2 v[104:105], v[72:73], off offset:32
	s_waitcnt lgkmcnt(0)
	v_mfma_f32_16x16x32_bf16 v[58:61], v[30:33], v[100:103], v[108:111]
	global_load_dwordx2 v[106:107], v[72:73], off offset:64
	s_nop 1
	global_load_dwordx2 v[108:109], v[72:73], off offset:96
	s_waitcnt vmcnt(3)
	v_lshlrev_b32_e32 v72, 16, v90
	v_mul_f32_e32 v73, v72, v72
	v_and_b32_e32 v90, 0xffff0000, v90
	v_fmamk_f32 v73, v73, 0xbdd2d3e7, v129
	v_mul_f32_e32 v76, v90, v90
	v_mul_f32_e32 v73, v73, v72
	v_fmamk_f32 v76, v76, 0xbdd2d3e7, v129
	v_mul_f32_e32 v76, v76, v90
	v_exp_f32_e32 v73, v73
	v_exp_f32_e32 v110, v76
	v_add_f32_e32 v86, v86, v85
	v_add_f32_e32 v73, 1.0, v73
	v_rcp_f32_e32 v73, v73
	v_add_f32_e32 v110, 1.0, v110
	v_rcp_f32_e32 v110, v110
	v_add_f32_e32 v88, v88, v85
	v_mul_f32_e32 v72, v73, v72
	v_add_f32_e32 v73, v92, v85
	v_mul_f32_e32 v72, v72, v73
	v_mul_f32_e32 v73, v110, v90
	v_add_f32_e32 v90, v93, v85
	v_lshlrev_b32_e32 v92, 16, v91
	v_mul_f32_e32 v73, v73, v90
	v_mul_f32_e32 v90, v92, v92
	v_and_b32_e32 v91, 0xffff0000, v91
	v_fmamk_f32 v90, v90, 0xbdd2d3e7, v129
	v_mul_f32_e32 v93, v91, v91
	v_mul_f32_e32 v90, v90, v92
	v_fmamk_f32 v93, v93, 0xbdd2d3e7, v129
	v_mul_f32_e32 v93, v93, v91
	v_exp_f32_e32 v90, v90
	v_exp_f32_e32 v93, v93
	v_add_f32_e32 v89, v89, v85
	v_add_f32_e32 v90, 1.0, v90
	v_rcp_f32_e32 v110, v90
	v_cvt_pk_bf16_f32 v90, v72, v73
	v_add_f32_e32 v72, 1.0, v93
	v_rcp_f32_e32 v72, v72
	v_mul_f32_e32 v73, v110, v92
	v_add_f32_e32 v92, v94, v85
	v_mul_f32_e32 v73, v73, v92
	v_mul_f32_e32 v72, v72, v91
	v_add_f32_e32 v91, v95, v85
	v_mul_f32_e32 v72, v72, v91
	v_cvt_pk_bf16_f32 v91, v73, v72
	v_mov_b64_e32 v[72:73], s[50:51]
	v_mad_u64_u32 v[92:93], s[0:1], v82, s3, v[72:73]
	v_lshl_add_u64 v[92:93], v[92:93], 0, s[8:9]
	v_lshl_add_u64 v[92:93], v[92:93], 0, v[0:1]
	v_lshl_add_u64 v[92:93], v[92:93], 0, v[70:71]
	global_store_dwordx2 v[92:93], v[90:91], off
	v_add_f32_e32 v67, v67, v85
	v_add_f32_e32 v66, v66, v85
	global_load_dwordx2 v[76:77], v[78:79], off
	v_add_f32_e32 v68, v68, v85
	v_add_f32_e32 v69, v69, v85
	v_mfma_f32_16x16x32_bf16 v[54:57], v[18:21], v[100:103], v[112:115]
	s_waitcnt vmcnt(4)
	v_lshlrev_b32_e32 v94, 16, v104
	v_mul_f32_e32 v95, v94, v94
	v_and_b32_e32 v104, 0xffff0000, v104
	v_fmamk_f32 v95, v95, 0xbdd2d3e7, v129
	v_mul_f32_e32 v110, v104, v104
	v_mul_f32_e32 v95, v95, v94
	v_fmamk_f32 v110, v110, 0xbdd2d3e7, v129
	v_mul_f32_e32 v110, v110, v104
	v_exp_f32_e32 v95, v95
	v_exp_f32_e32 v110, v110
	v_mfma_f32_16x16x32_bf16 v[50:53], v[22:25], v[100:103], v[116:119]
	v_add_f32_e32 v95, 1.0, v95
	v_rcp_f32_e32 v95, v95
	v_add_f32_e32 v90, 1.0, v110
	v_rcp_f32_e32 v90, v90
	v_mfma_f32_16x16x32_bf16 v[62:65], v[14:17], v[100:103], v[62:65]
	v_mul_f32_e32 v91, v95, v94
	v_add_f32_e32 v94, v96, v85
	v_mul_f32_e32 v91, v91, v94
	v_mul_f32_e32 v90, v90, v104
	v_add_f32_e32 v94, v97, v85
	v_mul_f32_e32 v90, v90, v94
	v_lshlrev_b32_e32 v94, 16, v105
	v_mul_f32_e32 v95, v94, v94
	v_and_b32_e32 v96, 0xffff0000, v105
	v_fmamk_f32 v95, v95, 0xbdd2d3e7, v129
	v_mul_f32_e32 v97, v96, v96
	v_mul_f32_e32 v95, v95, v94
	v_fmamk_f32 v97, v97, 0xbdd2d3e7, v129
	v_mul_f32_e32 v97, v97, v96
	v_exp_f32_e32 v95, v95
	v_exp_f32_e32 v97, v97
	v_cvt_pk_bf16_f32 v90, v91, v90
	v_add_f32_e32 v95, 1.0, v95
	v_rcp_f32_e32 v95, v95
	v_add_f32_e32 v91, 1.0, v97
	v_rcp_f32_e32 v91, v91
	v_mul_f32_e32 v94, v95, v94
	v_add_f32_e32 v95, v98, v85
	v_mul_f32_e32 v94, v94, v95
	v_mul_f32_e32 v91, v91, v96
	v_add_f32_e32 v95, v99, v85
	v_mul_f32_e32 v91, v91, v95
	s_waitcnt vmcnt(3)
	v_and_b32_e32 v96, 0xffff0000, v106
	v_cvt_pk_bf16_f32 v91, v94, v91
	v_lshlrev_b32_e32 v94, 16, v106
	v_mul_f32_e32 v97, v96, v96
	v_mul_f32_e32 v95, v94, v94
	v_fmamk_f32 v97, v97, 0xbdd2d3e7, v129
	v_fmamk_f32 v95, v95, 0xbdd2d3e7, v129
	v_mul_f32_e32 v97, v97, v96
	v_mul_f32_e32 v95, v95, v94
	v_exp_f32_e32 v97, v97
	v_exp_f32_e32 v95, v95
	global_store_dwordx2 v[92:93], v[90:91], off offset:32
	v_add_f32_e32 v90, 1.0, v97
	v_add_f32_e32 v95, 1.0, v95
	v_rcp_f32_e32 v90, v90
	v_rcp_f32_e32 v95, v95
	v_mul_f32_e32 v90, v90, v96
	v_mul_f32_e32 v91, v95, v94
	v_mul_f32_e32 v87, v90, v87
	v_lshlrev_b32_e32 v90, 16, v107
	v_and_b32_e32 v94, 0xffff0000, v107
	v_mul_f32_e32 v86, v91, v86
	v_mul_f32_e32 v91, v90, v90
	v_mul_f32_e32 v95, v94, v94
	v_fmamk_f32 v91, v91, 0xbdd2d3e7, v129
	v_fmamk_f32 v95, v95, 0xbdd2d3e7, v129
	v_mul_f32_e32 v91, v91, v90
	v_mul_f32_e32 v95, v95, v94
	v_exp_f32_e32 v91, v91
	v_exp_f32_e32 v95, v95
	v_cvt_pk_bf16_f32 v86, v86, v87
	v_add_f32_e32 v91, 1.0, v91
	v_add_f32_e32 v87, 1.0, v95
	v_rcp_f32_e32 v91, v91
	v_rcp_f32_e32 v87, v87
	v_mul_f32_e32 v90, v91, v90
	v_mul_f32_e32 v87, v87, v94
	v_mul_f32_e32 v88, v90, v88
	v_mul_f32_e32 v87, v87, v89
	s_waitcnt vmcnt(3)
	v_and_b32_e32 v90, 0xffff0000, v108
	v_cvt_pk_bf16_f32 v87, v88, v87
	v_lshlrev_b32_e32 v88, 16, v108
	v_mul_f32_e32 v91, v90, v90
	v_mul_f32_e32 v89, v88, v88
	v_fmamk_f32 v91, v91, 0xbdd2d3e7, v129
	v_fmamk_f32 v89, v89, 0xbdd2d3e7, v129
	v_mul_f32_e32 v91, v91, v90
	v_mul_f32_e32 v89, v89, v88
	v_exp_f32_e32 v91, v91
	v_exp_f32_e32 v89, v89
	global_store_dwordx2 v[92:93], v[86:87], off offset:64
	v_add_f32_e32 v86, 1.0, v91
	v_add_f32_e32 v89, 1.0, v89
	v_rcp_f32_e32 v86, v86
	v_rcp_f32_e32 v89, v89
	v_mul_f32_e32 v86, v86, v90
	v_mul_f32_e32 v87, v89, v88
	v_mul_f32_e32 v67, v86, v67
	v_lshlrev_b32_e32 v86, 16, v109
	v_and_b32_e32 v88, 0xffff0000, v109
	v_mul_f32_e32 v66, v87, v66
	v_mul_f32_e32 v87, v86, v86
	v_mul_f32_e32 v89, v88, v88
	v_fmamk_f32 v87, v87, 0xbdd2d3e7, v129
	v_fmamk_f32 v89, v89, 0xbdd2d3e7, v129
	v_mul_f32_e32 v87, v87, v86
	v_mul_f32_e32 v89, v89, v88
	v_exp_f32_e32 v87, v87
	v_exp_f32_e32 v89, v89
	v_cvt_pk_bf16_f32 v66, v66, v67
	global_load_dwordx2 v[90:91], v[78:79], off offset:32
	v_add_f32_e32 v87, 1.0, v87
	v_add_f32_e32 v67, 1.0, v89
	v_rcp_f32_e32 v87, v87
	v_rcp_f32_e32 v67, v67
	v_mul_f32_e32 v86, v87, v86
	v_mul_f32_e32 v67, v67, v88
	v_mul_f32_e32 v68, v68, v86
	v_mul_f32_e32 v67, v69, v67
	v_cvt_pk_bf16_f32 v67, v68, v67
	global_store_dwordx2 v[92:93], v[66:67], off offset:96
	global_load_dword v85, v81, s[12:13] offset:64
	ds_read_b128 v[86:89], v83 offset:8896
	global_load_dwordx2 v[92:93], v[78:79], off offset:64
	global_load_dwordx2 v[94:95], v[78:79], off offset:96
	s_waitcnt vmcnt(7)
	v_lshlrev_b32_e32 v79, 16, v76
	v_and_b32_e32 v76, 0xffff0000, v76
	v_mul_f32_e32 v67, v76, v76
	v_mul_f32_e32 v66, v79, v79
	v_fmamk_f32 v67, v67, 0xbdd2d3e7, v129
	v_fmamk_f32 v66, v66, 0xbdd2d3e7, v129
	v_mul_f32_e32 v67, v67, v76
	v_mul_f32_e32 v66, v66, v79
	v_exp_f32_e32 v96, v67
	v_exp_f32_e32 v66, v66
	v_or_b32_e32 v78, 32, v82
	v_mad_u64_u32 v[68:69], s[0:1], v78, s3, v[74:75]
	v_add_f32_e32 v96, 1.0, v96
	v_add_f32_e32 v66, 1.0, v66
	v_rcp_f32_e32 v96, v96
	v_rcp_f32_e32 v97, v66
	global_load_dwordx2 v[66:67], v[68:69], off
	s_waitcnt lgkmcnt(0)
	v_mfma_f32_16x16x32_bf16 v[38:41], v[30:33], v[86:89], v[38:41]
	v_mul_f32_e32 v76, v96, v76
	v_mul_f32_e32 v79, v97, v79
	s_waitcnt vmcnt(3)
	v_add_f32_e32 v59, v59, v85
	v_add_f32_e32 v58, v58, v85
	v_mul_f32_e32 v59, v76, v59
	v_lshlrev_b32_e32 v76, 16, v77
	v_and_b32_e32 v77, 0xffff0000, v77
	v_mul_f32_e32 v58, v79, v58
	v_mul_f32_e32 v79, v76, v76
	v_mul_f32_e32 v96, v77, v77
	v_fmamk_f32 v79, v79, 0xbdd2d3e7, v129
	v_fmamk_f32 v96, v96, 0xbdd2d3e7, v129
	v_mul_f32_e32 v79, v79, v76
	v_mul_f32_e32 v96, v96, v77
	v_exp_f32_e32 v79, v79
	v_exp_f32_e32 v96, v96
	v_cvt_pk_bf16_f32 v58, v58, v59
	v_add_f32_e32 v60, v60, v85
	v_add_f32_e32 v79, 1.0, v79
	v_add_f32_e32 v59, 1.0, v96
	v_rcp_f32_e32 v79, v79
	v_rcp_f32_e32 v59, v59
	v_add_f32_e32 v61, v61, v85
	v_add_f32_e32 v55, v55, v85
	v_mul_f32_e32 v76, v79, v76
	v_mul_f32_e32 v59, v59, v77
	v_mul_f32_e32 v60, v76, v60
	v_mul_f32_e32 v59, v59, v61
	v_and_b32_e32 v79, 0xffff0000, v90
	v_cvt_pk_bf16_f32 v59, v60, v59
	v_mad_u64_u32 v[60:61], s[0:1], v84, s3, v[72:73]
	v_lshlrev_b32_e32 v76, 16, v90
	v_mul_f32_e32 v84, v79, v79
	v_mul_f32_e32 v77, v76, v76
	v_fmamk_f32 v84, v84, 0xbdd2d3e7, v129
	v_fmamk_f32 v77, v77, 0xbdd2d3e7, v129
	v_mul_f32_e32 v84, v84, v79
	v_mul_f32_e32 v77, v77, v76
	v_exp_f32_e32 v84, v84
	v_lshl_add_u64 v[60:61], v[60:61], 0, s[8:9]
	v_exp_f32_e32 v77, v77
	v_lshl_add_u64 v[60:61], v[60:61], 0, v[0:1]
	v_lshl_add_u64 v[60:61], v[60:61], 0, v[70:71]
	global_store_dwordx2 v[60:61], v[58:59], off
	v_add_f32_e32 v58, 1.0, v84
	v_add_f32_e32 v77, 1.0, v77
	v_rcp_f32_e32 v58, v58
	v_rcp_f32_e32 v77, v77
	v_add_f32_e32 v54, v54, v85
	v_add_f32_e32 v56, v56, v85
	v_mul_f32_e32 v58, v58, v79
	v_mul_f32_e32 v59, v77, v76
	v_mul_f32_e32 v55, v58, v55
	v_lshlrev_b32_e32 v58, 16, v91
	v_and_b32_e32 v76, 0xffff0000, v91
	v_mul_f32_e32 v54, v59, v54
	v_mul_f32_e32 v59, v58, v58
	v_mul_f32_e32 v77, v76, v76
	v_fmamk_f32 v59, v59, 0xbdd2d3e7, v129
	v_fmamk_f32 v77, v77, 0xbdd2d3e7, v129
	v_mul_f32_e32 v59, v59, v58
	v_mul_f32_e32 v77, v77, v76
	v_exp_f32_e32 v59, v59
	v_exp_f32_e32 v77, v77
	v_cvt_pk_bf16_f32 v54, v54, v55
	v_add_f32_e32 v57, v57, v85
	v_add_f32_e32 v59, 1.0, v59
	v_add_f32_e32 v55, 1.0, v77
	v_rcp_f32_e32 v59, v59
	v_rcp_f32_e32 v55, v55
	v_add_f32_e32 v51, v51, v85
	v_add_f32_e32 v50, v50, v85
	v_mul_f32_e32 v58, v59, v58
	v_mul_f32_e32 v55, v55, v76
	v_mul_f32_e32 v56, v58, v56
	v_mul_f32_e32 v55, v55, v57
	s_waitcnt vmcnt(3)
	v_and_b32_e32 v58, 0xffff0000, v92
	v_cvt_pk_bf16_f32 v55, v56, v55
	v_lshlrev_b32_e32 v56, 16, v92
	v_mul_f32_e32 v59, v58, v58
	v_mul_f32_e32 v57, v56, v56
	v_fmamk_f32 v59, v59, 0xbdd2d3e7, v129
	v_fmamk_f32 v57, v57, 0xbdd2d3e7, v129
	v_mul_f32_e32 v59, v59, v58
	v_mul_f32_e32 v57, v57, v56
	v_exp_f32_e32 v59, v59
	v_exp_f32_e32 v57, v57
	global_store_dwordx2 v[60:61], v[54:55], off offset:32
	v_add_f32_e32 v52, v52, v85
	v_add_f32_e32 v54, 1.0, v59
	v_add_f32_e32 v57, 1.0, v57
	v_rcp_f32_e32 v54, v54
	v_rcp_f32_e32 v57, v57
	v_add_f32_e32 v53, v53, v85
	v_mfma_f32_16x16x32_bf16 v[34:37], v[18:21], v[86:89], v[34:37]
	v_mul_f32_e32 v54, v54, v58
	v_mul_f32_e32 v55, v57, v56
	v_mul_f32_e32 v51, v54, v51
	v_lshlrev_b32_e32 v54, 16, v93
	v_and_b32_e32 v56, 0xffff0000, v93
	v_mul_f32_e32 v50, v55, v50
	v_mul_f32_e32 v55, v54, v54
	v_mul_f32_e32 v57, v56, v56
	v_fmamk_f32 v55, v55, 0xbdd2d3e7, v129
	v_fmamk_f32 v57, v57, 0xbdd2d3e7, v129
	v_mul_f32_e32 v55, v55, v54
	v_mul_f32_e32 v57, v57, v56
	v_exp_f32_e32 v55, v55
	v_exp_f32_e32 v57, v57
	v_cvt_pk_bf16_f32 v50, v50, v51
	v_mfma_f32_16x16x32_bf16 v[46:49], v[22:25], v[86:89], v[46:49]
	v_add_f32_e32 v55, 1.0, v55
	v_add_f32_e32 v51, 1.0, v57
	v_rcp_f32_e32 v55, v55
	v_rcp_f32_e32 v51, v51
	v_mfma_f32_16x16x32_bf16 v[42:45], v[14:17], v[86:89], v[42:45]
	v_or_b32_e32 v57, 48, v82
	v_mul_f32_e32 v54, v55, v54
	v_mul_f32_e32 v51, v51, v56
	v_mul_f32_e32 v52, v54, v52
	v_mul_f32_e32 v51, v51, v53
	v_cvt_pk_bf16_f32 v51, v52, v51
	s_waitcnt vmcnt(3)
	v_lshlrev_b32_e32 v52, 16, v94
	v_mul_f32_e32 v53, v52, v52
	v_and_b32_e32 v54, 0xffff0000, v94
	v_fmamk_f32 v53, v53, 0xbdd2d3e7, v129
	v_mul_f32_e32 v55, v54, v54
	v_mul_f32_e32 v53, v53, v52
	v_fmamk_f32 v55, v55, 0xbdd2d3e7, v129
	v_mul_f32_e32 v55, v55, v54
	v_exp_f32_e32 v53, v53
	v_exp_f32_e32 v55, v55
	global_store_dwordx2 v[60:61], v[50:51], off offset:64
	v_add_f32_e32 v53, 1.0, v53
	v_rcp_f32_e32 v53, v53
	v_add_f32_e32 v50, 1.0, v55
	v_rcp_f32_e32 v50, v50
	v_mul_f32_e32 v51, v53, v52
	v_add_f32_e32 v52, v62, v85
	v_mul_f32_e32 v51, v51, v52
	v_mul_f32_e32 v50, v50, v54
	v_add_f32_e32 v52, v63, v85
	v_mul_f32_e32 v50, v50, v52
	v_lshlrev_b32_e32 v52, 16, v95
	v_mul_f32_e32 v53, v52, v52
	v_and_b32_e32 v54, 0xffff0000, v95
	v_fmamk_f32 v53, v53, 0xbdd2d3e7, v129
	v_mul_f32_e32 v55, v54, v54
	v_mul_f32_e32 v53, v53, v52
	v_fmamk_f32 v55, v55, 0xbdd2d3e7, v129
	v_mul_f32_e32 v55, v55, v54
	v_exp_f32_e32 v53, v53
	v_exp_f32_e32 v55, v55
	v_cvt_pk_bf16_f32 v50, v51, v50
	v_add_f32_e32 v53, 1.0, v53
	v_rcp_f32_e32 v53, v53
	v_add_f32_e32 v51, 1.0, v55
	v_rcp_f32_e32 v51, v51
	v_mul_f32_e32 v52, v53, v52
	v_add_f32_e32 v53, v64, v85
	v_mul_f32_e32 v52, v52, v53
	v_mul_f32_e32 v51, v51, v54
	v_add_f32_e32 v53, v65, v85
	v_mul_f32_e32 v51, v51, v53
	v_cvt_pk_bf16_f32 v51, v52, v51
	global_store_dwordx2 v[60:61], v[50:51], off offset:96
	global_load_dword v56, v81, s[12:13] offset:128
	global_load_dwordx2 v[54:55], v[68:69], off offset:32
	ds_read_b128 v[50:53], v83 offset:13248
	global_load_dwordx2 v[58:59], v[68:69], off offset:64
	global_load_dwordx2 v[60:61], v[68:69], off offset:96
	s_waitcnt vmcnt(8)
	v_lshlrev_b32_e32 v62, 16, v66
	s_waitcnt lgkmcnt(0)
	v_mfma_f32_16x16x32_bf16 v[26:29], v[30:33], v[50:53], v[26:29]
	v_mul_f32_e32 v30, v62, v62
	v_and_b32_e32 v63, 0xffff0000, v66
	v_fmamk_f32 v30, v30, 0xbdd2d3e7, v129
	v_mul_f32_e32 v31, v63, v63
	v_mul_f32_e32 v30, v30, v62
	v_fmamk_f32 v31, v31, 0xbdd2d3e7, v129
	v_mul_f32_e32 v31, v31, v63
	v_exp_f32_e32 v30, v30
	v_exp_f32_e32 v64, v31
	v_mad_u64_u32 v[32:33], s[0:1], v57, s3, v[74:75]
	v_add_f32_e32 v30, 1.0, v30
	v_rcp_f32_e32 v65, v30
	v_add_f32_e32 v64, 1.0, v64
	v_rcp_f32_e32 v64, v64
	global_load_dwordx2 v[30:31], v[32:33], off
	v_mul_f32_e32 v62, v65, v62
	v_mfma_f32_16x16x32_bf16 v[6:9], v[18:21], v[50:53], v[6:9]
	global_load_dwordx2 v[18:19], v[32:33], off offset:32
	s_waitcnt vmcnt(5)
	v_add_f32_e32 v38, v38, v56
	v_mul_f32_e32 v38, v62, v38
	v_mul_f32_e32 v62, v64, v63
	v_add_f32_e32 v39, v39, v56
	v_mul_f32_e32 v39, v62, v39
	v_lshlrev_b32_e32 v62, 16, v67
	v_mul_f32_e32 v63, v62, v62
	v_fmamk_f32 v63, v63, 0xbdd2d3e7, v129
	v_and_b32_e32 v64, 0xffff0000, v67
	v_mul_f32_e32 v63, v63, v62
	v_mul_f32_e32 v65, v64, v64
	v_fmamk_f32 v65, v65, 0xbdd2d3e7, v129
	v_mul_f32_e32 v65, v65, v64
	v_exp_f32_e32 v63, v63
	v_exp_f32_e32 v65, v65
	v_add_f32_e32 v63, 1.0, v63
	v_rcp_f32_e32 v63, v63
	v_cvt_pk_bf16_f32 v38, v38, v39
	v_add_f32_e32 v39, 1.0, v65
	v_rcp_f32_e32 v39, v39
	v_mul_f32_e32 v62, v63, v62
	v_add_f32_e32 v40, v40, v56
	v_mul_f32_e32 v40, v62, v40
	s_waitcnt vmcnt(4)
	v_lshlrev_b32_e32 v62, 16, v54
	v_and_b32_e32 v54, 0xffff0000, v54
	v_mul_f32_e32 v39, v39, v64
	v_mul_f32_e32 v64, v54, v54
	v_mul_f32_e32 v63, v62, v62
	v_fmamk_f32 v64, v64, 0xbdd2d3e7, v129
	v_fmamk_f32 v63, v63, 0xbdd2d3e7, v129
	v_mul_f32_e32 v64, v64, v54
	v_add_f32_e32 v41, v41, v56
	v_mul_f32_e32 v63, v63, v62
	v_mul_f32_e32 v39, v39, v41
	v_cvt_pk_bf16_f32 v39, v40, v39
	v_mad_u64_u32 v[40:41], s[0:1], v78, s3, v[72:73]
	v_exp_f32_e32 v64, v64
	v_lshl_add_u64 v[40:41], v[40:41], 0, s[8:9]
	v_exp_f32_e32 v63, v63
	v_lshl_add_u64 v[40:41], v[40:41], 0, v[0:1]
	v_lshl_add_u64 v[40:41], v[40:41], 0, v[70:71]
	global_store_dwordx2 v[40:41], v[38:39], off
	v_add_f32_e32 v38, 1.0, v64
	v_add_f32_e32 v63, 1.0, v63
	v_rcp_f32_e32 v38, v38
	v_rcp_f32_e32 v63, v63
	v_add_f32_e32 v35, v35, v56
	v_add_f32_e32 v34, v34, v56
	v_mul_f32_e32 v38, v38, v54
	v_mul_f32_e32 v39, v63, v62
	v_mul_f32_e32 v35, v38, v35
	v_lshlrev_b32_e32 v38, 16, v55
	v_and_b32_e32 v54, 0xffff0000, v55
	v_mul_f32_e32 v34, v39, v34
	v_mul_f32_e32 v39, v38, v38
	v_mul_f32_e32 v55, v54, v54
	v_fmamk_f32 v39, v39, 0xbdd2d3e7, v129
	v_fmamk_f32 v55, v55, 0xbdd2d3e7, v129
	v_mul_f32_e32 v39, v39, v38
	v_mul_f32_e32 v55, v55, v54
	v_exp_f32_e32 v39, v39
	v_exp_f32_e32 v55, v55
	v_cvt_pk_bf16_f32 v34, v34, v35
	v_add_f32_e32 v36, v36, v56
	v_add_f32_e32 v39, 1.0, v39
	v_add_f32_e32 v35, 1.0, v55
	v_rcp_f32_e32 v39, v39
	v_rcp_f32_e32 v35, v35
	v_add_f32_e32 v37, v37, v56
	v_mfma_f32_16x16x32_bf16 v[2:5], v[22:25], v[50:53], v[2:5]
	v_mul_f32_e32 v38, v39, v38
	v_mul_f32_e32 v35, v35, v54
	v_mul_f32_e32 v36, v38, v36
	v_mul_f32_e32 v35, v35, v37
	v_cvt_pk_bf16_f32 v35, v36, v35
	s_waitcnt vmcnt(4)
	v_lshlrev_b32_e32 v36, 16, v58
	v_mul_f32_e32 v37, v36, v36
	v_and_b32_e32 v38, 0xffff0000, v58
	v_fmamk_f32 v37, v37, 0xbdd2d3e7, v129
	v_mul_f32_e32 v39, v38, v38
	v_mul_f32_e32 v37, v37, v36
	v_fmamk_f32 v39, v39, 0xbdd2d3e7, v129
	v_mul_f32_e32 v39, v39, v38
	v_exp_f32_e32 v37, v37
	v_exp_f32_e32 v39, v39
	global_store_dwordx2 v[40:41], v[34:35], off offset:32
	v_add_f32_e32 v37, 1.0, v37
	v_rcp_f32_e32 v37, v37
	v_add_f32_e32 v34, 1.0, v39
	v_rcp_f32_e32 v34, v34
	s_waitcnt vmcnt(3)
	v_lshlrev_b32_e32 v24, 16, v30
	v_mul_f32_e32 v35, v37, v36
	v_add_f32_e32 v36, v46, v56
	v_mul_f32_e32 v35, v35, v36
	v_mul_f32_e32 v34, v34, v38
	v_add_f32_e32 v36, v47, v56
	v_mul_f32_e32 v34, v34, v36
	v_lshlrev_b32_e32 v36, 16, v59
	v_mul_f32_e32 v37, v36, v36
	v_and_b32_e32 v38, 0xffff0000, v59
	v_fmamk_f32 v37, v37, 0xbdd2d3e7, v129
	v_mul_f32_e32 v39, v38, v38
	v_mul_f32_e32 v37, v37, v36
	v_fmamk_f32 v39, v39, 0xbdd2d3e7, v129
	v_mul_f32_e32 v39, v39, v38
	v_exp_f32_e32 v37, v37
	v_exp_f32_e32 v39, v39
	v_cvt_pk_bf16_f32 v34, v35, v34
	v_add_f32_e32 v37, 1.0, v37
	v_rcp_f32_e32 v37, v37
	v_add_f32_e32 v35, 1.0, v39
	v_rcp_f32_e32 v35, v35
	v_mul_f32_e32 v25, 0x3d372713, v24
	v_mul_f32_e32 v36, v37, v36
	v_add_f32_e32 v37, v48, v56
	v_mul_f32_e32 v36, v36, v37
	v_mul_f32_e32 v35, v35, v38
	v_add_f32_e32 v37, v49, v56
	v_mul_f32_e32 v35, v35, v37
	v_cvt_pk_bf16_f32 v35, v36, v35
	v_lshlrev_b32_e32 v36, 16, v60
	v_mul_f32_e32 v37, v36, v36
	v_and_b32_e32 v38, 0xffff0000, v60
	v_fmamk_f32 v37, v37, 0xbdd2d3e7, v129
	v_mul_f32_e32 v39, v38, v38
	v_mul_f32_e32 v37, v37, v36
	v_fmamk_f32 v39, v39, 0xbdd2d3e7, v129
	v_mul_f32_e32 v39, v39, v38
	v_exp_f32_e32 v37, v37
	v_exp_f32_e32 v39, v39
	global_store_dwordx2 v[40:41], v[34:35], off offset:64
	v_add_f32_e32 v37, 1.0, v37
	v_rcp_f32_e32 v37, v37
	v_add_f32_e32 v34, 1.0, v39
	v_rcp_f32_e32 v34, v34
	v_and_b32_e32 v30, 0xffff0000, v30
	v_mul_f32_e32 v35, v37, v36
	v_add_f32_e32 v36, v42, v56
	v_mul_f32_e32 v35, v35, v36
	v_mul_f32_e32 v34, v34, v38
	v_add_f32_e32 v36, v43, v56
	v_mul_f32_e32 v34, v34, v36
	v_lshlrev_b32_e32 v36, 16, v61
	v_mul_f32_e32 v37, v36, v36
	v_and_b32_e32 v38, 0xffff0000, v61
	v_fmamk_f32 v37, v37, 0xbdd2d3e7, v129
	v_mul_f32_e32 v39, v38, v38
	v_mul_f32_e32 v37, v37, v36
	v_fmamk_f32 v39, v39, 0xbdd2d3e7, v129
	v_mul_f32_e32 v39, v39, v38
	v_exp_f32_e32 v37, v37
	v_exp_f32_e32 v39, v39
	v_cvt_pk_bf16_f32 v34, v35, v34
	v_add_f32_e32 v37, 1.0, v37
	v_rcp_f32_e32 v37, v37
	v_add_f32_e32 v35, 1.0, v39
	v_rcp_f32_e32 v35, v35
	v_mul_f32_e32 v25, v25, v24
	v_mul_f32_e32 v36, v37, v36
	v_add_f32_e32 v37, v44, v56
	v_mul_f32_e32 v36, v36, v37
	v_mul_f32_e32 v35, v35, v38
	v_add_f32_e32 v37, v45, v56
	v_mul_f32_e32 v35, v35, v37
	v_cvt_pk_bf16_f32 v35, v36, v35
	global_store_dwordx2 v[40:41], v[34:35], off offset:96
	global_load_dword v34, v81, s[12:13] offset:192
	s_nop 0
	global_load_dwordx2 v[20:21], v[32:33], off offset:64
	global_load_dwordx2 v[22:23], v[32:33], off offset:96
	v_mul_f32_e32 v32, v30, v30
	v_fma_f32 v25, v25, v24, v24
	v_fmamk_f32 v32, v32, 0xbdd2d3e7, v129
	v_mul_f32_e32 v25, 0xbfcc422a, v25
	v_mul_f32_e32 v32, v32, v30
	v_mul_f32_e32 v25, 0x3fb8aa3b, v25
	v_exp_f32_e32 v25, v25
	v_exp_f32_e32 v32, v32
	v_mfma_f32_16x16x32_bf16 v[10:13], v[14:17], v[50:53], v[10:13]
	v_add_f32_e32 v25, 1.0, v25
	v_rcp_f32_e32 v25, v25
	v_add_f32_e32 v14, 1.0, v32
	v_rcp_f32_e32 v14, v14
	v_mul_f32_e32 v15, v25, v24
	v_and_b32_e32 v24, 0xffff0000, v31
	v_mul_f32_e32 v14, v14, v30
	v_mul_f32_e32 v25, v24, v24
	v_fmamk_f32 v25, v25, 0xbdd2d3e7, v129
	v_mul_f32_e32 v25, v25, v24
	v_exp_f32_e32 v25, v25
	s_waitcnt vmcnt(2)
	v_add_f32_e32 v16, v26, v34
	v_mul_f32_e32 v15, v15, v16
	v_add_f32_e32 v16, v27, v34
	v_mul_f32_e32 v14, v14, v16
	v_lshlrev_b32_e32 v16, 16, v31
	v_mul_f32_e32 v17, v16, v16
	v_fmamk_f32 v17, v17, 0xbdd2d3e7, v129
	v_mul_f32_e32 v17, v17, v16
	v_exp_f32_e32 v17, v17
	v_cvt_pk_bf16_f32 v14, v15, v14
	v_add_f32_e32 v15, 1.0, v25
	v_rcp_f32_e32 v15, v15
	v_add_f32_e32 v17, 1.0, v17
	v_rcp_f32_e32 v17, v17
	v_add_f32_e32 v6, v6, v34
	v_mul_f32_e32 v15, v15, v24
	v_add_f32_e32 v7, v7, v34
	v_mul_f32_e32 v16, v17, v16
	v_add_f32_e32 v17, v28, v34
	v_mul_f32_e32 v16, v16, v17
	v_add_f32_e32 v17, v29, v34
	v_mul_f32_e32 v15, v15, v17
	v_cvt_pk_bf16_f32 v15, v16, v15
	v_mad_u64_u32 v[16:17], s[0:1], v57, s3, v[72:73]
	v_lshl_add_u64 v[16:17], v[16:17], 0, s[8:9]
	v_lshl_add_u64 v[16:17], v[16:17], 0, v[0:1]
	v_lshlrev_b32_e32 v0, 16, v18
	v_mul_f32_e32 v24, v0, v0
	v_and_b32_e32 v18, 0xffff0000, v18
	v_fmamk_f32 v24, v24, 0xbdd2d3e7, v129
	v_mul_f32_e32 v25, v18, v18
	v_mul_f32_e32 v24, v24, v0
	v_fmamk_f32 v25, v25, 0xbdd2d3e7, v129
	v_mul_f32_e32 v25, v25, v18
	v_exp_f32_e32 v24, v24
	v_exp_f32_e32 v25, v25
	v_lshl_add_u64 v[16:17], v[16:17], 0, v[70:71]
	v_add_f32_e32 v24, 1.0, v24
	v_rcp_f32_e32 v24, v24
	global_store_dwordx2 v[16:17], v[14:15], off
	v_add_f32_e32 v14, 1.0, v25
	v_rcp_f32_e32 v14, v14
	v_mul_f32_e32 v0, v24, v0
	v_mul_f32_e32 v0, v0, v6
	v_and_b32_e32 v15, 0xffff0000, v19
	v_mul_f32_e32 v6, v14, v18
	v_mul_f32_e32 v6, v6, v7
	v_lshlrev_b32_e32 v7, 16, v19
	v_mul_f32_e32 v14, v7, v7
	v_fmamk_f32 v14, v14, 0xbdd2d3e7, v129
	v_mul_f32_e32 v18, v15, v15
	v_mul_f32_e32 v14, v14, v7
	v_fmamk_f32 v18, v18, 0xbdd2d3e7, v129
	v_mul_f32_e32 v18, v18, v15
	v_exp_f32_e32 v14, v14
	v_exp_f32_e32 v18, v18
	v_cvt_pk_bf16_f32 v6, v0, v6
	v_add_f32_e32 v14, 1.0, v14
	v_rcp_f32_e32 v14, v14
	v_add_f32_e32 v0, 1.0, v18
	v_rcp_f32_e32 v0, v0
	v_add_f32_e32 v8, v8, v34
	v_mul_f32_e32 v7, v14, v7
	v_mul_f32_e32 v7, v7, v8
	v_mul_f32_e32 v0, v0, v15
	v_add_f32_e32 v8, v9, v34
	v_mul_f32_e32 v0, v0, v8
	v_cvt_pk_bf16_f32 v7, v7, v0
	s_waitcnt vmcnt(2)
	v_lshlrev_b32_e32 v0, 16, v20
	v_mul_f32_e32 v8, v0, v0
	v_and_b32_e32 v9, 0xffff0000, v20
	v_fmamk_f32 v8, v8, 0xbdd2d3e7, v129
	v_mul_f32_e32 v14, v9, v9
	v_mul_f32_e32 v8, v8, v0
	v_fmamk_f32 v14, v14, 0xbdd2d3e7, v129
	v_mul_f32_e32 v14, v14, v9
	v_exp_f32_e32 v8, v8
	v_exp_f32_e32 v14, v14
	global_store_dwordx2 v[16:17], v[6:7], off offset:32
	v_add_f32_e32 v8, 1.0, v8
	v_rcp_f32_e32 v8, v8
	v_add_f32_e32 v6, 1.0, v14
	v_rcp_f32_e32 v6, v6
	v_add_f32_e32 v2, v2, v34
	v_mul_f32_e32 v0, v8, v0
	v_mul_f32_e32 v0, v0, v2
	v_mul_f32_e32 v2, v6, v9
	v_add_f32_e32 v3, v3, v34
	v_mul_f32_e32 v2, v2, v3
	v_lshlrev_b32_e32 v3, 16, v21
	v_mul_f32_e32 v6, v3, v3
	v_and_b32_e32 v7, 0xffff0000, v21
	v_fmamk_f32 v6, v6, 0xbdd2d3e7, v129
	v_mul_f32_e32 v8, v7, v7
	v_mul_f32_e32 v6, v6, v3
	v_fmamk_f32 v8, v8, 0xbdd2d3e7, v129
	v_mul_f32_e32 v8, v8, v7
	v_exp_f32_e32 v6, v6
	v_exp_f32_e32 v8, v8
	v_cvt_pk_bf16_f32 v2, v0, v2
	v_add_f32_e32 v6, 1.0, v6
	v_rcp_f32_e32 v6, v6
	v_add_f32_e32 v0, 1.0, v8
	v_rcp_f32_e32 v0, v0
	v_add_f32_e32 v4, v4, v34
	v_mul_f32_e32 v3, v6, v3
	v_mul_f32_e32 v3, v3, v4
	v_mul_f32_e32 v0, v0, v7
	v_add_f32_e32 v4, v5, v34
	v_mul_f32_e32 v0, v0, v4
	v_cvt_pk_bf16_f32 v3, v3, v0
	s_waitcnt vmcnt(2)
	v_lshlrev_b32_e32 v0, 16, v22
	v_mul_f32_e32 v4, v0, v0
	v_and_b32_e32 v5, 0xffff0000, v22
	v_fmamk_f32 v4, v4, 0xbdd2d3e7, v129
	v_mul_f32_e32 v6, v5, v5
	v_mul_f32_e32 v4, v4, v0
	v_fmamk_f32 v6, v6, 0xbdd2d3e7, v129
	v_mul_f32_e32 v6, v6, v5
	v_exp_f32_e32 v4, v4
	v_exp_f32_e32 v6, v6
	global_store_dwordx2 v[16:17], v[2:3], off offset:64
	v_add_f32_e32 v4, 1.0, v4
	v_rcp_f32_e32 v4, v4
	v_add_f32_e32 v2, 1.0, v6
	v_rcp_f32_e32 v2, v2
	v_add_f32_e32 v3, v10, v34
	v_mul_f32_e32 v0, v4, v0
	v_mul_f32_e32 v0, v0, v3
	v_mul_f32_e32 v2, v2, v5
	v_add_f32_e32 v3, v11, v34
	v_mul_f32_e32 v2, v2, v3
	v_lshlrev_b32_e32 v3, 16, v23
	v_mul_f32_e32 v4, v3, v3
	v_and_b32_e32 v5, 0xffff0000, v23
	v_fmamk_f32 v4, v4, 0xbdd2d3e7, v129
	v_mul_f32_e32 v6, v5, v5
	v_mul_f32_e32 v4, v4, v3
	v_fmamk_f32 v6, v6, 0xbdd2d3e7, v129
	v_mul_f32_e32 v6, v6, v5
	v_exp_f32_e32 v4, v4
	v_exp_f32_e32 v6, v6
	v_cvt_pk_bf16_f32 v2, v0, v2
	v_add_f32_e32 v4, 1.0, v4
	v_rcp_f32_e32 v4, v4
	v_add_f32_e32 v0, 1.0, v6
	v_rcp_f32_e32 v0, v0
	v_mul_f32_e32 v3, v4, v3
	v_add_f32_e32 v4, v12, v34
	v_mul_f32_e32 v3, v3, v4
	v_mul_f32_e32 v0, v0, v5
	v_add_f32_e32 v4, v13, v34
	v_mul_f32_e32 v0, v0, v4
	v_cvt_pk_bf16_f32 v3, v3, v0
	global_store_dwordx2 v[16:17], v[2:3], off offset:96
	s_barrier
	s_cbranch_scc0 .LBB0_626
	s_and_b32 s0, s10, 3
	s_lshl_b32 s1, s10, 5
	v_mov_b32_e32 v38, v194
	v_cvt_f32_ubyte0_e32 v0, s0
	s_and_b32 s1, s1, 0x7fffff80
	v_sub_f32_e32 v37, 0xc0a00000, v0
	v_bfe_u32 v36, v38, 1, 7
	s_mov_b32 s2, 0xc2fc0000
	v_cmp_gt_f32_e32 vcc, s2, v37
	v_or_b32_e32 v0, s1, v36
	v_mov_b64_e32 v[2:3], s[50:51]
	s_and_b64 s[4:5], vcc, exec
	v_mad_u64_u32 v[34:35], s[4:5], v0, s3, v[2:3]
	v_and_b32_e32 v40, 1, v38
	s_cselect_b32 s2, 0xffffffc0, 0
	s_lshl_b32 s4, s0, 8
	s_mov_b32 s5, s89
	v_lshl_add_u64 v[2:3], v[34:35], 0, s[4:5]
	v_lshlrev_b32_e32 v4, 7, v40
	v_mov_b32_e32 v5, v1
	v_lshl_add_u64 v[2:3], v[2:3], 0, v[4:5]
	global_load_dwordx4 v[30:33], v[2:3], off offset:3072
	global_load_dwordx4 v[26:29], v[2:3], off offset:3088
	global_load_dwordx4 v[22:25], v[2:3], off offset:3104
	global_load_dwordx4 v[18:21], v[2:3], off offset:3120
	global_load_dwordx4 v[14:17], v[2:3], off offset:3136
	global_load_dwordx4 v[10:13], v[2:3], off offset:3152
	global_load_dwordx4 v[6:9], v[2:3], off offset:3168
	s_nop 0
	global_load_dwordx4 v[2:5], v[2:3], off offset:3184
	s_mov_b32 s1, s89
	s_lshl_b32 s0, s0, 7
	v_lshlrev_b32_e32 v0, 6, v40
	v_mul_u32_u24_e32 v41, 0x2200, v40
	v_cndmask_b32_e32 v42, 0, v248, vcc
	v_lshl_add_u64 v[34:35], v[34:35], 0, s[0:1]
	v_lshlrev_b32_e32 v36, 1, v36
	v_lshlrev_b32_e32 v41, 1, v41
	v_add_f32_e32 v37, v37, v42
	v_lshl_add_u64 v[42:43], v[34:35], 0, v[0:1]
	v_add3_u32 v44, s15, v41, v36
	v_add3_u32 v41, s15, v36, v41
	v_exp_f32_e32 v45, v37
	global_load_dwordx4 v[34:37], v[42:43], off offset:2560
	v_lshrrev_b32_e32 v39, 1, v38
	v_and_b32_e32 v55, 0x60, v39
	v_ldexp_f32 v0, v45, s2
	v_sub_f32_e32 v0, 1.0, v0
	v_cmp_gt_f32_e32 vcc, s11, v0
	s_and_b64 s[0:1], vcc, exec
	s_cselect_b32 s0, 32, 0
	v_ldexp_f32 v0, v0, s0
	v_log_f32_e32 v0, v0
	s_mov_b32 s0, 0x3f317217
	v_bfe_u32 v54, v38, 4, 2
	s_mov_b32 s11, s89
	s_mul_i32 s2, s10, 3
	s_movk_i32 s39, 0xd80
	s_mov_b32 s69, 0x800000
	s_waitcnt vmcnt(8)
	ds_write_b16 v44, v30
	ds_write_b16_d16_hi v41, v30 offset:272
	ds_write_b16 v44, v31 offset:544
	ds_write_b16_d16_hi v41, v31 offset:816
	ds_write_b16 v44, v32 offset:1088
	ds_write_b16_d16_hi v41, v32 offset:1360
	ds_write_b16 v44, v33 offset:1632
	ds_write_b16_d16_hi v41, v33 offset:1904
	s_waitcnt vmcnt(7)
	ds_write_b16 v44, v26 offset:2176
	ds_write_b16_d16_hi v41, v26 offset:2448
	ds_write_b16 v44, v27 offset:2720
	ds_write_b16_d16_hi v41, v27 offset:2992
	ds_write_b16 v44, v28 offset:3264
	ds_write_b16_d16_hi v41, v28 offset:3536
	ds_write_b16 v44, v29 offset:3808
	ds_write_b16_d16_hi v41, v29 offset:4080
	s_waitcnt vmcnt(6)
	ds_write_b16 v44, v22 offset:4352
	ds_write_b16_d16_hi v41, v22 offset:4624
	ds_write_b16 v44, v23 offset:4896
	ds_write_b16_d16_hi v41, v23 offset:5168
	ds_write_b16 v44, v24 offset:5440
	ds_write_b16_d16_hi v41, v24 offset:5712
	ds_write_b16 v44, v25 offset:5984
	ds_write_b16_d16_hi v41, v25 offset:6256
	s_waitcnt vmcnt(5)
	ds_write_b16 v44, v18 offset:6528
	ds_write_b16_d16_hi v41, v18 offset:6800
	ds_write_b16 v44, v19 offset:7072
	ds_write_b16_d16_hi v41, v19 offset:7344
	ds_write_b16 v44, v20 offset:7616
	ds_write_b16_d16_hi v41, v20 offset:7888
	ds_write_b16 v44, v21 offset:8160
	ds_write_b16_d16_hi v41, v21 offset:8432
	s_waitcnt vmcnt(4)
	ds_write_b16 v44, v14 offset:8704
	ds_write_b16_d16_hi v41, v14 offset:8976
	ds_write_b16 v44, v15 offset:9248
	ds_write_b16_d16_hi v41, v15 offset:9520
	ds_write_b16 v44, v16 offset:9792
	ds_write_b16_d16_hi v41, v16 offset:10064
	ds_write_b16 v44, v17 offset:10336
	ds_write_b16_d16_hi v41, v17 offset:10608
	s_waitcnt vmcnt(3)
	ds_write_b16 v44, v10 offset:10880
	ds_write_b16_d16_hi v41, v10 offset:11152
	ds_write_b16 v44, v11 offset:11424
	ds_write_b16_d16_hi v41, v11 offset:11696
	ds_write_b16 v44, v12 offset:11968
	ds_write_b16_d16_hi v41, v12 offset:12240
	ds_write_b16 v44, v13 offset:12512
	ds_write_b16_d16_hi v41, v13 offset:12784
	s_waitcnt vmcnt(2)
	ds_write_b16 v44, v6 offset:13056
	ds_write_b16_d16_hi v41, v6 offset:13328
	ds_write_b16 v44, v7 offset:13600
	ds_write_b16_d16_hi v41, v7 offset:13872
	global_load_dwordx4 v[10:13], v[42:43], off offset:2576
	ds_write_b16 v44, v8 offset:14144
	ds_write_b16_d16_hi v41, v8 offset:14416
	ds_write_b16 v44, v9 offset:14688
	ds_write_b16_d16_hi v41, v9 offset:14960
	s_waitcnt vmcnt(2)
	ds_write_b16 v44, v2 offset:15232
	ds_write_b16_d16_hi v41, v2 offset:15504
	ds_write_b16 v44, v3 offset:15776
	ds_write_b16_d16_hi v41, v3 offset:16048
	ds_write_b16 v44, v4 offset:16320
	ds_write_b16_d16_hi v41, v4 offset:16592
	global_load_dwordx4 v[6:9], v[42:43], off offset:2592
	v_mul_f32_e32 v2, 0x3f317217, v0
	v_fma_f32 v2, v0, s0, -v2
	v_fmac_f32_e32 v2, 0x3377d1cf, v0
	s_mov_b32 s0, 0x7f800000
	v_fmac_f32_e32 v2, 0x3f317217, v0
	v_cmp_lt_f32_e64 s[0:1], |v0|, s0
	ds_write_b16 v44, v5 offset:16864
	ds_write_b16_d16_hi v41, v5 offset:17136
	v_cndmask_b32_e64 v0, v0, v2, s[0:1]
	v_cndmask_b32_e32 v2, 0, v231, vcc
	s_movk_i32 s0, 0x7f
	v_sub_f32_e32 v0, v0, v2
	v_bitop3_b32 v2, v39, s0, v39 bitop3:0xc
	v_cvt_f32_ubyte0_e32 v2, v2
	v_mul_f32_e32 v2, v0, v2
	v_mul_f32_e32 v0, 0x3fb8aa3b, v2
	s_mov_b32 s0, 0x3fb8aa3b
	v_fma_f32 v3, v2, s0, -v0
	v_rndne_f32_e32 v4, v0
	v_fmac_f32_e32 v3, 0x32a5705f, v2
	v_sub_f32_e32 v0, v0, v4
	v_add_f32_e32 v0, v0, v3
	v_exp_f32_e32 v3, v0
	v_cvt_i32_f32_e32 v4, v4
	s_mov_b32 s0, 0xc2ce8ed0
	v_cmp_ngt_f32_e32 vcc, s0, v2
	s_mov_b32 s0, 0x42b17218
	v_ldexp_f32 v3, v3, v4
	v_cndmask_b32_e32 v3, 0, v3, vcc
	v_cmp_nlt_f32_e32 vcc, s0, v2
	s_waitcnt vmcnt(2)
	v_lshlrev_b32_e32 v15, 16, v34
	v_and_b32_e32 v0, 15, v38
	v_cndmask_b32_e32 v2, v195, v3, vcc
	v_mul_f32_e32 v14, 0x3e000000, v2
	global_load_dwordx4 v[2:5], v[42:43], off offset:2608
	v_mul_f32_e32 v15, v14, v15
	v_cvt_pk_bf16_f32 v15, v15, s0
	s_movk_i32 s0, 0xde00
	v_mad_i32_i24 v16, v40, s0, v44
	ds_write_b16 v16, v15 offset:34816
	v_and_b32_e32 v15, 0xffff0000, v34
	v_mul_f32_e32 v15, v14, v15
	v_cvt_pk_bf16_f32 v15, v15, s0
	v_mad_i32_i24 v17, v40, s0, v41
	ds_write_b16 v17, v15 offset:35088
	v_lshlrev_b32_e32 v15, 16, v35
	v_mul_f32_e32 v15, v14, v15
	v_cvt_pk_bf16_f32 v15, v15, s0
	ds_write_b16 v16, v15 offset:35360
	v_and_b32_e32 v15, 0xffff0000, v35
	v_mul_f32_e32 v15, v14, v15
	v_cvt_pk_bf16_f32 v15, v15, s0
	ds_write_b16 v17, v15 offset:35632
	v_lshlrev_b32_e32 v15, 16, v36
	v_mul_f32_e32 v15, v14, v15
	v_cvt_pk_bf16_f32 v15, v15, s0
	ds_write_b16 v16, v15 offset:35904
	v_and_b32_e32 v15, 0xffff0000, v36
	v_mul_f32_e32 v15, v14, v15
	v_cvt_pk_bf16_f32 v15, v15, s0
	ds_write_b16 v17, v15 offset:36176
	v_lshlrev_b32_e32 v15, 16, v37
	v_mul_f32_e32 v15, v14, v15
	v_cvt_pk_bf16_f32 v15, v15, s0
	ds_write_b16 v16, v15 offset:36448
	v_and_b32_e32 v15, 0xffff0000, v37
	v_mul_f32_e32 v15, v14, v15
	v_cvt_pk_bf16_f32 v15, v15, s0
	ds_write_b16 v17, v15 offset:36720
	s_waitcnt vmcnt(2)
	v_lshlrev_b32_e32 v15, 16, v10
	v_and_b32_e32 v10, 0xffff0000, v10
	v_mul_f32_e32 v10, v14, v10
	v_cvt_pk_bf16_f32 v10, v10, s0
	ds_write_b16 v17, v10 offset:37264
	v_lshlrev_b32_e32 v10, 16, v11
	v_mul_f32_e32 v10, v14, v10
	v_cvt_pk_bf16_f32 v10, v10, s0
	ds_write_b16 v16, v10 offset:37536
	v_and_b32_e32 v10, 0xffff0000, v11
	v_mul_f32_e32 v10, v14, v10
	v_cvt_pk_bf16_f32 v10, v10, s0
	ds_write_b16 v17, v10 offset:37808
	v_lshlrev_b32_e32 v10, 16, v12
	v_mul_f32_e32 v10, v14, v10
	v_cvt_pk_bf16_f32 v10, v10, s0
	ds_write_b16 v16, v10 offset:38080
	v_and_b32_e32 v10, 0xffff0000, v12
	v_mul_f32_e32 v10, v14, v10
	v_cvt_pk_bf16_f32 v10, v10, s0
	ds_write_b16 v17, v10 offset:38352
	v_lshlrev_b32_e32 v10, 16, v13
	v_mul_f32_e32 v10, v14, v10
	v_cvt_pk_bf16_f32 v10, v10, s0
	ds_write_b16 v16, v10 offset:38624
	v_and_b32_e32 v10, 0xffff0000, v13
	v_mul_f32_e32 v10, v14, v10
	v_cvt_pk_bf16_f32 v10, v10, s0
	ds_write_b16 v17, v10 offset:38896
	s_waitcnt vmcnt(1)
	v_lshlrev_b32_e32 v10, 16, v6
	v_and_b32_e32 v6, 0xffff0000, v6
	v_mul_f32_e32 v6, v14, v6
	v_cvt_pk_bf16_f32 v6, v6, s0
	ds_write_b16 v17, v6 offset:39440
	v_lshlrev_b32_e32 v6, 16, v7
	v_mul_f32_e32 v6, v14, v6
	v_cvt_pk_bf16_f32 v6, v6, s0
	ds_write_b16 v16, v6 offset:39712
	v_and_b32_e32 v6, 0xffff0000, v7
	v_mul_f32_e32 v6, v14, v6
	v_cvt_pk_bf16_f32 v6, v6, s0
	ds_write_b16 v17, v6 offset:39984
	v_lshlrev_b32_e32 v6, 16, v8
	v_mul_f32_e32 v6, v14, v6
	v_cvt_pk_bf16_f32 v6, v6, s0
	ds_write_b16 v16, v6 offset:40256
	v_and_b32_e32 v6, 0xffff0000, v8
	v_mul_f32_e32 v6, v14, v6
	v_cvt_pk_bf16_f32 v6, v6, s0
	ds_write_b16 v17, v6 offset:40528
	v_lshlrev_b32_e32 v6, 16, v9
	v_mul_f32_e32 v6, v14, v6
	v_cvt_pk_bf16_f32 v6, v6, s0
	ds_write_b16 v16, v6 offset:40800
	v_and_b32_e32 v6, 0xffff0000, v9
	v_mul_f32_e32 v6, v14, v6
	v_cvt_pk_bf16_f32 v6, v6, s0
	ds_write_b16 v17, v6 offset:41072
	s_waitcnt vmcnt(0)
	v_lshlrev_b32_e32 v6, 16, v2
	v_and_b32_e32 v2, 0xffff0000, v2
	v_mul_f32_e32 v2, v14, v2
	v_cvt_pk_bf16_f32 v2, v2, s0
	ds_write_b16 v17, v2 offset:41616
	v_lshlrev_b32_e32 v2, 16, v3
	v_mul_f32_e32 v2, v14, v2
	v_cvt_pk_bf16_f32 v2, v2, s0
	ds_write_b16 v16, v2 offset:41888
	v_and_b32_e32 v2, 0xffff0000, v3
	v_mul_f32_e32 v2, v14, v2
	v_cvt_pk_bf16_f32 v2, v2, s0
	ds_write_b16 v17, v2 offset:42160
	v_lshlrev_b32_e32 v2, 16, v4
	v_mul_f32_e32 v2, v14, v2
	v_cvt_pk_bf16_f32 v2, v2, s0
	ds_write_b16 v16, v2 offset:42432
	v_and_b32_e32 v2, 0xffff0000, v4
	v_mul_f32_e32 v2, v14, v2
	v_cvt_pk_bf16_f32 v2, v2, s0
	ds_write_b16 v17, v2 offset:42704
	v_lshlrev_b32_e32 v2, 16, v5
	v_mul_f32_e32 v2, v14, v2
	v_cvt_pk_bf16_f32 v2, v2, s0
	ds_write_b16 v16, v2 offset:42976
	v_and_b32_e32 v2, 0xffff0000, v5
	v_mul_f32_e32 v2, v14, v2
	v_mul_f32_e32 v6, v14, v6
	v_cvt_pk_bf16_f32 v2, v2, s0
	v_cvt_pk_bf16_f32 v6, v6, s0
	ds_write_b16 v17, v2 offset:43248
	v_or_b32_e32 v2, v55, v0
	v_mul_f32_e32 v15, v14, v15
	v_mul_f32_e32 v10, v14, v10
	ds_write_b16 v16, v6 offset:41344
	v_lshl_add_u32 v6, v54, 4, s15
	v_mul_u32_u24_e32 v2, 0x88, v2
	v_mul_u32_u24_e32 v7, 0x88, v0
	v_cvt_pk_bf16_f32 v15, v15, s0
	v_cvt_pk_bf16_f32 v10, v10, s0
	v_lshl_add_u32 v56, v2, 1, v6
	v_lshl_add_u32 v57, v7, 1, v6
	ds_write_b16 v16, v15 offset:36992
	ds_write_b16 v16, v10 offset:39168
	s_waitcnt lgkmcnt(0)
	s_barrier
	ds_read_b128 v[2:5], v56
	ds_read_b128 v[38:41], v56 offset:64
	ds_read_b128 v[6:9], v57 offset:34816
	ds_read_b128 v[34:37], v56 offset:4352
	ds_read_b128 v[14:17], v57 offset:39168
	ds_read_b128 v[22:25], v57 offset:43520
	ds_read_b128 v[30:33], v57 offset:47872
	ds_read_b128 v[46:49], v57 offset:43584
	s_waitcnt lgkmcnt(5)
	v_mfma_f32_16x16x32_bf16 v[10:13], v[2:5], v[6:9], 0
	ds_read_b128 v[42:45], v57 offset:39232
	ds_read_b128 v[50:53], v57 offset:47936
	s_lshl_b64 s[0:1], s[10:11], 15
	s_waitcnt lgkmcnt(5)
	v_mfma_f32_16x16x32_bf16 v[18:21], v[2:5], v[14:17], 0
	s_add_u32 s0, s24, s0
	s_addc_u32 s1, s25, s1
	s_add_i32 s9, s2, 0xfffffd80
	s_waitcnt lgkmcnt(4)
	v_mfma_f32_16x16x32_bf16 v[26:29], v[2:5], v[22:25], 0
	s_waitcnt lgkmcnt(3)
	v_mfma_f32_16x16x32_bf16 v[2:5], v[2:5], v[30:33], 0
	v_mfma_f32_16x16x32_bf16 v[6:9], v[34:37], v[6:9], 0
	v_mfma_f32_16x16x32_bf16 v[14:17], v[34:37], v[14:17], 0
	v_mfma_f32_16x16x32_bf16 v[22:25], v[34:37], v[22:25], 0
	v_mfma_f32_16x16x32_bf16 v[30:33], v[34:37], v[30:33], 0
	ds_read_b128 v[34:37], v57 offset:34880
	s_waitcnt lgkmcnt(0)
	v_mfma_f32_16x16x32_bf16 v[10:13], v[38:41], v[34:37], v[10:13]
	v_mfma_f32_16x16x32_bf16 v[18:21], v[38:41], v[42:45], v[18:21]
	v_mfma_f32_16x16x32_bf16 v[26:29], v[38:41], v[46:49], v[26:29]
	v_mfma_f32_16x16x32_bf16 v[2:5], v[38:41], v[50:53], v[2:5]
	ds_read_b128 v[38:41], v56 offset:4416
	s_waitcnt lgkmcnt(0)
	v_mfma_f32_16x16x32_bf16 v[6:9], v[38:41], v[34:37], v[6:9]
	ds_read_b128 v[34:37], v56 offset:128
	v_mfma_f32_16x16x32_bf16 v[14:17], v[38:41], v[42:45], v[14:17]
	ds_read_b128 v[42:45], v57 offset:39296
	v_mfma_f32_16x16x32_bf16 v[22:25], v[38:41], v[46:49], v[22:25]
	ds_read_b128 v[46:49], v57 offset:43648
	v_mfma_f32_16x16x32_bf16 v[30:33], v[38:41], v[50:53], v[30:33]
	ds_read_b128 v[38:41], v57 offset:34944
	ds_read_b128 v[50:53], v57 offset:48000
	s_waitcnt lgkmcnt(1)
	v_mfma_f32_16x16x32_bf16 v[10:13], v[34:37], v[38:41], v[10:13]
	v_mfma_f32_16x16x32_bf16 v[18:21], v[34:37], v[42:45], v[18:21]
	v_mfma_f32_16x16x32_bf16 v[26:29], v[34:37], v[46:49], v[26:29]
	s_waitcnt lgkmcnt(0)
	v_mfma_f32_16x16x32_bf16 v[2:5], v[34:37], v[50:53], v[2:5]
	ds_read_b128 v[34:37], v56 offset:4480
	s_waitcnt lgkmcnt(0)
	v_mfma_f32_16x16x32_bf16 v[6:9], v[34:37], v[38:41], v[6:9]
	ds_read_b128 v[38:41], v56 offset:192
	v_mfma_f32_16x16x32_bf16 v[14:17], v[34:37], v[42:45], v[14:17]
	ds_read_b128 v[42:45], v57 offset:39360
	v_mfma_f32_16x16x32_bf16 v[22:25], v[34:37], v[46:49], v[22:25]
	ds_read_b128 v[46:49], v57 offset:43712
	v_mfma_f32_16x16x32_bf16 v[30:33], v[34:37], v[50:53], v[30:33]
	ds_read_b128 v[34:37], v57 offset:35008
	ds_read_b128 v[50:53], v57 offset:48064
	s_waitcnt lgkmcnt(1)
	v_mfma_f32_16x16x32_bf16 v[10:13], v[38:41], v[34:37], v[10:13]
	v_mfma_f32_16x16x32_bf16 v[18:21], v[38:41], v[42:45], v[18:21]
	v_mfma_f32_16x16x32_bf16 v[26:29], v[38:41], v[46:49], v[26:29]
	s_waitcnt lgkmcnt(0)
	v_mfma_f32_16x16x32_bf16 v[2:5], v[38:41], v[50:53], v[2:5]
	ds_read_b128 v[38:41], v56 offset:4544
	s_waitcnt lgkmcnt(0)
	v_mfma_f32_16x16x32_bf16 v[6:9], v[38:41], v[34:37], v[6:9]
	v_lshlrev_b32_e32 v37, 6, v55
	v_lshl_or_b32 v37, v54, 8, v37
	v_or_b32_e32 v34, 16, v0
	v_mfma_f32_16x16x32_bf16 v[14:17], v[38:41], v[42:45], v[14:17]
	v_or_b32_e32 v35, 32, v0
	v_or_b32_e32 v36, 48, v0
	v_mfma_f32_16x16x32_bf16 v[22:25], v[38:41], v[46:49], v[22:25]
	v_mfma_f32_16x16x32_bf16 v[30:33], v[38:41], v[50:53], v[30:33]
	v_or_b32_e32 v38, v37, v0
	v_lshlrev_b32_e32 v38, 2, v38
	global_store_dword v38, v10, s[0:1]
	global_store_dword v38, v11, s[0:1] offset:256
	global_store_dword v38, v12, s[0:1] offset:512
	global_store_dword v38, v13, s[0:1] offset:768
	global_store_dword v38, v18, s[0:1] offset:64
	v_or_b32_e32 v10, v37, v34
	v_lshlrev_b32_e32 v10, 2, v10
	global_store_dword v10, v19, s[0:1] offset:256
	global_store_dword v10, v20, s[0:1] offset:512
	global_store_dword v10, v21, s[0:1] offset:768
	global_store_dword v38, v26, s[0:1] offset:128
	v_or_b32_e32 v10, v37, v35
	v_lshlrev_b32_e32 v10, 2, v10
	global_store_dword v10, v27, s[0:1] offset:256
	global_store_dword v10, v28, s[0:1] offset:512
	global_store_dword v10, v29, s[0:1] offset:768
	global_store_dword v38, v2, s[0:1] offset:192
	v_or_b32_e32 v2, v37, v36
	v_lshlrev_b32_e32 v2, 2, v2
	global_store_dword v2, v3, s[0:1] offset:256
	global_store_dword v2, v4, s[0:1] offset:512
	global_store_dword v2, v5, s[0:1] offset:768
	v_or_b32_e32 v2, 0x400, v37
	v_or_b32_e32 v3, v2, v0
	v_lshlrev_b32_e32 v3, 2, v3
	global_store_dword v3, v6, s[0:1]
	v_or_b32_e32 v3, 0x440, v37
	v_or_b32_e32 v4, v3, v0
	v_lshlrev_b32_e32 v4, 2, v4
	global_store_dword v4, v7, s[0:1]
	v_or_b32_e32 v4, 0x480, v37
	v_or_b32_e32 v5, v4, v0
	v_lshlrev_b32_e32 v5, 2, v5
	global_store_dword v5, v8, s[0:1]
	v_or_b32_e32 v5, 0x4c0, v37
	v_or_b32_e32 v0, v5, v0
	v_lshlrev_b32_e32 v0, 2, v0
	global_store_dword v0, v9, s[0:1]
	v_or_b32_e32 v0, v2, v34
	v_lshlrev_b32_e32 v0, 2, v0
	global_store_dword v0, v14, s[0:1]
	v_or_b32_e32 v0, v3, v34
	v_lshlrev_b32_e32 v0, 2, v0
	global_store_dword v0, v15, s[0:1]
	v_or_b32_e32 v0, v4, v34
	v_lshlrev_b32_e32 v0, 2, v0
	global_store_dword v0, v16, s[0:1]
	v_or_b32_e32 v0, v5, v34
	v_lshlrev_b32_e32 v0, 2, v0
	global_store_dword v0, v17, s[0:1]
	v_or_b32_e32 v0, v2, v35
	v_lshlrev_b32_e32 v0, 2, v0
	global_store_dword v0, v22, s[0:1]
	v_or_b32_e32 v0, v3, v35
	v_lshlrev_b32_e32 v0, 2, v0
	global_store_dword v0, v23, s[0:1]
	v_or_b32_e32 v0, v4, v35
	v_lshlrev_b32_e32 v0, 2, v0
	global_store_dword v0, v24, s[0:1]
	v_or_b32_e32 v0, v5, v35
	v_lshlrev_b32_e32 v0, 2, v0
	global_store_dword v0, v25, s[0:1]
	v_or_b32_e32 v0, v2, v36
	v_lshlrev_b32_e32 v0, 2, v0
	global_store_dword v0, v30, s[0:1]
	v_or_b32_e32 v0, v3, v36
	v_lshlrev_b32_e32 v0, 2, v0
	global_store_dword v0, v31, s[0:1]
	v_or_b32_e32 v0, v4, v36
	v_lshlrev_b32_e32 v0, 2, v0
	global_store_dword v0, v32, s[0:1]
	v_or_b32_e32 v0, v5, v36
	v_lshlrev_b32_e32 v0, 2, v0
	global_store_dword v0, v33, s[0:1]
	s_lshl_b32 s0, s9, 6
	s_and_b32 s11, s0, 0x3fc0
	v_mov_b32_e32 v0, v194
	s_cmpk_lt_u32 s9, 0x200
	s_barrier
	s_cselect_b64 s[0:1], -1, 0
	s_and_b64 s[4:5], s[0:1], exec
	v_bfe_u32 v12, v0, 2, 6
	v_lshlrev_b32_e32 v0, 4, v0
	s_cselect_b32 s4, s39, 0xe80
	s_lshr_b32 s5, s9, 2
	v_and_b32_e32 v10, 48, v0
	v_or_b32_e32 v0, s11, v12
	s_and_b32 s9, s5, 64
	v_mul_u32_u24_e32 v0, 0xf80, v0
	s_or_b32 s4, s4, s9
	v_lshlrev_b32_e32 v0, 1, v0
	v_lshl_add_u64 v[2:3], s[50:51], 0, v[0:1]
	s_lshl_b32 s4, s4, 1
	s_mov_b32 s5, s89
	v_lshl_add_u64 v[2:3], v[2:3], 0, s[4:5]
	v_lshlrev_b32_e32 v0, 1, v10
	v_lshl_add_u64 v[6:7], v[2:3], 0, v[0:1]
	global_load_dwordx4 v[2:5], v[6:7], off
	s_nop 0
	global_load_dwordx4 v[6:9], v[6:7], off offset:16
	v_mul_u32_u24_e32 v10, 0x48, v10
	v_lshlrev_b32_e32 v10, 1, v10
	v_lshlrev_b32_e32 v11, 1, v12
	v_add3_u32 v13, s15, v10, v11
	v_add3_u32 v10, s15, v11, v10
	s_and_b64 s[0:1], s[0:1], exec
	s_cselect_b32 s1, s53, s55
	s_cselect_b32 s0, s52, s54
	s_waitcnt vmcnt(1)
	ds_write_b16 v13, v2
	ds_write_b16_d16_hi v10, v2 offset:144
	ds_write_b16 v13, v3 offset:288
	ds_write_b16_d16_hi v10, v3 offset:432
	ds_write_b16 v13, v4 offset:576
	ds_write_b16_d16_hi v10, v4 offset:720
	ds_write_b16 v13, v5 offset:864
	ds_write_b16_d16_hi v10, v5 offset:1008
	s_waitcnt vmcnt(0)
	ds_write_b16 v13, v6 offset:1152
	ds_write_b16_d16_hi v10, v6 offset:1296
	ds_write_b16 v13, v7 offset:1440
	ds_write_b16_d16_hi v10, v7 offset:1584
	ds_write_b16 v13, v8 offset:1728
	ds_write_b16_d16_hi v10, v8 offset:1872
	ds_write_b16 v13, v9 offset:2016
	ds_write_b16_d16_hi v10, v9 offset:2160
	v_or_b32_e32 v2, s9, v12
	v_lshlrev_b32_e32 v2, 15, v2
	v_mov_b32_e32 v3, v1
	v_lshl_add_u64 v[10:11], s[0:1], 0, v[2:3]
	v_mul_u32_u24_e32 v2, 0x90, v12
	v_add3_u32 v6, s15, v2, v0
	s_waitcnt lgkmcnt(0)
	s_barrier
	ds_read_b128 v[2:5], v6
	ds_read_b128 v[6:9], v6 offset:16
	s_lshl_b32 s0, s11, 1
	s_mov_b32 s1, s89
	s_add_i32 s9, s2, 0xfffffd81
	v_lshl_add_u64 v[10:11], v[10:11], 0, s[0:1]
	s_lshl_b32 s0, s9, 6
	s_and_b32 s11, s0, 0x3fc0
	v_lshl_add_u64 v[10:11], v[10:11], 0, v[0:1]
	v_mov_b32_e32 v0, v194
	s_cmpk_lt_u32 s9, 0x200
	s_waitcnt lgkmcnt(1)
	global_store_dwordx4 v[10:11], v[2:5], off
	s_waitcnt lgkmcnt(0)
	global_store_dwordx4 v[10:11], v[6:9], off offset:16
	s_barrier
	s_cselect_b64 s[0:1], -1, 0
	s_and_b64 s[4:5], s[0:1], exec
	v_bfe_u32 v12, v0, 2, 6
	v_lshlrev_b32_e32 v0, 4, v0
	s_cselect_b32 s4, s39, 0xe80
	s_lshr_b32 s5, s9, 2
	v_and_b32_e32 v10, 48, v0
	v_or_b32_e32 v0, s11, v12
	s_and_b32 s9, s5, 64
	v_mul_u32_u24_e32 v0, 0xf80, v0
	s_or_b32 s4, s4, s9
	v_lshlrev_b32_e32 v0, 1, v0
	v_lshl_add_u64 v[2:3], s[50:51], 0, v[0:1]
	s_lshl_b32 s4, s4, 1
	s_mov_b32 s5, s89
	v_lshl_add_u64 v[2:3], v[2:3], 0, s[4:5]
	v_lshlrev_b32_e32 v0, 1, v10
	v_lshl_add_u64 v[6:7], v[2:3], 0, v[0:1]
	global_load_dwordx4 v[2:5], v[6:7], off
	s_nop 0
	global_load_dwordx4 v[6:9], v[6:7], off offset:16
	v_mul_u32_u24_e32 v10, 0x48, v10
	v_lshlrev_b32_e32 v10, 1, v10
	v_lshlrev_b32_e32 v11, 1, v12
	v_add3_u32 v13, s15, v10, v11
	v_add3_u32 v10, s15, v11, v10
	s_and_b64 s[0:1], s[0:1], exec
	s_cselect_b32 s1, s53, s55
	s_cselect_b32 s0, s52, s54
	s_addk_i32 s2, 0xfd82
	s_waitcnt vmcnt(1)
	ds_write_b16 v13, v2
	ds_write_b16_d16_hi v10, v2 offset:144
	ds_write_b16 v13, v3 offset:288
	ds_write_b16_d16_hi v10, v3 offset:432
	ds_write_b16 v13, v4 offset:576
	ds_write_b16_d16_hi v10, v4 offset:720
	ds_write_b16 v13, v5 offset:864
	ds_write_b16_d16_hi v10, v5 offset:1008
	s_waitcnt vmcnt(0)
	ds_write_b16 v13, v6 offset:1152
	ds_write_b16_d16_hi v10, v6 offset:1296
	ds_write_b16 v13, v7 offset:1440
	ds_write_b16_d16_hi v10, v7 offset:1584
	ds_write_b16 v13, v8 offset:1728
	ds_write_b16_d16_hi v10, v8 offset:1872
	ds_write_b16 v13, v9 offset:2016
	ds_write_b16_d16_hi v10, v9 offset:2160
	v_or_b32_e32 v2, s9, v12
	v_lshlrev_b32_e32 v2, 15, v2
	v_mov_b32_e32 v3, v1
	v_lshl_add_u64 v[10:11], s[0:1], 0, v[2:3]
	v_mul_u32_u24_e32 v2, 0x90, v12
	v_add3_u32 v6, s15, v2, v0
	s_waitcnt lgkmcnt(0)
	s_barrier
	ds_read_b128 v[2:5], v6
	ds_read_b128 v[6:9], v6 offset:16
	s_lshl_b32 s0, s11, 1
	s_mov_b32 s1, s89
	v_lshl_add_u64 v[10:11], v[10:11], 0, s[0:1]
	s_lshl_b32 s0, s2, 6
	s_and_b32 s9, s0, 0x3fc0
	v_lshl_add_u64 v[10:11], v[10:11], 0, v[0:1]
	v_mov_b32_e32 v0, v194
	s_cmpk_lt_u32 s2, 0x200
	s_waitcnt lgkmcnt(1)
	global_store_dwordx4 v[10:11], v[2:5], off
	s_waitcnt lgkmcnt(0)
	global_store_dwordx4 v[10:11], v[6:9], off offset:16
	s_barrier
	s_cselect_b64 s[0:1], -1, 0
	s_and_b64 s[4:5], s[0:1], exec
	v_bfe_u32 v12, v0, 2, 6
	v_lshlrev_b32_e32 v0, 4, v0
	s_cselect_b32 s4, s39, 0xe80
	s_lshr_b32 s2, s2, 2
	v_and_b32_e32 v10, 48, v0
	v_or_b32_e32 v0, s9, v12
	s_and_b32 s2, s2, 64
	v_mul_u32_u24_e32 v0, 0xf80, v0
	s_or_b32 s4, s4, s2
	v_lshlrev_b32_e32 v0, 1, v0
	v_lshl_add_u64 v[2:3], s[50:51], 0, v[0:1]
	s_lshl_b32 s4, s4, 1
	s_mov_b32 s5, s89
	v_lshl_add_u64 v[2:3], v[2:3], 0, s[4:5]
	v_lshlrev_b32_e32 v0, 1, v10
	v_lshl_add_u64 v[6:7], v[2:3], 0, v[0:1]
	global_load_dwordx4 v[2:5], v[6:7], off
	s_nop 0
	global_load_dwordx4 v[6:9], v[6:7], off offset:16
	v_mul_u32_u24_e32 v10, 0x48, v10
	v_lshlrev_b32_e32 v10, 1, v10
	v_lshlrev_b32_e32 v11, 1, v12
	v_add3_u32 v13, s15, v10, v11
	v_add3_u32 v10, s15, v11, v10
	s_and_b64 s[0:1], s[0:1], exec
	s_cselect_b32 s1, s53, s55
	s_cselect_b32 s0, s52, s54
	s_mov_b64 s[4:5], 0
	s_waitcnt vmcnt(1)
	ds_write_b16 v13, v2
	ds_write_b16_d16_hi v10, v2 offset:144
	ds_write_b16 v13, v3 offset:288
	ds_write_b16_d16_hi v10, v3 offset:432
	ds_write_b16 v13, v4 offset:576
	ds_write_b16_d16_hi v10, v4 offset:720
	ds_write_b16 v13, v5 offset:864
	ds_write_b16_d16_hi v10, v5 offset:1008
	s_waitcnt vmcnt(0)
	ds_write_b16 v13, v6 offset:1152
	ds_write_b16_d16_hi v10, v6 offset:1296
	ds_write_b16 v13, v7 offset:1440
	ds_write_b16_d16_hi v10, v7 offset:1584
	ds_write_b16 v13, v8 offset:1728
	ds_write_b16_d16_hi v10, v8 offset:1872
	ds_write_b16 v13, v9 offset:2016
	ds_write_b16_d16_hi v10, v9 offset:2160
	v_or_b32_e32 v2, s2, v12
	v_lshlrev_b32_e32 v2, 15, v2
	v_mov_b32_e32 v3, v1
	v_lshl_add_u64 v[10:11], s[0:1], 0, v[2:3]
	v_mul_u32_u24_e32 v2, 0x90, v12
	v_add3_u32 v6, s15, v2, v0
	s_waitcnt lgkmcnt(0)
	s_barrier
	ds_read_b128 v[2:5], v6
	ds_read_b128 v[6:9], v6 offset:16
	s_lshl_b32 s0, s9, 1
	s_mov_b32 s1, s89
	v_lshl_add_u64 v[10:11], v[10:11], 0, s[0:1]
	v_lshl_add_u64 v[10:11], v[10:11], 0, v[0:1]
	s_mov_b64 s[0:1], 0
	s_cmpk_lt_u32 s10, 0x180
	s_waitcnt lgkmcnt(1)
	global_store_dwordx4 v[10:11], v[2:5], off
	s_waitcnt lgkmcnt(0)
	global_store_dwordx4 v[10:11], v[6:9], off offset:16
	s_barrier
	s_cbranch_scc0 .LBB0_627
	s_lshl_b32 s2, s10, 6
	v_mov_b32_e32 v0, v194
	s_and_b32 s2, s2, 0x3fc0
	s_xor_b32 s2, s2, 0x2000
	v_bfe_u32 v12, v0, 2, 6
	v_lshlrev_b32_e32 v0, 4, v0
	v_and_b32_e32 v10, 48, v0
	v_or_b32_e32 v0, s2, v12
	v_mul_u32_u24_e32 v0, 0xf80, v0
	v_readlane_b32 s40, v251, 54
	v_lshlrev_b32_e32 v0, 1, v0
	v_readlane_b32 s46, v251, 60
	v_readlane_b32 s47, v251, 61
	s_mov_b64 s[4:5], 0x1d80
	v_lshlrev_b32_e32 v11, 1, v12
	v_lshl_add_u64 v[2:3], s[46:47], 0, v[0:1]
	v_lshlrev_b32_e32 v0, 1, v10
	v_lshl_add_u64 v[2:3], v[2:3], 0, v[0:1]
	v_lshl_add_u64 v[6:7], v[2:3], 0, s[4:5]
	v_add_co_u32_e32 v2, vcc, s68, v2
	v_mul_u32_u24_e32 v10, 0x48, v10
	s_nop 0
	v_addc_co_u32_e32 v3, vcc, 0, v3, vcc
	global_load_dwordx4 v[2:5], v[2:3], off offset:3456
	s_nop 0
	global_load_dwordx4 v[6:9], v[6:7], off offset:16
	v_lshlrev_b32_e32 v10, 1, v10
	v_add3_u32 v13, s15, v10, v11
	v_add3_u32 v10, s15, v11, v10
	v_readlane_b32 s50, v252, 0
	v_readlane_b32 s51, v252, 1
	s_lshl_b32 s4, s2, 1
	s_mov_b32 s5, s89
	v_readlane_b32 s41, v251, 55
	v_readlane_b32 s42, v251, 56
	v_readlane_b32 s43, v251, 57
	v_readlane_b32 s44, v251, 58
	v_readlane_b32 s45, v251, 59
	v_readlane_b32 s48, v251, 62
	v_readlane_b32 s49, v251, 63
	v_readlane_b32 s52, v252, 2
	v_readlane_b32 s53, v252, 3
	v_readlane_b32 s54, v252, 4
	v_readlane_b32 s55, v252, 5
	s_waitcnt vmcnt(1)
	ds_write_b16 v13, v2
	ds_write_b16_d16_hi v10, v2 offset:144
	ds_write_b16 v13, v3 offset:288
	ds_write_b16_d16_hi v10, v3 offset:432
	ds_write_b16 v13, v4 offset:576
	ds_write_b16_d16_hi v10, v4 offset:720
	ds_write_b16 v13, v5 offset:864
	ds_write_b16_d16_hi v10, v5 offset:1008
	s_waitcnt vmcnt(0)
	ds_write_b16 v13, v6 offset:1152
	ds_write_b16_d16_hi v10, v6 offset:1296
	ds_write_b16 v13, v7 offset:1440
	ds_write_b16_d16_hi v10, v7 offset:1584
	ds_write_b16 v13, v8 offset:1728
	ds_write_b16_d16_hi v10, v8 offset:1872
	ds_write_b16 v13, v9 offset:2016
	ds_write_b16_d16_hi v10, v9 offset:2160
	v_lshlrev_b32_e32 v2, 15, v12
	v_mov_b32_e32 v3, v1
	v_lshl_add_u64 v[2:3], s[50:51], 0, v[2:3]
	v_lshl_add_u64 v[2:3], v[2:3], 0, s[4:5]
	v_lshl_add_u64 v[2:3], v[2:3], 0, v[0:1]
	v_mul_u32_u24_e32 v4, 0x90, v12
	s_mov_b64 s[4:5], 0x200000
	v_add3_u32 v0, s15, v4, v0
	v_add_co_u32_e32 v12, vcc, 0x200000, v2
	s_waitcnt lgkmcnt(0)
	s_barrier
	v_lshl_add_u64 v[10:11], v[2:3], 0, s[4:5]
	v_addc_co_u32_e32 v13, vcc, 0, v3, vcc
	ds_read_b128 v[2:5], v0
	ds_read_b128 v[6:9], v0 offset:16
	s_waitcnt lgkmcnt(1)
	global_store_dwordx4 v[12:13], v[2:5], off
	s_waitcnt lgkmcnt(0)
	global_store_dwordx4 v[10:11], v[6:9], off offset:16
	s_barrier
	s_mov_b64 s[4:5], -1
	s_branch .LBB0_627

.LBB0_627:
	s_and_b64 vcc, exec, s[0:1]
	s_cbranch_vccz .LBB0_631
	s_lshl_b32 s0, s10, 5
	s_and_b32 s4, s0, 0x1f80
	v_mov_b32_e32 v50, v194
	s_bitset1_b32 s4, 13
	v_readlane_b32 s40, v251, 54
	v_bfe_u32 v31, v50, 1, 7
	v_or_b32_e32 v0, s4, v31
	v_and_b32_e32 v16, 1, v50
	v_mul_u32_u24_e32 v0, 0x1f00, v0
	v_readlane_b32 s46, v251, 60
	v_readlane_b32 s47, v251, 61
	v_mov_b32_e32 v18, 0
	v_lshrrev_b32_e32 v30, 1, v50
	v_lshl_add_u64 v[10:11], s[46:47], 0, v[0:1]
	v_lshlrev_b32_e32 v0, 9, v16
	v_readlane_b32 s41, v251, 55
	v_readlane_b32 s42, v251, 56
	v_readlane_b32 s43, v251, 57
	v_readlane_b32 s44, v251, 58
	v_readlane_b32 s45, v251, 59
	v_readlane_b32 s48, v251, 62
	v_readlane_b32 s49, v251, 63
	v_readlane_b32 s50, v252, 0
	v_readlane_b32 s51, v252, 1
	v_readlane_b32 s52, v252, 2
	v_readlane_b32 s53, v252, 3
	v_readlane_b32 s54, v252, 4
	v_readlane_b32 s55, v252, 5
	v_lshl_add_u64 v[12:13], v[10:11], 0, v[0:1]
	v_readfirstlane_b32 s64, v194
	s_lshr_b32 s64, s64, 8
	s_lshl_b32 s0, s64, 8
	s_mov_b32 s1, 0
	s_add_i32 s65, s0, 0x100
	v_mov_b32_e32 v19, v18
	v_lshl_add_u64 v[172:173], v[12:13], 0, s[0:1]
	global_load_dwordx4 v[176:179], v[172:173], off offset:1072
	global_load_dwordx4 v[180:183], v[172:173], off offset:1056
	global_load_dwordx4 v[184:187], v[172:173], off offset:1040
	global_load_dwordx4 v[188:191], v[172:173], off offset:1024
.LBB0_629:
	s_add_u32 s0, s0, 0x80
	s_addc_u32 s1, s1, 0
	s_waitcnt vmcnt(0)
	v_mov_b32_e32 v2, v176
	v_mov_b32_e32 v3, v177
	v_mov_b32_e32 v4, v178
	v_mov_b32_e32 v5, v179
	v_mov_b32_e32 v6, v180
	v_mov_b32_e32 v7, v181
	v_mov_b32_e32 v8, v182
	v_mov_b32_e32 v9, v183
	v_mov_b32_e32 v20, v184
	v_mov_b32_e32 v21, v185
	v_mov_b32_e32 v22, v186
	v_mov_b32_e32 v23, v187
	v_mov_b32_e32 v24, v188
	v_mov_b32_e32 v25, v189
	v_mov_b32_e32 v26, v190
	v_mov_b32_e32 v27, v191
	global_load_dwordx4 v[176:179], v[172:173], off offset:1136
	global_load_dwordx4 v[180:183], v[172:173], off offset:1120
	global_load_dwordx4 v[184:187], v[172:173], off offset:1104
	global_load_dwordx4 v[188:191], v[172:173], off offset:1088
	s_cmp_lg_u32 s0, s65
	v_lshlrev_b32_e32 v0, 16, v24
	v_mul_f32_e32 v17, v0, v0
	v_fmamk_f32 v17, v17, 0xbdd2d3e7, v129
	v_mul_f32_e32 v17, v17, v0
	v_exp_f32_e32 v17, v17
	v_and_b32_e32 v40, 0xffff0000, v27
	v_add_f32_e32 v17, 1.0, v17
	v_rcp_f32_e32 v17, v17
	s_nop 0
	v_mul_f32_e32 v29, v17, v0
	v_and_b32_e32 v0, 0xffff0000, v24
	v_mul_f32_e32 v17, v0, v0
	v_fmamk_f32 v17, v17, 0xbdd2d3e7, v129
	v_mul_f32_e32 v17, v17, v0
	v_exp_f32_e32 v17, v17
	v_mul_f32_e32 v28, v29, v29
	v_add_f32_e32 v17, 1.0, v17
	v_rcp_f32_e32 v17, v17
	s_nop 0
	v_mul_f32_e32 v33, v17, v0
	v_lshlrev_b32_e32 v0, 16, v25
	v_mul_f32_e32 v17, v0, v0
	v_fmamk_f32 v17, v17, 0xbdd2d3e7, v129
	v_mul_f32_e32 v17, v17, v0
	v_exp_f32_e32 v17, v17
	v_mul_f32_e32 v32, v33, v33
	v_add_f32_e32 v17, 1.0, v17
	v_rcp_f32_e32 v17, v17
	s_nop 0
	v_mul_f32_e32 v35, v17, v0
	v_and_b32_e32 v0, 0xffff0000, v25
	v_mul_f32_e32 v17, v0, v0
	v_fmamk_f32 v17, v17, 0xbdd2d3e7, v129
	v_mul_f32_e32 v17, v17, v0
	v_exp_f32_e32 v17, v17
	v_mul_f32_e32 v34, v35, v35
	v_add_f32_e32 v17, 1.0, v17
	v_rcp_f32_e32 v17, v17
	s_nop 0
	v_mul_f32_e32 v25, v17, v0
	v_lshlrev_b32_e32 v0, 16, v26
	v_mul_f32_e32 v17, v0, v0
	v_fmamk_f32 v17, v17, 0xbdd2d3e7, v129
	v_mul_f32_e32 v17, v17, v0
	v_exp_f32_e32 v17, v17
	v_mul_f32_e32 v24, v25, v25
	v_pk_add_f32 v[24:25], v[34:35], v[24:25]
	v_add_f32_e32 v17, 1.0, v17
	v_rcp_f32_e32 v17, v17
	s_nop 0
	v_mul_f32_e32 v37, v17, v0
	v_and_b32_e32 v0, 0xffff0000, v26
	v_mul_f32_e32 v17, v0, v0
	v_fmamk_f32 v17, v17, 0xbdd2d3e7, v129
	v_mul_f32_e32 v17, v17, v0
	v_exp_f32_e32 v17, v17
	v_mul_f32_e32 v26, v40, v40
	v_fmamk_f32 v26, v26, 0xbdd2d3e7, v129
	v_mul_f32_e32 v26, v26, v40
	v_add_f32_e32 v17, 1.0, v17
	v_rcp_f32_e32 v17, v17
	v_exp_f32_e32 v26, v26
	v_mul_f32_e32 v39, v17, v0
	v_lshlrev_b32_e32 v0, 16, v27
	v_mul_f32_e32 v17, v0, v0
	v_fmamk_f32 v17, v17, 0xbdd2d3e7, v129
	v_mul_f32_e32 v17, v17, v0
	v_exp_f32_e32 v17, v17
	v_add_f32_e32 v26, 1.0, v26
	v_rcp_f32_e32 v41, v26
	v_pk_add_f32 v[26:27], v[28:29], v[32:33]
	v_add_f32_e32 v17, 1.0, v17
	v_rcp_f32_e32 v17, v17
	v_mul_f32_e32 v36, v37, v37
	v_mul_f32_e32 v38, v39, v39
	v_pk_add_f32 v[18:19], v[18:19], v[26:27]
	v_mul_f32_e32 v27, v41, v40
	v_pk_add_f32 v[18:19], v[18:19], v[24:25]
	v_pk_add_f32 v[24:25], v[36:37], v[38:39]
	v_mul_f32_e32 v26, v27, v27
	v_pk_add_f32 v[18:19], v[18:19], v[24:25]
	v_mul_f32_e32 v25, v17, v0
	v_lshlrev_b32_e32 v0, 16, v20
	v_mul_f32_e32 v17, v0, v0
	v_fmamk_f32 v17, v17, 0xbdd2d3e7, v129
	v_mul_f32_e32 v17, v17, v0
	v_exp_f32_e32 v17, v17
	v_mul_f32_e32 v24, v25, v25
	v_pk_add_f32 v[24:25], v[24:25], v[26:27]
	v_and_b32_e32 v36, 0xffff0000, v23
	v_add_f32_e32 v17, 1.0, v17
	v_rcp_f32_e32 v17, v17
	v_pk_add_f32 v[18:19], v[18:19], v[24:25]
	v_mul_f32_e32 v25, v17, v0
	v_and_b32_e32 v0, 0xffff0000, v20
	v_mul_f32_e32 v17, v0, v0
	v_fmamk_f32 v17, v17, 0xbdd2d3e7, v129
	v_mul_f32_e32 v17, v17, v0
	v_exp_f32_e32 v17, v17
	v_mul_f32_e32 v24, v25, v25
	v_add_f32_e32 v17, 1.0, v17
	v_rcp_f32_e32 v17, v17
	s_nop 0
	v_mul_f32_e32 v27, v17, v0
	v_lshlrev_b32_e32 v0, 16, v21
	v_mul_f32_e32 v17, v0, v0
	v_fmamk_f32 v17, v17, 0xbdd2d3e7, v129
	v_mul_f32_e32 v17, v17, v0
	v_exp_f32_e32 v17, v17
	v_mul_f32_e32 v26, v27, v27
	v_add_f32_e32 v17, 1.0, v17
	v_rcp_f32_e32 v17, v17
	s_nop 0
	v_mul_f32_e32 v29, v17, v0
	v_and_b32_e32 v0, 0xffff0000, v21
	v_mul_f32_e32 v17, v0, v0
	v_fmamk_f32 v17, v17, 0xbdd2d3e7, v129
	v_mul_f32_e32 v17, v17, v0
	v_exp_f32_e32 v17, v17
	v_mul_f32_e32 v28, v29, v29
	v_add_f32_e32 v17, 1.0, v17
	v_rcp_f32_e32 v17, v17
	s_nop 0
	v_mul_f32_e32 v21, v17, v0
	v_lshlrev_b32_e32 v0, 16, v22
	v_mul_f32_e32 v17, v0, v0
	v_fmamk_f32 v17, v17, 0xbdd2d3e7, v129
	v_mul_f32_e32 v17, v17, v0
	v_exp_f32_e32 v17, v17
	v_mul_f32_e32 v20, v21, v21
	v_pk_add_f32 v[20:21], v[28:29], v[20:21]
	v_add_f32_e32 v17, 1.0, v17
	v_rcp_f32_e32 v17, v17
	s_nop 0
	v_mul_f32_e32 v33, v17, v0
	v_and_b32_e32 v0, 0xffff0000, v22
	v_mul_f32_e32 v17, v0, v0
	v_fmamk_f32 v17, v17, 0xbdd2d3e7, v129
	v_mul_f32_e32 v17, v17, v0
	v_exp_f32_e32 v17, v17
	v_mul_f32_e32 v22, v36, v36
	v_fmamk_f32 v22, v22, 0xbdd2d3e7, v129
	v_mul_f32_e32 v22, v22, v36
	v_add_f32_e32 v17, 1.0, v17
	v_rcp_f32_e32 v17, v17
	v_exp_f32_e32 v22, v22
	v_mul_f32_e32 v35, v17, v0
	v_lshlrev_b32_e32 v0, 16, v23
	v_mul_f32_e32 v17, v0, v0
	v_fmamk_f32 v17, v17, 0xbdd2d3e7, v129
	v_mul_f32_e32 v17, v17, v0
	v_exp_f32_e32 v17, v17
	v_add_f32_e32 v22, 1.0, v22
	v_rcp_f32_e32 v37, v22
	v_pk_add_f32 v[22:23], v[24:25], v[26:27]
	v_add_f32_e32 v17, 1.0, v17
	v_rcp_f32_e32 v17, v17
	v_mul_f32_e32 v32, v33, v33
	v_mul_f32_e32 v34, v35, v35
	v_pk_add_f32 v[18:19], v[18:19], v[22:23]
	v_mul_f32_e32 v23, v37, v36
	v_pk_add_f32 v[18:19], v[18:19], v[20:21]
	v_pk_add_f32 v[20:21], v[32:33], v[34:35]
	v_mul_f32_e32 v22, v23, v23
	v_pk_add_f32 v[18:19], v[18:19], v[20:21]
	v_mul_f32_e32 v21, v17, v0
	v_lshlrev_b32_e32 v0, 16, v6
	v_mul_f32_e32 v17, v0, v0
	v_fmamk_f32 v17, v17, 0xbdd2d3e7, v129
	v_mul_f32_e32 v17, v17, v0
	v_exp_f32_e32 v17, v17
	v_mul_f32_e32 v20, v21, v21
	v_pk_add_f32 v[20:21], v[20:21], v[22:23]
	v_and_b32_e32 v32, 0xffff0000, v9
	v_add_f32_e32 v17, 1.0, v17
	v_rcp_f32_e32 v17, v17
	v_pk_add_f32 v[18:19], v[18:19], v[20:21]
	v_mul_f32_e32 v21, v17, v0
	v_and_b32_e32 v0, 0xffff0000, v6
	v_mul_f32_e32 v6, v0, v0
	v_fmamk_f32 v6, v6, 0xbdd2d3e7, v129
	v_mul_f32_e32 v6, v6, v0
	v_exp_f32_e32 v6, v6
	v_mul_f32_e32 v20, v21, v21
	v_add_f32_e32 v6, 1.0, v6
	v_rcp_f32_e32 v6, v6
	s_nop 0
	v_mul_f32_e32 v23, v6, v0
	v_lshlrev_b32_e32 v0, 16, v7
	v_mul_f32_e32 v6, v0, v0
	v_fmamk_f32 v6, v6, 0xbdd2d3e7, v129
	v_mul_f32_e32 v6, v6, v0
	v_exp_f32_e32 v6, v6
	v_mul_f32_e32 v22, v23, v23
	v_add_f32_e32 v6, 1.0, v6
	v_rcp_f32_e32 v6, v6
	s_nop 0
	v_mul_f32_e32 v25, v6, v0
	v_and_b32_e32 v0, 0xffff0000, v7
	v_mul_f32_e32 v6, v0, v0
	v_fmamk_f32 v6, v6, 0xbdd2d3e7, v129
	v_mul_f32_e32 v6, v6, v0
	v_exp_f32_e32 v6, v6
	v_mul_f32_e32 v24, v25, v25
	v_add_f32_e32 v6, 1.0, v6
	v_rcp_f32_e32 v6, v6
	s_nop 0
	v_mul_f32_e32 v7, v6, v0
	v_lshlrev_b32_e32 v0, 16, v8
	v_mul_f32_e32 v17, v0, v0
	v_fmamk_f32 v17, v17, 0xbdd2d3e7, v129
	v_mul_f32_e32 v17, v17, v0
	v_exp_f32_e32 v17, v17
	v_mul_f32_e32 v6, v7, v7
	v_pk_add_f32 v[6:7], v[24:25], v[6:7]
	v_add_f32_e32 v17, 1.0, v17
	v_rcp_f32_e32 v17, v17
	s_nop 0
	v_mul_f32_e32 v27, v17, v0
	v_and_b32_e32 v0, 0xffff0000, v8
	v_mul_f32_e32 v8, v0, v0
	v_fmamk_f32 v8, v8, 0xbdd2d3e7, v129
	v_mul_f32_e32 v8, v8, v0
	v_exp_f32_e32 v8, v8
	v_mul_f32_e32 v26, v27, v27
	v_add_f32_e32 v8, 1.0, v8
	v_rcp_f32_e32 v8, v8
	s_nop 0
	v_mul_f32_e32 v29, v8, v0
	v_lshlrev_b32_e32 v0, 16, v9
	v_mul_f32_e32 v8, v0, v0
	v_fmamk_f32 v8, v8, 0xbdd2d3e7, v129
	v_mul_f32_e32 v8, v8, v0
	v_exp_f32_e32 v8, v8
	v_mul_f32_e32 v28, v29, v29
	v_add_f32_e32 v8, 1.0, v8
	v_rcp_f32_e32 v17, v8
	v_mul_f32_e32 v8, v32, v32
	v_fmamk_f32 v8, v8, 0xbdd2d3e7, v129
	v_mul_f32_e32 v8, v8, v32
	v_exp_f32_e32 v8, v8
	s_nop 0
	v_add_f32_e32 v8, 1.0, v8
	v_rcp_f32_e32 v33, v8
	v_pk_add_f32 v[8:9], v[20:21], v[22:23]
	s_nop 0
	v_pk_add_f32 v[8:9], v[18:19], v[8:9]
	v_mul_f32_e32 v19, v33, v32
	v_pk_add_f32 v[6:7], v[8:9], v[6:7]
	v_pk_add_f32 v[8:9], v[26:27], v[28:29]
	v_mul_f32_e32 v18, v19, v19
	v_pk_add_f32 v[6:7], v[6:7], v[8:9]
	v_mul_f32_e32 v9, v17, v0
	v_mul_f32_e32 v8, v9, v9
	v_pk_add_f32 v[8:9], v[8:9], v[18:19]
	v_lshlrev_b32_e32 v0, 16, v2
	v_pk_add_f32 v[6:7], v[6:7], v[8:9]
	v_mul_f32_e32 v8, v0, v0
	v_fmamk_f32 v8, v8, 0xbdd2d3e7, v129
	v_mul_f32_e32 v8, v8, v0
	v_exp_f32_e32 v8, v8
	v_and_b32_e32 v26, 0xffff0000, v5
	v_add_f32_e32 v8, 1.0, v8
	v_rcp_f32_e32 v8, v8
	s_nop 0
	v_mul_f32_e32 v9, v8, v0
	v_and_b32_e32 v0, 0xffff0000, v2
	v_mul_f32_e32 v2, v0, v0
	v_fmamk_f32 v2, v2, 0xbdd2d3e7, v129
	v_mul_f32_e32 v2, v2, v0
	v_exp_f32_e32 v2, v2
	v_mul_f32_e32 v8, v9, v9
	v_add_f32_e32 v2, 1.0, v2
	v_rcp_f32_e32 v2, v2
	s_nop 0
	v_mul_f32_e32 v19, v2, v0
	v_lshlrev_b32_e32 v0, 16, v3
	v_mul_f32_e32 v2, v0, v0
	v_fmamk_f32 v2, v2, 0xbdd2d3e7, v129
	v_mul_f32_e32 v2, v2, v0
	v_exp_f32_e32 v2, v2
	v_mul_f32_e32 v18, v19, v19
	v_add_f32_e32 v2, 1.0, v2
	v_rcp_f32_e32 v2, v2
	s_nop 0
	v_mul_f32_e32 v21, v2, v0
	v_and_b32_e32 v0, 0xffff0000, v3
	v_mul_f32_e32 v2, v0, v0
	v_fmamk_f32 v2, v2, 0xbdd2d3e7, v129
	v_mul_f32_e32 v2, v2, v0
	v_exp_f32_e32 v2, v2
	v_mul_f32_e32 v20, v21, v21
	v_add_f32_e32 v2, 1.0, v2
	v_rcp_f32_e32 v2, v2
	s_nop 0
	v_mul_f32_e32 v3, v2, v0
	v_lshlrev_b32_e32 v0, 16, v4
	v_mul_f32_e32 v17, v0, v0
	v_fmamk_f32 v17, v17, 0xbdd2d3e7, v129
	v_mul_f32_e32 v17, v17, v0
	v_exp_f32_e32 v17, v17
	v_mul_f32_e32 v2, v3, v3
	v_pk_add_f32 v[2:3], v[20:21], v[2:3]
	v_add_f32_e32 v17, 1.0, v17
	v_rcp_f32_e32 v17, v17
	s_nop 0
	v_mul_f32_e32 v23, v17, v0
	v_and_b32_e32 v0, 0xffff0000, v4
	v_mul_f32_e32 v4, v0, v0
	v_fmamk_f32 v4, v4, 0xbdd2d3e7, v129
	v_mul_f32_e32 v4, v4, v0
	v_exp_f32_e32 v4, v4
	v_mul_f32_e32 v22, v23, v23
	v_add_f32_e32 v4, 1.0, v4
	v_rcp_f32_e32 v4, v4
	s_nop 0
	v_mul_f32_e32 v25, v4, v0
	v_lshlrev_b32_e32 v0, 16, v5
	v_mul_f32_e32 v4, v0, v0
	v_fmamk_f32 v4, v4, 0xbdd2d3e7, v129
	v_mul_f32_e32 v4, v4, v0
	v_exp_f32_e32 v4, v4
	v_mul_f32_e32 v24, v25, v25
	v_add_f32_e32 v4, 1.0, v4
	v_rcp_f32_e32 v17, v4
	v_mul_f32_e32 v4, v26, v26
	v_fmamk_f32 v4, v4, 0xbdd2d3e7, v129
	v_mul_f32_e32 v4, v4, v26
	v_exp_f32_e32 v4, v4
	s_nop 0
	v_add_f32_e32 v4, 1.0, v4
	v_rcp_f32_e32 v27, v4
	v_pk_add_f32 v[4:5], v[8:9], v[18:19]
	s_nop 0
	v_pk_add_f32 v[4:5], v[6:7], v[4:5]
	v_mul_f32_e32 v7, v27, v26
	v_pk_add_f32 v[2:3], v[4:5], v[2:3]
	v_pk_add_f32 v[4:5], v[22:23], v[24:25]
	v_mul_f32_e32 v6, v7, v7
	v_pk_add_f32 v[2:3], v[2:3], v[4:5]
	v_mul_f32_e32 v5, v17, v0
	v_mul_f32_e32 v4, v5, v5
	v_pk_add_f32 v[4:5], v[4:5], v[6:7]
	s_nop 0
	v_pk_add_f32 v[26:27], v[2:3], v[4:5]
	s_waitcnt vmcnt(0)
	v_mov_b32_e32 v2, v176
	v_mov_b32_e32 v3, v177
	v_mov_b32_e32 v4, v178
	v_mov_b32_e32 v5, v179
	v_mov_b32_e32 v6, v180
	v_mov_b32_e32 v7, v181
	v_mov_b32_e32 v8, v182
	v_mov_b32_e32 v9, v183
	v_mov_b32_e32 v18, v184
	v_mov_b32_e32 v19, v185
	v_mov_b32_e32 v20, v186
	v_mov_b32_e32 v21, v187
	v_mov_b32_e32 v22, v188
	v_mov_b32_e32 v23, v189
	v_mov_b32_e32 v24, v190
	v_mov_b32_e32 v25, v191
	v_lshl_add_u64 v[172:173], v[12:13], 0, s[0:1]
	global_load_dwordx4 v[176:179], v[172:173], off offset:1072
	global_load_dwordx4 v[180:183], v[172:173], off offset:1056
	global_load_dwordx4 v[184:187], v[172:173], off offset:1040
	global_load_dwordx4 v[188:191], v[172:173], off offset:1024
	v_lshlrev_b32_e32 v0, 16, v22
	v_mul_f32_e32 v14, v0, v0
	v_fmamk_f32 v14, v14, 0xbdd2d3e7, v129
	v_mul_f32_e32 v14, v14, v0
	v_exp_f32_e32 v14, v14
	s_nop 0
	v_add_f32_e32 v14, 1.0, v14
	v_rcp_f32_e32 v14, v14
	s_nop 0
	v_mul_f32_e32 v15, v14, v0
	v_and_b32_e32 v0, 0xffff0000, v22
	v_mul_f32_e32 v14, v0, v0
	v_fmamk_f32 v14, v14, 0xbdd2d3e7, v129
	v_mul_f32_e32 v14, v14, v0
	v_exp_f32_e32 v14, v14
	s_nop 0
	v_add_f32_e32 v14, 1.0, v14
	v_rcp_f32_e32 v14, v14
	s_nop 0
	v_mul_f32_e32 v29, v14, v0
	v_lshlrev_b32_e32 v0, 16, v23
	v_mul_f32_e32 v17, v0, v0
	v_fmamk_f32 v17, v17, 0xbdd2d3e7, v129
	v_mul_f32_e32 v17, v17, v0
	v_exp_f32_e32 v17, v17
	v_mul_f32_e32 v14, v15, v15
	v_mul_f32_e32 v28, v29, v29
	v_pk_add_f32 v[14:15], v[14:15], v[28:29]
	v_add_f32_e32 v17, 1.0, v17
	v_rcp_f32_e32 v17, v17
	v_pk_add_f32 v[14:15], v[26:27], v[14:15]
	v_mul_f32_e32 v33, v17, v0
	v_and_b32_e32 v0, 0xffff0000, v23
	v_mul_f32_e32 v17, v0, v0
	v_fmamk_f32 v17, v17, 0xbdd2d3e7, v129
	v_mul_f32_e32 v17, v17, v0
	v_exp_f32_e32 v17, v17
	v_mul_f32_e32 v32, v33, v33
	v_add_f32_e32 v17, 1.0, v17
	v_rcp_f32_e32 v17, v17
	s_nop 0
	v_mul_f32_e32 v23, v17, v0
	v_lshlrev_b32_e32 v0, 16, v24
	v_mul_f32_e32 v17, v0, v0
	v_fmamk_f32 v17, v17, 0xbdd2d3e7, v129
	v_mul_f32_e32 v17, v17, v0
	v_exp_f32_e32 v17, v17
	v_mul_f32_e32 v22, v23, v23
	v_pk_add_f32 v[22:23], v[32:33], v[22:23]
	v_add_f32_e32 v17, 1.0, v17
	v_rcp_f32_e32 v17, v17
	v_pk_add_f32 v[14:15], v[14:15], v[22:23]
	v_mul_f32_e32 v35, v17, v0
	v_and_b32_e32 v0, 0xffff0000, v24
	v_mul_f32_e32 v17, v0, v0
	v_fmamk_f32 v17, v17, 0xbdd2d3e7, v129
	v_mul_f32_e32 v17, v17, v0
	v_exp_f32_e32 v17, v17
	v_and_b32_e32 v24, 0xffff0000, v25
	v_mul_f32_e32 v34, v35, v35
	v_add_f32_e32 v17, 1.0, v17
	v_rcp_f32_e32 v17, v17
	s_nop 0
	v_mul_f32_e32 v37, v17, v0
	v_lshlrev_b32_e32 v0, 16, v25
	v_mul_f32_e32 v17, v0, v0
	v_fmamk_f32 v17, v17, 0xbdd2d3e7, v129
	v_mul_f32_e32 v17, v17, v0
	v_exp_f32_e32 v17, v17
	v_mul_f32_e32 v36, v37, v37
	v_mul_f32_e32 v25, v24, v24
	v_fmamk_f32 v25, v25, 0xbdd2d3e7, v129
	v_add_f32_e32 v17, 1.0, v17
	v_rcp_f32_e32 v17, v17
	v_pk_add_f32 v[22:23], v[34:35], v[36:37]
	v_mul_f32_e32 v25, v25, v24
	v_pk_add_f32 v[14:15], v[14:15], v[22:23]
	v_mul_f32_e32 v23, v17, v0
	v_lshlrev_b32_e32 v0, 16, v18
	v_mul_f32_e32 v17, v0, v0
	v_fmamk_f32 v17, v17, 0xbdd2d3e7, v129
	v_exp_f32_e32 v25, v25
	v_mul_f32_e32 v17, v17, v0
	v_exp_f32_e32 v17, v17
	v_add_f32_e32 v25, 1.0, v25
	v_rcp_f32_e32 v25, v25
	v_mul_f32_e32 v22, v23, v23
	v_add_f32_e32 v17, 1.0, v17
	v_rcp_f32_e32 v17, v17
	v_mul_f32_e32 v25, v25, v24
	v_mul_f32_e32 v24, v25, v25
	v_pk_add_f32 v[22:23], v[22:23], v[24:25]
	v_and_b32_e32 v34, 0xffff0000, v21
	v_pk_add_f32 v[14:15], v[14:15], v[22:23]
	v_mul_f32_e32 v23, v17, v0
	v_and_b32_e32 v0, 0xffff0000, v18
	v_mul_f32_e32 v17, v0, v0
	v_fmamk_f32 v17, v17, 0xbdd2d3e7, v129
	v_mul_f32_e32 v17, v17, v0
	v_exp_f32_e32 v17, v17
	v_mul_f32_e32 v22, v23, v23
	v_add_f32_e32 v17, 1.0, v17
	v_rcp_f32_e32 v17, v17
	s_nop 0
	v_mul_f32_e32 v25, v17, v0
	v_lshlrev_b32_e32 v0, 16, v19
	v_mul_f32_e32 v17, v0, v0
	v_fmamk_f32 v17, v17, 0xbdd2d3e7, v129
	v_mul_f32_e32 v17, v17, v0
	v_exp_f32_e32 v17, v17
	v_mul_f32_e32 v24, v25, v25
	v_add_f32_e32 v17, 1.0, v17
	v_rcp_f32_e32 v17, v17
	s_nop 0
	v_mul_f32_e32 v27, v17, v0
	v_and_b32_e32 v0, 0xffff0000, v19
	v_mul_f32_e32 v17, v0, v0
	v_fmamk_f32 v17, v17, 0xbdd2d3e7, v129
	v_mul_f32_e32 v17, v17, v0
	v_exp_f32_e32 v17, v17
	v_mul_f32_e32 v26, v27, v27
	v_add_f32_e32 v17, 1.0, v17
	v_rcp_f32_e32 v17, v17
	s_nop 0
	v_mul_f32_e32 v19, v17, v0
	v_lshlrev_b32_e32 v0, 16, v20
	v_mul_f32_e32 v17, v0, v0
	v_fmamk_f32 v17, v17, 0xbdd2d3e7, v129
	v_mul_f32_e32 v17, v17, v0
	v_exp_f32_e32 v17, v17
	v_mul_f32_e32 v18, v19, v19
	v_pk_add_f32 v[18:19], v[26:27], v[18:19]
	v_add_f32_e32 v17, 1.0, v17
	v_rcp_f32_e32 v17, v17
	s_nop 0
	v_mul_f32_e32 v29, v17, v0
	v_and_b32_e32 v0, 0xffff0000, v20
	v_mul_f32_e32 v17, v0, v0
	v_fmamk_f32 v17, v17, 0xbdd2d3e7, v129
	v_mul_f32_e32 v17, v17, v0
	v_exp_f32_e32 v17, v17
	v_mul_f32_e32 v20, v34, v34
	v_fmamk_f32 v20, v20, 0xbdd2d3e7, v129
	v_mul_f32_e32 v20, v20, v34
	v_add_f32_e32 v17, 1.0, v17
	v_rcp_f32_e32 v17, v17
	v_exp_f32_e32 v20, v20
	v_mul_f32_e32 v33, v17, v0
	v_lshlrev_b32_e32 v0, 16, v21
	v_mul_f32_e32 v17, v0, v0
	v_fmamk_f32 v17, v17, 0xbdd2d3e7, v129
	v_mul_f32_e32 v17, v17, v0
	v_exp_f32_e32 v17, v17
	v_add_f32_e32 v20, 1.0, v20
	v_rcp_f32_e32 v35, v20
	v_pk_add_f32 v[20:21], v[22:23], v[24:25]
	v_add_f32_e32 v17, 1.0, v17
	v_rcp_f32_e32 v17, v17
	v_mul_f32_e32 v28, v29, v29
	v_mul_f32_e32 v32, v33, v33
	v_pk_add_f32 v[14:15], v[14:15], v[20:21]
	v_mul_f32_e32 v21, v35, v34
	v_pk_add_f32 v[14:15], v[14:15], v[18:19]
	v_pk_add_f32 v[18:19], v[28:29], v[32:33]
	v_mul_f32_e32 v20, v21, v21
	v_pk_add_f32 v[14:15], v[14:15], v[18:19]
	v_mul_f32_e32 v19, v17, v0
	v_lshlrev_b32_e32 v0, 16, v6
	v_mul_f32_e32 v17, v0, v0
	v_fmamk_f32 v17, v17, 0xbdd2d3e7, v129
	v_mul_f32_e32 v17, v17, v0
	v_exp_f32_e32 v17, v17
	v_mul_f32_e32 v18, v19, v19
	v_pk_add_f32 v[18:19], v[18:19], v[20:21]
	v_and_b32_e32 v28, 0xffff0000, v9
	v_add_f32_e32 v17, 1.0, v17
	v_rcp_f32_e32 v17, v17
	v_pk_add_f32 v[14:15], v[14:15], v[18:19]
	v_mul_f32_e32 v19, v17, v0
	v_and_b32_e32 v0, 0xffff0000, v6
	v_mul_f32_e32 v6, v0, v0
	v_fmamk_f32 v6, v6, 0xbdd2d3e7, v129
	v_mul_f32_e32 v6, v6, v0
	v_exp_f32_e32 v6, v6
	v_mul_f32_e32 v18, v19, v19
	v_add_f32_e32 v6, 1.0, v6
	v_rcp_f32_e32 v6, v6
	s_nop 0
	v_mul_f32_e32 v21, v6, v0
	v_lshlrev_b32_e32 v0, 16, v7
	v_mul_f32_e32 v6, v0, v0
	v_fmamk_f32 v6, v6, 0xbdd2d3e7, v129
	v_mul_f32_e32 v6, v6, v0
	v_exp_f32_e32 v6, v6
	v_mul_f32_e32 v20, v21, v21
	v_add_f32_e32 v6, 1.0, v6
	v_rcp_f32_e32 v6, v6
	s_nop 0
	v_mul_f32_e32 v23, v6, v0
	v_and_b32_e32 v0, 0xffff0000, v7
	v_mul_f32_e32 v6, v0, v0
	v_fmamk_f32 v6, v6, 0xbdd2d3e7, v129
	v_mul_f32_e32 v6, v6, v0
	v_exp_f32_e32 v6, v6
	v_mul_f32_e32 v22, v23, v23
	v_add_f32_e32 v6, 1.0, v6
	v_rcp_f32_e32 v6, v6
	s_nop 0
	v_mul_f32_e32 v7, v6, v0
	v_lshlrev_b32_e32 v0, 16, v8
	v_mul_f32_e32 v17, v0, v0
	v_fmamk_f32 v17, v17, 0xbdd2d3e7, v129
	v_mul_f32_e32 v17, v17, v0
	v_exp_f32_e32 v17, v17
	v_mul_f32_e32 v6, v7, v7
	v_pk_add_f32 v[6:7], v[22:23], v[6:7]
	v_add_f32_e32 v17, 1.0, v17
	v_rcp_f32_e32 v17, v17
	s_nop 0
	v_mul_f32_e32 v25, v17, v0
	v_and_b32_e32 v0, 0xffff0000, v8
	v_mul_f32_e32 v8, v0, v0
	v_fmamk_f32 v8, v8, 0xbdd2d3e7, v129
	v_mul_f32_e32 v8, v8, v0
	v_exp_f32_e32 v8, v8
	v_mul_f32_e32 v24, v25, v25
	v_add_f32_e32 v8, 1.0, v8
	v_rcp_f32_e32 v8, v8
	s_nop 0
	v_mul_f32_e32 v27, v8, v0
	v_lshlrev_b32_e32 v0, 16, v9
	v_mul_f32_e32 v8, v0, v0
	v_fmamk_f32 v8, v8, 0xbdd2d3e7, v129
	v_mul_f32_e32 v8, v8, v0
	v_exp_f32_e32 v8, v8
	v_mul_f32_e32 v26, v27, v27
	v_add_f32_e32 v8, 1.0, v8
	v_rcp_f32_e32 v17, v8
	v_mul_f32_e32 v8, v28, v28
	v_fmamk_f32 v8, v8, 0xbdd2d3e7, v129
	v_mul_f32_e32 v8, v8, v28
	v_exp_f32_e32 v8, v8
	s_nop 0
	v_add_f32_e32 v8, 1.0, v8
	v_rcp_f32_e32 v29, v8
	v_pk_add_f32 v[8:9], v[18:19], v[20:21]
	s_nop 0
	v_pk_add_f32 v[8:9], v[14:15], v[8:9]
	v_mul_f32_e32 v15, v29, v28
	v_pk_add_f32 v[6:7], v[8:9], v[6:7]
	v_pk_add_f32 v[8:9], v[24:25], v[26:27]
	v_mul_f32_e32 v14, v15, v15
	v_pk_add_f32 v[6:7], v[6:7], v[8:9]
	v_mul_f32_e32 v9, v17, v0
	v_mul_f32_e32 v8, v9, v9
	v_pk_add_f32 v[8:9], v[8:9], v[14:15]
	v_lshlrev_b32_e32 v0, 16, v2
	v_pk_add_f32 v[6:7], v[6:7], v[8:9]
	v_mul_f32_e32 v8, v0, v0
	v_fmamk_f32 v8, v8, 0xbdd2d3e7, v129
	v_mul_f32_e32 v8, v8, v0
	v_exp_f32_e32 v8, v8
	v_and_b32_e32 v24, 0xffff0000, v5
	v_add_f32_e32 v8, 1.0, v8
	v_rcp_f32_e32 v8, v8
	s_nop 0
	v_mul_f32_e32 v9, v8, v0
	v_and_b32_e32 v0, 0xffff0000, v2
	v_mul_f32_e32 v2, v0, v0
	v_fmamk_f32 v2, v2, 0xbdd2d3e7, v129
	v_mul_f32_e32 v2, v2, v0
	v_exp_f32_e32 v2, v2
	v_mul_f32_e32 v8, v9, v9
	v_add_f32_e32 v2, 1.0, v2
	v_rcp_f32_e32 v2, v2
	s_nop 0
	v_mul_f32_e32 v15, v2, v0
	v_lshlrev_b32_e32 v0, 16, v3
	v_mul_f32_e32 v2, v0, v0
	v_fmamk_f32 v2, v2, 0xbdd2d3e7, v129
	v_mul_f32_e32 v2, v2, v0
	v_exp_f32_e32 v2, v2
	v_mul_f32_e32 v14, v15, v15
	v_add_f32_e32 v2, 1.0, v2
	v_rcp_f32_e32 v2, v2
	s_nop 0
	v_mul_f32_e32 v19, v2, v0
	v_and_b32_e32 v0, 0xffff0000, v3
	v_mul_f32_e32 v2, v0, v0
	v_fmamk_f32 v2, v2, 0xbdd2d3e7, v129
	v_mul_f32_e32 v2, v2, v0
	v_exp_f32_e32 v2, v2
	v_mul_f32_e32 v18, v19, v19
	v_add_f32_e32 v2, 1.0, v2
	v_rcp_f32_e32 v2, v2
	s_nop 0
	v_mul_f32_e32 v3, v2, v0
	v_lshlrev_b32_e32 v0, 16, v4
	v_mul_f32_e32 v17, v0, v0
	v_fmamk_f32 v17, v17, 0xbdd2d3e7, v129
	v_mul_f32_e32 v17, v17, v0
	v_exp_f32_e32 v17, v17
	v_mul_f32_e32 v2, v3, v3
	v_pk_add_f32 v[2:3], v[18:19], v[2:3]
	v_add_f32_e32 v17, 1.0, v17
	v_rcp_f32_e32 v17, v17
	s_nop 0
	v_mul_f32_e32 v21, v17, v0
	v_and_b32_e32 v0, 0xffff0000, v4
	v_mul_f32_e32 v4, v0, v0
	v_fmamk_f32 v4, v4, 0xbdd2d3e7, v129
	v_mul_f32_e32 v4, v4, v0
	v_exp_f32_e32 v4, v4
	v_mul_f32_e32 v20, v21, v21
	v_add_f32_e32 v4, 1.0, v4
	v_rcp_f32_e32 v4, v4
	s_nop 0
	v_mul_f32_e32 v23, v4, v0
	v_lshlrev_b32_e32 v0, 16, v5
	v_mul_f32_e32 v4, v0, v0
	v_fmamk_f32 v4, v4, 0xbdd2d3e7, v129
	v_mul_f32_e32 v4, v4, v0
	v_exp_f32_e32 v4, v4
	v_mul_f32_e32 v22, v23, v23
	v_add_f32_e32 v4, 1.0, v4
	v_rcp_f32_e32 v17, v4
	v_mul_f32_e32 v4, v24, v24
	v_fmamk_f32 v4, v4, 0xbdd2d3e7, v129
	v_mul_f32_e32 v4, v4, v24
	v_exp_f32_e32 v4, v4
	s_nop 0
	v_add_f32_e32 v4, 1.0, v4
	v_rcp_f32_e32 v25, v4
	v_pk_add_f32 v[4:5], v[8:9], v[14:15]
	s_nop 0
	v_pk_add_f32 v[4:5], v[6:7], v[4:5]
	v_mul_f32_e32 v7, v25, v24
	v_pk_add_f32 v[2:3], v[4:5], v[2:3]
	v_pk_add_f32 v[4:5], v[20:21], v[22:23]
	v_mul_f32_e32 v6, v7, v7
	v_pk_add_f32 v[2:3], v[2:3], v[4:5]
	v_mul_f32_e32 v5, v17, v0
	v_mul_f32_e32 v4, v5, v5
	v_pk_add_f32 v[4:5], v[4:5], v[6:7]
	s_nop 0
	v_pk_add_f32 v[18:19], v[2:3], v[4:5]
	s_cbranch_scc1 .LBB0_629
	v_and_b32_e32 v171, 0xff, v194
	v_lshlrev_b32_e32 v171, 3, v171
	s_mul_i32 s66, s64, 0x12000
	s_add_i32 s66, s66, 0x11000
	s_xor_b32 s67, s64, 1
	s_mul_i32 s67, s67, 0x12000
	s_add_i32 s67, s67, 0x11000
	v_add_u32_e32 v172, s66, v171
	v_add_u32_e32 v173, s67, v171
	ds_write_b64 v172, v[18:19]
	s_waitcnt lgkmcnt(0)
	s_barrier
	ds_read_b64 v[174:175], v173
	s_waitcnt lgkmcnt(0)
	v_add_f32_e32 v18, v18, v174
	v_add_f32_e32 v19, v19, v175
	s_mov_b32 s9, s89
	v_lshl_add_u64 v[2:3], v[10:11], 0, s[8:9]
	v_lshlrev_b32_e32 v0, 7, v16
	v_lshl_add_u64 v[22:23], v[2:3], 0, v[0:1]
	global_load_dwordx4 v[10:13], v[22:23], off offset:1024
	v_lshlrev_b32_e32 v20, 8, v16
	global_load_dwordx2 v[28:29], v20, s[16:17]
	global_load_dwordx2 v[36:37], v20, s[20:21]
	global_load_dwordx2 v[40:41], v20, s[16:17] offset:16
	global_load_dwordx2 v[42:43], v20, s[16:17] offset:32
	global_load_dwordx2 v[24:25], v20, s[16:17] offset:48
	global_load_dwordx2 v[44:45], v20, s[20:21] offset:16
	global_load_dwordx2 v[46:47], v20, s[20:21] offset:32
	global_load_dwordx2 v[26:27], v20, s[20:21] offset:48
	v_lshlrev_b32_e32 v34, 6, v16
	v_mul_u32_u24_e32 v4, 0x4400, v16
	global_load_dwordx4 v[14:17], v[22:23], off offset:1040
	ds_bpermute_b32 v3, v80, v19
	ds_bpermute_b32 v2, v80, v18
	s_mov_b32 s0, 0x3b000000
	v_lshlrev_b32_e32 v33, 1, v31
	v_add3_u32 v38, s15, v4, v33
	v_or_b32_e32 v4, 1, v34
	s_waitcnt lgkmcnt(0)
	v_pk_add_f32 v[2:3], v[18:19], v[2:3]
	v_mul_u32_u24_e32 v39, 0x110, v4
	v_pk_mul_f32 v[18:19], v[2:3], s[0:1] op_sel_hi:[1,0]
	v_or_b32_e32 v78, 7, v34
	v_fma_f32 v2, -v19, v19, v18
	v_max_f32_e32 v2, 0, v2
	v_add_f32_e32 v2, 0x358637bd, v2
	v_mul_f32_e32 v3, 0x4b800000, v2
	v_cmp_gt_f32_e32 vcc, s69, v2
	v_add3_u32 v18, s15, v39, v33
	v_or_b32_e32 v80, 10, v34
	v_cndmask_b32_e32 v2, v2, v3, vcc
	v_rsq_f32_e32 v48, v2
	global_load_dwordx4 v[2:5], v[22:23], off offset:1072
	global_load_dwordx4 v[6:9], v[22:23], off offset:1056
	v_or_b32_e32 v79, 11, v34
	v_readlane_b32 s40, v251, 22
	v_mul_f32_e32 v39, 0x45800000, v48
	v_cndmask_b32_e32 v39, v48, v39, vcc
	v_readlane_b32 s41, v251, 23
	v_mov_b32_e32 v21, v1
	v_mul_u32_u24_e32 v83, 0x110, v31
	v_add3_u32 v0, s15, v83, v0
	v_or_b32_e32 v100, 31, v34
	v_cmp_gt_u32_e32 vcc, v31, v34
	v_or_b32_e32 v35, 4, v34
	v_and_b32_e32 v32, 15, v50
	v_readlane_b32 s42, v251, 24
	v_readlane_b32 s43, v251, 25
	v_readlane_b32 s44, v251, 26
	v_readlane_b32 s45, v251, 27
	v_readlane_b32 s46, v251, 28
	v_readlane_b32 s47, v251, 29
	v_readlane_b32 s48, v251, 30
	v_readlane_b32 s49, v251, 31
	v_readlane_b32 s50, v251, 32
	v_readlane_b32 s51, v251, 33
	v_readlane_b32 s52, v251, 34
	v_readlane_b32 s53, v251, 35
	v_readlane_b32 s54, v251, 36
	v_readlane_b32 s55, v251, 37
	s_mov_b32 s2, 0x1f000
	s_waitcnt vmcnt(11)
	v_lshlrev_b32_e32 v48, 16, v10
	v_and_b32_e32 v10, 0xffff0000, v10
	v_lshlrev_b32_e32 v49, 16, v11
	v_and_b32_e32 v11, 0xffff0000, v11
	v_mul_f32_e32 v52, v48, v48
	v_mul_f32_e32 v53, v10, v10
	v_mul_f32_e32 v55, v11, v11
	v_fmamk_f32 v52, v52, 0xbdd2d3e7, v129
	v_fmamk_f32 v53, v53, 0xbdd2d3e7, v129
	v_fmamk_f32 v55, v55, 0xbdd2d3e7, v129
	v_mul_f32_e32 v52, v52, v48
	v_mul_f32_e32 v53, v53, v10
	v_mul_f32_e32 v55, v55, v11
	v_exp_f32_e32 v52, v52
	v_exp_f32_e32 v53, v53
	v_exp_f32_e32 v55, v55
	v_lshlrev_b32_e32 v51, 16, v12
	v_add_f32_e32 v52, 1.0, v52
	v_add_f32_e32 v53, 1.0, v53
	v_add_f32_e32 v55, 1.0, v55
	v_rcp_f32_e32 v52, v52
	v_mul_f32_e32 v56, v51, v51
	v_rcp_f32_e32 v53, v53
	v_rcp_f32_e32 v55, v55
	v_fmamk_f32 v56, v56, 0xbdd2d3e7, v129
	v_mul_f32_e32 v56, v56, v51
	v_fma_f32 v48, v52, v48, -v19
	v_and_b32_e32 v12, 0xffff0000, v12
	v_fma_f32 v10, v53, v10, -v19
	v_fma_f32 v11, v55, v11, -v19
	v_mul_f32_e32 v48, v39, v48
	v_mul_f32_e32 v57, 0x3d372713, v12
	v_exp_f32_e32 v56, v56
	v_mul_f32_e32 v10, v39, v10
	v_mul_f32_e32 v59, v39, v11
	s_waitcnt vmcnt(9)
	v_fma_f32 v11, v28, v48, v36
	v_mul_f32_e32 v57, v57, v12
	v_fmac_f32_e32 v37, v29, v10
	v_cvt_pk_bf16_f32 v10, v11, s0
	v_cvt_pk_bf16_f32 v11, v37, s0
	ds_write_b16 v38, v10 offset:34816
	ds_write_b16 v18, v11 offset:34816
	v_fma_f32 v10, v57, v12, v12
	v_mul_f32_e32 v10, 0xbfcc422a, v10
	v_lshlrev_b32_e32 v28, 16, v13
	v_add_f32_e32 v56, 1.0, v56
	v_mul_f32_e32 v10, 0x3fb8aa3b, v10
	v_mul_f32_e32 v29, v28, v28
	v_rcp_f32_e32 v56, v56
	v_exp_f32_e32 v10, v10
	v_fmamk_f32 v29, v29, 0xbdd2d3e7, v129
	v_mul_f32_e32 v29, v29, v28
	v_fma_f32 v51, v56, v51, -v19
	v_add_f32_e32 v10, 1.0, v10
	v_exp_f32_e32 v29, v29
	v_mul_f32_e32 v11, v39, v51
	v_rcp_f32_e32 v10, v10
	s_waitcnt vmcnt(5)
	v_fma_f32 v11, v40, v11, v44
	v_cvt_pk_bf16_f32 v11, v11, s0
	ds_write_b16 v18, v11 offset:35632
	v_add_f32_e32 v11, 1.0, v29
	v_fma_f32 v10, v10, v12, -v19
	v_rcp_f32_e32 v11, v11
	v_mul_f32_e32 v10, v39, v10
	v_fmac_f32_e32 v45, v10, v41
	v_cvt_pk_bf16_f32 v10, v45, s0
	ds_write_b16 v18, v10 offset:35904
	v_fma_f32 v10, v11, v28, -v19
	v_and_b32_e32 v11, 0xffff0000, v13
	v_mul_f32_e32 v12, v11, v11
	v_fmamk_f32 v12, v12, 0xbdd2d3e7, v129
	v_mul_f32_e32 v12, v12, v11
	v_exp_f32_e32 v12, v12
	s_waitcnt vmcnt(2)
	v_lshlrev_b32_e32 v13, 16, v14
	v_mul_f32_e32 v28, v13, v13
	v_fmamk_f32 v28, v28, 0xbdd2d3e7, v129
	v_add_f32_e32 v12, 1.0, v12
	v_rcp_f32_e32 v12, v12
	v_mul_f32_e32 v28, v28, v13
	v_fma_f32 v11, v12, v11, -v19
	v_exp_f32_e32 v28, v28
	v_mul_f32_e32 v44, v39, v11
	v_and_b32_e32 v11, 0xffff0000, v14
	v_mul_f32_e32 v12, v11, v11
	v_fmamk_f32 v12, v12, 0xbdd2d3e7, v129
	v_mul_f32_e32 v12, v12, v11
	v_mul_f32_e32 v45, v39, v10
	v_add_f32_e32 v10, 1.0, v28
	v_rcp_f32_e32 v10, v10
	v_exp_f32_e32 v12, v12
	v_lshlrev_b32_e32 v29, 16, v16
	v_fma_f32 v10, v10, v13, -v19
	v_lshlrev_b32_e32 v13, 16, v15
	v_add_f32_e32 v12, 1.0, v12
	v_mul_f32_e32 v14, v13, v13
	v_rcp_f32_e32 v12, v12
	v_fmamk_f32 v14, v14, 0xbdd2d3e7, v129
	v_mul_f32_e32 v10, v39, v10
	v_mul_f32_e32 v14, v14, v13
	v_fma_f32 v10, v42, v10, v46
	v_cvt_pk_bf16_f32 v10, v10, s0
	v_exp_f32_e32 v14, v14
	ds_write_b16 v18, v10 offset:36720
	v_fma_f32 v10, v12, v11, -v19
	v_mul_f32_e32 v10, v39, v10
	v_fmac_f32_e32 v47, v43, v10
	v_cvt_pk_bf16_f32 v10, v47, s0
	v_and_b32_e32 v15, 0xffff0000, v15
	v_add_f32_e32 v11, 1.0, v14
	ds_write_b16 v18, v10 offset:36992
	v_mul_f32_e32 v10, v15, v15
	v_rcp_f32_e32 v11, v11
	v_fmamk_f32 v10, v10, 0xbdd2d3e7, v129
	v_mul_f32_e32 v10, v10, v15
	v_fma_f32 v14, v11, v13, -v19
	v_exp_f32_e32 v28, v10
	global_load_dwordx2 v[10:11], v20, s[16:17] offset:64
	global_load_dwordx2 v[12:13], v20, s[20:21] offset:64
	v_mul_f32_e32 v37, v29, v29
	v_fmamk_f32 v37, v37, 0xbdd2d3e7, v129
	v_add_f32_e32 v28, 1.0, v28
	v_mul_f32_e32 v37, v37, v29
	v_rcp_f32_e32 v28, v28
	v_exp_f32_e32 v37, v37
	v_fma_f32 v15, v28, v15, -v19
	v_mul_f32_e32 v46, v39, v15
	v_and_b32_e32 v15, 0xffff0000, v16
	v_mul_f32_e32 v16, v15, v15
	v_mul_f32_e32 v47, v39, v14
	v_add_f32_e32 v14, 1.0, v37
	v_fmamk_f32 v16, v16, 0xbdd2d3e7, v129
	v_rcp_f32_e32 v14, v14
	v_mul_f32_e32 v16, v16, v15
	v_exp_f32_e32 v16, v16
	v_fma_f32 v14, v14, v29, -v19
	v_mul_f32_e32 v14, v39, v14
	v_fma_f32 v14, v24, v14, v26
	v_lshlrev_b32_e32 v24, 16, v17
	v_add_f32_e32 v16, 1.0, v16
	v_mul_f32_e32 v26, v24, v24
	v_rcp_f32_e32 v16, v16
	v_fmamk_f32 v26, v26, 0xbdd2d3e7, v129
	v_mul_f32_e32 v26, v26, v24
	v_cvt_pk_bf16_f32 v14, v14, s0
	v_exp_f32_e32 v26, v26
	ds_write_b16 v18, v14 offset:37808
	v_fma_f32 v14, v16, v15, -v19
	v_mul_f32_e32 v14, v39, v14
	v_fmac_f32_e32 v27, v14, v25
	v_cvt_pk_bf16_f32 v14, v27, s0
	v_and_b32_e32 v25, 0xffff0000, v17
	v_add_f32_e32 v15, 1.0, v26
	ds_write_b16 v18, v14 offset:38080
	v_mul_f32_e32 v14, v25, v25
	v_rcp_f32_e32 v15, v15
	v_fmamk_f32 v14, v14, 0xbdd2d3e7, v129
	v_mul_f32_e32 v14, v14, v25
	v_fma_f32 v24, v15, v24, -v19
	v_exp_f32_e32 v26, v14
	global_load_dwordx2 v[14:15], v20, s[16:17] offset:80
	global_load_dwordx2 v[16:17], v20, s[20:21] offset:80
	s_waitcnt vmcnt(4)
	v_lshlrev_b32_e32 v27, 16, v6
	v_mul_f32_e32 v28, v27, v27
	v_fmamk_f32 v28, v28, 0xbdd2d3e7, v129
	v_mul_f32_e32 v28, v28, v27
	v_exp_f32_e32 v28, v28
	v_mul_f32_e32 v55, v39, v24
	v_mul_f32_e32 v54, v49, v49
	v_fmamk_f32 v54, v54, 0xbdd2d3e7, v129
	v_add_f32_e32 v24, 1.0, v28
	v_rcp_f32_e32 v24, v24
	v_and_b32_e32 v6, 0xffff0000, v6
	v_mul_f32_e32 v54, v54, v49
	v_fma_f32 v24, v24, v27, -v19
	v_mul_f32_e32 v40, v39, v24
	v_mul_f32_e32 v24, v6, v6
	v_fmamk_f32 v24, v24, 0xbdd2d3e7, v129
	v_mul_f32_e32 v24, v24, v6
	v_exp_f32_e32 v54, v54
	v_exp_f32_e32 v41, v24
	v_add_f32_e32 v54, 1.0, v54
	v_add_f32_e32 v26, 1.0, v26
	v_rcp_f32_e32 v54, v54
	v_rcp_f32_e32 v26, v26
	s_waitcnt vmcnt(2)
	v_fma_f32 v10, v10, v40, v12
	v_lshlrev_b32_e32 v40, 16, v7
	v_add_f32_e32 v12, 1.0, v41
	v_mul_f32_e32 v41, v40, v40
	v_fmamk_f32 v41, v41, 0xbdd2d3e7, v129
	v_mul_f32_e32 v41, v41, v40
	v_fma_f32 v49, v54, v49, -v19
	v_fma_f32 v25, v26, v25, -v19
	v_mul_f32_e32 v65, v39, v49
	v_mul_f32_e32 v54, v39, v25
	global_load_dwordx2 v[24:25], v20, s[16:17] offset:96
	global_load_dwordx2 v[28:29], v20, s[16:17] offset:112
	global_load_dwordx2 v[26:27], v20, s[20:21] offset:96
	global_load_dwordx2 v[48:49], v20, s[20:21] offset:112
	v_exp_f32_e32 v41, v41
	v_rcp_f32_e32 v12, v12
	v_cvt_pk_bf16_f32 v10, v10, s0
	ds_write_b16 v18, v10 offset:38896
	v_add_f32_e32 v10, 1.0, v41
	v_fma_f32 v6, v12, v6, -v19
	v_rcp_f32_e32 v10, v10
	v_mul_f32_e32 v6, v39, v6
	v_fmac_f32_e32 v13, v11, v6
	v_cvt_pk_bf16_f32 v6, v13, s0
	v_and_b32_e32 v7, 0xffff0000, v7
	ds_write_b16 v18, v6 offset:39168
	v_fma_f32 v6, v10, v40, -v19
	v_mul_f32_e32 v10, v7, v7
	v_fmamk_f32 v10, v10, 0xbdd2d3e7, v129
	v_mul_f32_e32 v10, v10, v7
	v_exp_f32_e32 v10, v10
	v_lshlrev_b32_e32 v11, 16, v8
	v_mul_f32_e32 v12, v11, v11
	v_fmamk_f32 v12, v12, 0xbdd2d3e7, v129
	v_mul_f32_e32 v12, v12, v11
	v_add_f32_e32 v10, 1.0, v10
	v_rcp_f32_e32 v10, v10
	v_exp_f32_e32 v12, v12
	v_mul_f32_e32 v53, v39, v6
	v_fma_f32 v7, v10, v7, -v19
	v_mul_f32_e32 v52, v39, v7
	v_and_b32_e32 v7, 0xffff0000, v8
	v_add_f32_e32 v6, 1.0, v12
	v_mul_f32_e32 v8, v7, v7
	v_rcp_f32_e32 v6, v6
	v_fmamk_f32 v8, v8, 0xbdd2d3e7, v129
	v_mul_f32_e32 v8, v8, v7
	v_lshlrev_b32_e32 v10, 16, v9
	v_fma_f32 v6, v6, v11, -v19
	v_exp_f32_e32 v8, v8
	v_mul_f32_e32 v11, v10, v10
	v_fmamk_f32 v11, v11, 0xbdd2d3e7, v129
	v_mul_f32_e32 v11, v11, v10
	v_add_f32_e32 v8, 1.0, v8
	v_rcp_f32_e32 v8, v8
	v_exp_f32_e32 v11, v11
	v_mul_f32_e32 v6, v39, v6
	s_waitcnt vmcnt(4)
	v_fma_f32 v6, v14, v6, v16
	v_cvt_pk_bf16_f32 v6, v6, s0
	ds_write_b16 v18, v6 offset:39984
	v_fma_f32 v6, v8, v7, -v19
	v_add_f32_e32 v7, 1.0, v11
	v_rcp_f32_e32 v7, v7
	v_mul_f32_e32 v6, v39, v6
	v_fmac_f32_e32 v17, v6, v15
	v_cvt_pk_bf16_f32 v6, v17, s0
	ds_write_b16 v18, v6 offset:40256
	v_fma_f32 v6, v7, v10, -v19
	v_and_b32_e32 v7, 0xffff0000, v9
	v_lshlrev_b32_e32 v9, 16, v2
	v_mul_f32_e32 v10, v9, v9
	v_fmamk_f32 v10, v10, 0xbdd2d3e7, v129
	v_mul_f32_e32 v8, v7, v7
	v_mul_f32_e32 v10, v10, v9
	v_fmamk_f32 v8, v8, 0xbdd2d3e7, v129
	v_mul_f32_e32 v8, v8, v7
	v_exp_f32_e32 v10, v10
	v_exp_f32_e32 v8, v8
	v_mul_f32_e32 v58, v39, v6
	v_add_f32_e32 v6, 1.0, v10
	global_load_dwordx4 v[10:13], v[22:23], off offset:1104
	global_load_dwordx4 v[14:17], v[22:23], off offset:1088
	v_add_f32_e32 v8, 1.0, v8
	v_rcp_f32_e32 v8, v8
	v_and_b32_e32 v2, 0xffff0000, v2
	v_rcp_f32_e32 v6, v6
	v_or_b32_e32 v36, 8, v34
	v_fma_f32 v7, v8, v7, -v19
	v_mul_f32_e32 v56, v39, v7
	v_mul_f32_e32 v7, v2, v2
	v_fmamk_f32 v7, v7, 0xbdd2d3e7, v129
	v_mul_f32_e32 v7, v7, v2
	v_exp_f32_e32 v7, v7
	v_lshlrev_b32_e32 v8, 16, v3
	v_fma_f32 v6, v6, v9, -v19
	v_mul_f32_e32 v9, v8, v8
	v_add_f32_e32 v7, 1.0, v7
	v_rcp_f32_e32 v7, v7
	v_fmamk_f32 v9, v9, 0xbdd2d3e7, v129
	v_mul_f32_e32 v9, v9, v8
	v_fma_f32 v2, v7, v2, -v19
	v_mul_f32_e32 v6, v39, v6
	v_mul_f32_e32 v2, v39, v2
	s_waitcnt vmcnt(3)
	v_fma_f32 v6, v24, v6, v26
	v_exp_f32_e32 v9, v9
	v_fmac_f32_e32 v27, v25, v2
	v_cvt_pk_bf16_f32 v6, v6, s0
	v_cvt_pk_bf16_f32 v2, v27, s0
	ds_write_b16 v18, v6 offset:41072
	ds_write_b16 v18, v2 offset:41344
	global_load_dwordx2 v[24:25], v20, s[16:17] offset:128
	global_load_dwordx2 v[26:27], v20, s[20:21] offset:128
	v_add_f32_e32 v6, 1.0, v9
	v_rcp_f32_e32 v6, v6
	v_and_b32_e32 v3, 0xffff0000, v3
	v_lshlrev_b32_e32 v7, 16, v4
	v_or_b32_e32 v37, 12, v34
	v_fma_f32 v2, v6, v8, -v19
	v_mul_f32_e32 v6, v3, v3
	v_fmamk_f32 v6, v6, 0xbdd2d3e7, v129
	v_mul_f32_e32 v6, v6, v3
	v_exp_f32_e32 v6, v6
	v_mul_f32_e32 v8, v7, v7
	v_fmamk_f32 v8, v8, 0xbdd2d3e7, v129
	v_mul_f32_e32 v8, v8, v7
	v_add_f32_e32 v6, 1.0, v6
	v_rcp_f32_e32 v6, v6
	v_exp_f32_e32 v8, v8
	v_mul_f32_e32 v64, v39, v2
	v_fma_f32 v3, v6, v3, -v19
	v_mul_f32_e32 v63, v39, v3
	v_and_b32_e32 v3, 0xffff0000, v4
	v_add_f32_e32 v2, 1.0, v8
	v_mul_f32_e32 v4, v3, v3
	v_rcp_f32_e32 v2, v2
	v_fmamk_f32 v4, v4, 0xbdd2d3e7, v129
	v_mul_f32_e32 v4, v4, v3
	v_fma_f32 v2, v2, v7, -v19
	v_exp_f32_e32 v4, v4
	v_mul_f32_e32 v2, v39, v2
	s_waitcnt vmcnt(4)
	v_fma_f32 v2, v28, v2, v48
	v_cvt_pk_bf16_f32 v2, v2, s0
	ds_write_b16 v18, v2 offset:42160
	v_add_f32_e32 v2, 1.0, v4
	v_lshlrev_b32_e32 v4, 16, v5
	v_mul_f32_e32 v6, v4, v4
	v_fmamk_f32 v6, v6, 0xbdd2d3e7, v129
	v_rcp_f32_e32 v2, v2
	v_mul_f32_e32 v6, v6, v4
	v_exp_f32_e32 v6, v6
	v_fma_f32 v2, v2, v3, -v19
	v_mul_f32_e32 v2, v39, v2
	v_fmac_f32_e32 v49, v2, v29
	v_add_f32_e32 v2, 1.0, v6
	v_cvt_pk_bf16_f32 v6, v49, s0
	ds_write_b16 v18, v6 offset:42432
	global_load_dwordx2 v[60:61], v20, s[16:17] offset:144
	global_load_dwordx2 v[66:67], v20, s[20:21] offset:144
	v_and_b32_e32 v3, 0xffff0000, v5
	v_mul_f32_e32 v5, v3, v3
	v_fmamk_f32 v5, v5, 0xbdd2d3e7, v129
	v_mul_f32_e32 v5, v5, v3
	v_rcp_f32_e32 v2, v2
	v_exp_f32_e32 v5, v5
	s_waitcnt vmcnt(4)
	v_lshlrev_b32_e32 v28, 16, v14
	v_and_b32_e32 v14, 0xffff0000, v14
	v_fma_f32 v2, v2, v4, -v19
	v_add_f32_e32 v4, 1.0, v5
	v_mul_f32_e32 v5, v28, v28
	v_fmamk_f32 v5, v5, 0xbdd2d3e7, v129
	v_mul_f32_e32 v5, v5, v28
	v_rcp_f32_e32 v4, v4
	v_exp_f32_e32 v5, v5
	v_mul_f32_e32 v69, v39, v2
	v_fma_f32 v2, v4, v3, -v19
	v_mul_f32_e32 v68, v39, v2
	v_add_f32_e32 v2, 1.0, v5
	v_rcp_f32_e32 v29, v2
	global_load_dwordx4 v[2:5], v[22:23], off offset:1136
	global_load_dwordx4 v[6:9], v[22:23], off offset:1120
	v_or_b32_e32 v38, 16, v34
	v_or_b32_e32 v40, 20, v34
	v_fma_f32 v22, v29, v28, -v19
	v_mul_f32_e32 v48, v39, v22
	v_mul_f32_e32 v22, v14, v14
	v_fmamk_f32 v22, v22, 0xbdd2d3e7, v129
	v_mul_f32_e32 v22, v22, v14
	v_exp_f32_e32 v49, v22
	global_load_dwordx2 v[74:75], v20, s[16:17] offset:160
	global_load_dwordx2 v[22:23], v20, s[16:17] offset:176
	global_load_dwordx2 v[76:77], v20, s[20:21] offset:160
	global_load_dwordx2 v[28:29], v20, s[20:21] offset:176
	s_waitcnt vmcnt(8)
	v_fma_f32 v24, v24, v48, v26
	v_lshlrev_b32_e32 v48, 16, v15
	v_add_f32_e32 v26, 1.0, v49
	v_mul_f32_e32 v49, v48, v48
	v_fmamk_f32 v49, v49, 0xbdd2d3e7, v129
	v_mul_f32_e32 v49, v49, v48
	v_exp_f32_e32 v49, v49
	v_rcp_f32_e32 v26, v26
	v_cvt_pk_bf16_f32 v24, v24, s0
	ds_write_b16 v18, v24 offset:43248
	v_add_f32_e32 v24, 1.0, v49
	v_fma_f32 v14, v26, v14, -v19
	v_rcp_f32_e32 v24, v24
	v_mul_f32_e32 v14, v39, v14
	v_fmac_f32_e32 v27, v25, v14
	v_cvt_pk_bf16_f32 v14, v27, s0
	v_and_b32_e32 v15, 0xffff0000, v15
	ds_write_b16 v18, v14 offset:43520
	v_fma_f32 v14, v24, v48, -v19
	v_mul_f32_e32 v24, v15, v15
	v_fmamk_f32 v24, v24, 0xbdd2d3e7, v129
	v_mul_f32_e32 v24, v24, v15
	v_exp_f32_e32 v24, v24
	v_lshlrev_b32_e32 v25, 16, v16
	v_mul_f32_e32 v26, v25, v25
	v_fmamk_f32 v26, v26, 0xbdd2d3e7, v129
	v_mul_f32_e32 v26, v26, v25
	v_add_f32_e32 v24, 1.0, v24
	v_rcp_f32_e32 v24, v24
	v_exp_f32_e32 v26, v26
	v_mul_f32_e32 v73, v39, v14
	v_fma_f32 v15, v24, v15, -v19
	v_mul_f32_e32 v72, v39, v15
	v_and_b32_e32 v15, 0xffff0000, v16
	v_add_f32_e32 v14, 1.0, v26
	v_mul_f32_e32 v16, v15, v15
	v_rcp_f32_e32 v14, v14
	v_fmamk_f32 v16, v16, 0xbdd2d3e7, v129
	v_mul_f32_e32 v16, v16, v15
	v_lshlrev_b32_e32 v24, 16, v17
	v_fma_f32 v14, v14, v25, -v19
	v_exp_f32_e32 v16, v16
	v_mul_f32_e32 v25, v24, v24
	v_fmamk_f32 v25, v25, 0xbdd2d3e7, v129
	v_mul_f32_e32 v25, v25, v24
	v_add_f32_e32 v16, 1.0, v16
	v_rcp_f32_e32 v16, v16
	v_exp_f32_e32 v25, v25
	v_mul_f32_e32 v14, v39, v14
	s_waitcnt vmcnt(6)
	v_fma_f32 v14, v60, v14, v66
	v_cvt_pk_bf16_f32 v14, v14, s0
	ds_write_b16 v18, v14 offset:44336
	v_fma_f32 v14, v16, v15, -v19
	v_add_f32_e32 v15, 1.0, v25
	v_rcp_f32_e32 v15, v15
	v_mul_f32_e32 v14, v39, v14
	v_fmac_f32_e32 v67, v14, v61
	v_cvt_pk_bf16_f32 v14, v67, s0
	ds_write_b16 v18, v14 offset:44608
	v_fma_f32 v14, v15, v24, -v19
	v_and_b32_e32 v15, 0xffff0000, v17
	v_mul_f32_e32 v16, v15, v15
	v_fmamk_f32 v16, v16, 0xbdd2d3e7, v129
	v_mul_f32_e32 v16, v16, v15
	v_exp_f32_e32 v16, v16
	v_lshlrev_b32_e32 v17, 16, v10
	v_mul_f32_e32 v24, v17, v17
	v_fmamk_f32 v24, v24, 0xbdd2d3e7, v129
	v_mul_f32_e32 v24, v24, v17
	v_add_f32_e32 v16, 1.0, v16
	v_rcp_f32_e32 v16, v16
	v_exp_f32_e32 v24, v24
	v_and_b32_e32 v10, 0xffff0000, v10
	v_mul_f32_e32 v71, v39, v14
	v_fma_f32 v15, v16, v15, -v19
	v_add_f32_e32 v14, 1.0, v24
	v_mul_f32_e32 v70, v39, v15
	v_mul_f32_e32 v15, v10, v10
	v_rcp_f32_e32 v14, v14
	v_fmamk_f32 v15, v15, 0xbdd2d3e7, v129
	v_mul_f32_e32 v15, v15, v10
	v_fma_f32 v14, v14, v17, -v19
	v_exp_f32_e32 v15, v15
	v_mul_f32_e32 v14, v39, v14
	s_waitcnt vmcnt(1)
	v_fma_f32 v14, v74, v14, v76
	v_cvt_pk_bf16_f32 v14, v14, s0
	ds_write_b16 v18, v14 offset:45424
	v_add_f32_e32 v14, 1.0, v15
	v_lshlrev_b32_e32 v15, 16, v11
	v_rcp_f32_e32 v14, v14
	v_mul_f32_e32 v16, v15, v15
	v_fmamk_f32 v16, v16, 0xbdd2d3e7, v129
	v_mul_f32_e32 v16, v16, v15
	v_and_b32_e32 v11, 0xffff0000, v11
	v_fma_f32 v10, v14, v10, -v19
	v_mul_f32_e32 v14, v11, v11
	v_exp_f32_e32 v16, v16
	v_fmamk_f32 v14, v14, 0xbdd2d3e7, v129
	v_mul_f32_e32 v14, v14, v11
	v_mul_f32_e32 v10, v39, v10
	v_fmac_f32_e32 v77, v75, v10
	v_add_f32_e32 v10, 1.0, v16
	v_exp_f32_e32 v14, v14
	v_rcp_f32_e32 v10, v10
	v_cvt_pk_bf16_f32 v16, v77, s0
	ds_write_b16 v18, v16 offset:45696
	v_add_f32_e32 v14, 1.0, v14
	v_fma_f32 v10, v10, v15, -v19
	v_rcp_f32_e32 v14, v14
	v_lshlrev_b32_e32 v15, 16, v12
	v_mul_f32_e32 v16, v15, v15
	v_fmamk_f32 v16, v16, 0xbdd2d3e7, v129
	v_mul_f32_e32 v16, v16, v15
	v_mul_f32_e32 v67, v39, v10
	v_fma_f32 v10, v14, v11, -v19
	v_and_b32_e32 v11, 0xffff0000, v12
	v_mul_f32_e32 v12, v11, v11
	v_exp_f32_e32 v16, v16
	v_fmamk_f32 v12, v12, 0xbdd2d3e7, v129
	v_mul_f32_e32 v12, v12, v11
	v_mul_f32_e32 v66, v39, v10
	v_add_f32_e32 v10, 1.0, v16
	v_exp_f32_e32 v12, v12
	v_rcp_f32_e32 v10, v10
	v_or_b32_e32 v76, 2, v34
	v_or_b32_e32 v77, 3, v34
	v_add_f32_e32 v12, 1.0, v12
	v_fma_f32 v10, v10, v15, -v19
	v_rcp_f32_e32 v12, v12
	v_mul_f32_e32 v10, v39, v10
	s_waitcnt vmcnt(0)
	v_fma_f32 v10, v22, v10, v28
	v_cvt_pk_bf16_f32 v10, v10, s0
	ds_write_b16 v18, v10 offset:46512
	v_fma_f32 v10, v12, v11, -v19
	v_lshlrev_b32_e32 v11, 16, v13
	v_mul_f32_e32 v12, v11, v11
	v_fmamk_f32 v12, v12, 0xbdd2d3e7, v129
	v_mul_f32_e32 v12, v12, v11
	v_exp_f32_e32 v12, v12
	v_mul_f32_e32 v10, v39, v10
	v_fmac_f32_e32 v29, v10, v23
	v_lshlrev_b32_e32 v14, 2, v76
	v_add_f32_e32 v12, 1.0, v12
	v_rcp_f32_e32 v12, v12
	v_cvt_pk_bf16_f32 v10, v29, s0
	v_lshlrev_b32_e32 v16, 2, v77
	global_load_dword v15, v14, s[16:17]
	s_nop 0
	global_load_dword v14, v14, s[20:21]
	s_nop 0
	global_load_dword v17, v16, s[16:17]
	s_nop 0
	global_load_dword v16, v16, s[20:21]
	ds_write_b16 v18, v10 offset:46784
	v_fma_f32 v10, v12, v11, -v19
	v_and_b32_e32 v11, 0xffff0000, v13
	v_lshlrev_b32_e32 v13, 16, v6
	v_mul_f32_e32 v22, v13, v13
	v_fmamk_f32 v22, v22, 0xbdd2d3e7, v129
	v_mul_f32_e32 v22, v22, v13
	v_mul_f32_e32 v12, v11, v11
	v_fmamk_f32 v12, v12, 0xbdd2d3e7, v129
	v_exp_f32_e32 v22, v22
	v_mul_f32_e32 v12, v12, v11
	v_exp_f32_e32 v12, v12
	v_mul_f32_e32 v75, v39, v10
	v_add_f32_e32 v10, 1.0, v22
	v_rcp_f32_e32 v10, v10
	v_add_f32_e32 v12, 1.0, v12
	v_and_b32_e32 v6, 0xffff0000, v6
	v_rcp_f32_e32 v12, v12
	v_fma_f32 v22, v10, v13, -v19
	v_mul_f32_e32 v10, v6, v6
	v_fmamk_f32 v10, v10, 0xbdd2d3e7, v129
	v_mul_f32_e32 v10, v10, v6
	v_fma_f32 v11, v12, v11, -v19
	v_mul_f32_e32 v74, v39, v11
	v_exp_f32_e32 v23, v10
	global_load_dwordx2 v[10:11], v20, s[16:17] offset:192
	global_load_dwordx2 v[12:13], v20, s[20:21] offset:192
	v_mul_f32_e32 v81, v39, v22
	v_lshlrev_b32_e32 v90, 16, v8
	v_add_f32_e32 v22, 1.0, v23
	v_lshlrev_b32_e32 v23, 16, v7
	v_mul_f32_e32 v24, v23, v23
	v_and_b32_e32 v7, 0xffff0000, v7
	v_fmamk_f32 v24, v24, 0xbdd2d3e7, v129
	v_mul_f32_e32 v25, v7, v7
	v_mul_f32_e32 v24, v24, v23
	v_fmamk_f32 v25, v25, 0xbdd2d3e7, v129
	v_mul_f32_e32 v25, v25, v7
	v_rcp_f32_e32 v22, v22
	v_exp_f32_e32 v24, v24
	v_exp_f32_e32 v25, v25
	v_fma_f32 v6, v22, v6, -v19
	v_add_f32_e32 v22, 1.0, v24
	v_rcp_f32_e32 v22, v22
	v_add_f32_e32 v24, 1.0, v25
	v_rcp_f32_e32 v24, v24
	v_mul_f32_e32 v82, v39, v6
	v_fma_f32 v6, v22, v23, -v19
	v_mul_f32_e32 v62, v39, v6
	v_fma_f32 v6, v24, v7, -v19
	v_mul_f32_e32 v61, v39, v6
	v_or_b32_e32 v6, s88, v31
	v_lshlrev_b32_e32 v6, 7, v6
	v_mov_b32_e32 v7, v1
	v_lshl_add_u64 v[6:7], v[6:7], 2, s[40:41]
	v_lshl_add_u64 v[6:7], v[6:7], 0, v[20:21]
	v_and_b32_e32 v8, 0xffff0000, v8
	v_mul_f32_e32 v97, v8, v8
	v_fmamk_f32 v97, v97, 0xbdd2d3e7, v129
	v_mul_f32_e32 v97, v97, v8
	v_exp_f32_e32 v97, v97
	v_and_b32_e32 v98, 0xffff0000, v9
	v_and_b32_e32 v104, 0xffff0000, v5
	v_or_b32_e32 v41, 24, v34
	v_or_b32_e32 v42, 28, v34
	v_or_b32_e32 v43, 32, v34
	v_or_b32_e32 v48, 36, v34
	s_waitcnt vmcnt(4)
	v_fmac_f32_e32 v14, v15, v65
	v_mul_u32_u24_e32 v15, 0x110, v76
	v_cvt_pk_bf16_f32 v14, v14, s0
	v_add3_u32 v15, s15, v15, v33
	v_or_b32_e32 v65, 6, v34
	ds_write_b16 v15, v14 offset:34816
	v_lshlrev_b32_e32 v14, 2, v65
	global_load_dword v84, v14, s[16:17]
	global_load_dword v85, v14, s[20:21]
	s_waitcnt vmcnt(4)
	v_fmac_f32_e32 v16, v17, v59
	v_lshlrev_b32_e32 v14, 2, v78
	v_mul_u32_u24_e32 v15, 0x110, v77
	global_load_dword v86, v14, s[16:17]
	global_load_dword v87, v14, s[20:21]
	v_cvt_pk_bf16_f32 v14, v16, s0
	v_add3_u32 v15, s15, v15, v33
	ds_write_b16 v15, v14 offset:34816
	v_lshlrev_b32_e32 v14, 2, v80
	global_load_dwordx2 v[22:23], v20, s[16:17] offset:208
	global_load_dwordx2 v[24:25], v20, s[20:21] offset:208
	global_load_dword v88, v14, s[16:17]
	global_load_dword v89, v14, s[20:21]
	v_lshlrev_b32_e32 v14, 2, v79
	global_load_dword v91, v14, s[16:17]
	global_load_dword v92, v14, s[20:21]
	v_mul_f32_e32 v14, v90, v90
	v_fmamk_f32 v14, v14, 0xbdd2d3e7, v129
	v_mul_f32_e32 v14, v14, v90
	v_or_b32_e32 v59, 14, v34
	v_lshlrev_b32_e32 v15, 2, v59
	global_load_dword v93, v15, s[16:17]
	global_load_dword v94, v15, s[20:21]
	v_exp_f32_e32 v95, v14
	global_load_dwordx2 v[14:15], v20, s[16:17] offset:224
	global_load_dwordx2 v[16:17], v20, s[16:17] offset:240
	global_load_dwordx2 v[26:27], v20, s[20:21] offset:224
	s_nop 0
	global_load_dwordx2 v[20:21], v20, s[20:21] offset:240
	v_or_b32_e32 v49, 40, v34
	v_or_b32_e32 v51, 44, v34
	v_or_b32_e32 v57, 48, v34
	s_waitcnt vmcnt(16)
	v_fma_f32 v10, v10, v81, v12
	v_cvt_pk_bf16_f32 v12, v10, s0
	v_or_b32_e32 v10, 15, v34
	v_add_f32_e32 v81, 1.0, v95
	v_lshlrev_b32_e32 v95, 2, v10
	global_load_dword v96, v95, s[16:17]
	s_nop 0
	global_load_dword v95, v95, s[20:21]
	v_rcp_f32_e32 v81, v81
	ds_write_b16 v18, v12 offset:47600
	v_fmac_f32_e32 v13, v11, v82
	v_cvt_pk_bf16_f32 v11, v13, s0
	v_fma_f32 v12, v81, v90, -v19
	v_lshlrev_b32_e32 v90, 16, v9
	v_add_f32_e32 v81, 1.0, v97
	v_mul_f32_e32 v97, v90, v90
	v_fmamk_f32 v97, v97, 0xbdd2d3e7, v129
	v_mul_f32_e32 v97, v97, v90
	v_rcp_f32_e32 v81, v81
	v_exp_f32_e32 v97, v97
	v_mul_f32_e32 v12, v39, v12
	v_mul_u32_u24_e32 v13, 0x110, v80
	v_fma_f32 v8, v81, v8, -v19
	v_add_f32_e32 v81, 1.0, v97
	v_rcp_f32_e32 v81, v81
	v_mul_f32_e32 v99, v39, v8
	v_add3_u32 v13, s15, v13, v33
	v_mul_f32_e32 v9, v98, v98
	v_fma_f32 v8, v81, v90, -v19
	v_mul_u32_u24_e32 v81, 0x110, v65
	v_add3_u32 v81, s15, v81, v33
	v_fmamk_f32 v9, v9, 0xbdd2d3e7, v129
	v_mul_f32_e32 v9, v9, v98
	v_exp_f32_e32 v9, v9
	v_or_b32_e32 v90, 26, v34
	v_or_b32_e32 v60, 52, v34
	v_or_b32_e32 v29, 56, v34
	v_add_f32_e32 v9, 1.0, v9
	v_rcp_f32_e32 v97, v9
	v_mul_f32_e32 v9, v39, v8
	v_or_b32_e32 v28, 60, v34
	v_readlane_b32 s40, v251, 54
	v_fma_f32 v8, v97, v98, -v19
	v_or_b32_e32 v97, 30, v34
	v_mul_f32_e32 v8, v39, v8
	v_readlane_b32 s46, v251, 60
	v_readlane_b32 s47, v251, 61
	v_readlane_b32 s48, v251, 62
	v_readlane_b32 s49, v251, 63
	v_readlane_b32 s41, v251, 55
	v_readlane_b32 s42, v251, 56
	v_readlane_b32 s43, v251, 57
	s_waitcnt vmcnt(16)
	v_fmac_f32_e32 v85, v45, v84
	v_cvt_pk_bf16_f32 v45, v85, s0
	ds_write_b16 v81, v45 offset:34816
	v_mul_u32_u24_e32 v45, 0x110, v78
	s_waitcnt vmcnt(14)
	v_fmac_f32_e32 v87, v44, v86
	v_cvt_pk_bf16_f32 v44, v87, s0
	v_add3_u32 v45, s15, v45, v33
	ds_write_b16 v45, v44 offset:34816
	ds_write_b16 v18, v11 offset:47872
	s_waitcnt vmcnt(12)
	v_fma_f32 v11, v22, v12, v24
	s_waitcnt vmcnt(10)
	v_fmac_f32_e32 v89, v88, v47
	v_cvt_pk_bf16_f32 v12, v89, s0
	ds_write_b16 v13, v12 offset:34816
	s_waitcnt vmcnt(8)
	v_fmac_f32_e32 v92, v91, v46
	v_mul_u32_u24_e32 v13, 0x110, v79
	v_cvt_pk_bf16_f32 v12, v92, s0
	v_add3_u32 v13, s15, v13, v33
	v_cvt_pk_bf16_f32 v11, v11, s0
	ds_write_b16 v13, v12 offset:34816
	ds_write_b16 v18, v11 offset:48688
	v_lshlrev_b32_e32 v13, 16, v2
	v_mul_f32_e32 v22, v13, v13
	v_fmamk_f32 v22, v22, 0xbdd2d3e7, v129
	v_mul_f32_e32 v22, v22, v13
	v_exp_f32_e32 v22, v22
	v_fmac_f32_e32 v25, v99, v23
	v_cvt_pk_bf16_f32 v11, v25, s0
	s_waitcnt vmcnt(6)
	v_fmac_f32_e32 v94, v55, v93
	v_mul_u32_u24_e32 v12, 0x110, v59
	ds_write_b16 v18, v11 offset:48960
	v_cvt_pk_bf16_f32 v11, v94, s0
	v_add3_u32 v12, s15, v12, v33
	ds_write_b16 v12, v11 offset:34816
	v_add_f32_e32 v12, 1.0, v22
	v_rcp_f32_e32 v12, v12
	s_waitcnt vmcnt(0)
	v_fmac_f32_e32 v95, v54, v96
	v_mul_u32_u24_e32 v22, 0x110, v10
	v_cvt_pk_bf16_f32 v11, v95, s0
	v_add3_u32 v22, s15, v22, v33
	v_and_b32_e32 v2, 0xffff0000, v2
	ds_write_b16 v22, v11 offset:34816
	v_fma_f32 v11, v12, v13, -v19
	v_mul_f32_e32 v12, v2, v2
	v_lshlrev_b32_e32 v13, 16, v3
	v_fmamk_f32 v12, v12, 0xbdd2d3e7, v129
	v_mul_f32_e32 v22, v13, v13
	v_mul_f32_e32 v12, v12, v2
	v_fmamk_f32 v22, v22, 0xbdd2d3e7, v129
	v_mul_f32_e32 v22, v22, v13
	v_exp_f32_e32 v12, v12
	v_exp_f32_e32 v22, v22
	v_mul_f32_e32 v11, v39, v11
	v_add_f32_e32 v12, 1.0, v12
	v_fma_f32 v11, v14, v11, v26
	v_rcp_f32_e32 v12, v12
	v_add_f32_e32 v14, 1.0, v22
	v_rcp_f32_e32 v14, v14
	v_and_b32_e32 v3, 0xffff0000, v3
	v_fma_f32 v2, v12, v2, -v19
	v_mul_f32_e32 v12, v39, v2
	v_fma_f32 v2, v14, v13, -v19
	v_mul_f32_e32 v13, v3, v3
	v_fmamk_f32 v13, v13, 0xbdd2d3e7, v129
	v_mul_f32_e32 v13, v13, v3
	v_or_b32_e32 v81, 18, v34
	v_or_b32_e32 v86, 19, v34
	v_lshlrev_b32_e32 v14, 2, v81
	v_lshlrev_b32_e32 v22, 2, v86
	global_load_dword v26, v14, s[16:17]
	s_nop 0
	global_load_dword v14, v14, s[20:21]
	s_nop 0
	global_load_dword v54, v22, s[16:17]
	global_load_dword v55, v22, s[20:21]
	v_lshlrev_b32_e32 v22, 16, v4
	v_exp_f32_e32 v13, v13
	v_mul_f32_e32 v23, v22, v22
	v_fmamk_f32 v23, v23, 0xbdd2d3e7, v129
	v_mul_f32_e32 v23, v23, v22
	v_add_f32_e32 v13, 1.0, v13
	v_rcp_f32_e32 v13, v13
	v_exp_f32_e32 v23, v23
	v_or_b32_e32 v87, 22, v34
	v_lshlrev_b32_e32 v24, 2, v87
	v_fma_f32 v3, v13, v3, -v19
	v_add_f32_e32 v13, 1.0, v23
	global_load_dword v82, v24, s[16:17]
	global_load_dword v83, v24, s[20:21]
	v_or_b32_e32 v88, 23, v34
	v_rcp_f32_e32 v13, v13
	v_and_b32_e32 v4, 0xffff0000, v4
	v_lshlrev_b32_e32 v24, 2, v88
	v_mul_f32_e32 v23, v4, v4
	global_load_dword v84, v24, s[16:17]
	global_load_dword v85, v24, s[20:21]
	v_fmamk_f32 v23, v23, 0xbdd2d3e7, v129
	v_mul_f32_e32 v23, v23, v4
	v_fma_f32 v13, v13, v22, -v19
	v_lshlrev_b32_e32 v22, 2, v90
	global_load_dword v91, v22, s[16:17]
	global_load_dword v92, v22, s[20:21]
	v_or_b32_e32 v93, 27, v34
	v_exp_f32_e32 v23, v23
	v_lshlrev_b32_e32 v22, 2, v93
	global_load_dword v94, v22, s[16:17]
	global_load_dword v95, v22, s[20:21]
	v_lshlrev_b32_e32 v96, 16, v5
	v_lshlrev_b32_e32 v22, 2, v97
	global_load_dword v98, v22, s[16:17]
	global_load_dword v99, v22, s[20:21]
	v_mul_f32_e32 v22, 0x3d372713, v96
	v_mul_f32_e32 v89, v39, v13
	v_add_f32_e32 v13, 1.0, v23
	v_lshlrev_b32_e32 v23, 2, v100
	v_mul_f32_e32 v22, v22, v96
	global_load_dword v101, v23, s[16:17]
	global_load_dword v102, v23, s[20:21]
	v_fma_f32 v22, v22, v96, v96
	v_mul_f32_e32 v22, 0xbfcc422a, v22
	v_mul_f32_e32 v103, 0x3fb8aa3b, v22
	global_load_dwordx4 v[22:25], v[6:7], off offset:16
	global_load_dwordx4 v[44:47], v[6:7], off
	v_rcp_f32_e32 v13, v13
	v_exp_f32_e32 v103, v103
	v_mul_f32_e32 v5, v104, v104
	v_fmamk_f32 v5, v5, 0xbdd2d3e7, v129
	v_mul_f32_e32 v5, v5, v104
	v_fma_f32 v4, v13, v4, -v19
	v_add_f32_e32 v13, 1.0, v103
	v_rcp_f32_e32 v13, v13
	v_exp_f32_e32 v5, v5
	v_mul_f32_e32 v105, v39, v4
	v_cvt_pk_bf16_f32 v11, v11, s0
	v_fma_f32 v4, v13, v96, -v19
	v_add_f32_e32 v5, 1.0, v5
	v_rcp_f32_e32 v103, v5
	v_fmac_f32_e32 v27, v15, v12
	v_mul_f32_e32 v5, v39, v4
	v_fma_f32 v16, v16, v89, v20
	v_fma_f32 v4, v103, v104, -v19
	v_mul_u32_u24_e32 v19, 0x110, v87
	v_add3_u32 v19, s15, v19, v33
	v_cvt_pk_bf16_f32 v16, v16, s0
	v_fmac_f32_e32 v21, v105, v17
	v_mul_f32_e32 v2, v39, v2
	v_mul_f32_e32 v3, v39, v3
	v_mul_f32_e32 v4, v39, v4
	v_mul_u32_u24_e32 v17, 0x110, v90
	v_add3_u32 v17, s15, v17, v33
	v_readlane_b32 s44, v251, 58
	v_readlane_b32 s45, v251, 59
	v_readlane_b32 s50, v252, 0
	v_readlane_b32 s51, v252, 1
	s_waitcnt vmcnt(16)
	v_fmac_f32_e32 v14, v26, v53
	v_cvt_pk_bf16_f32 v13, v14, s0
	v_mul_u32_u24_e32 v14, 0x110, v81
	v_add3_u32 v14, s15, v14, v33
	ds_write_b16 v14, v13 offset:34816
	s_waitcnt vmcnt(14)
	v_fmac_f32_e32 v55, v54, v52
	v_mul_u32_u24_e32 v14, 0x110, v86
	v_cvt_pk_bf16_f32 v13, v55, s0
	v_add3_u32 v14, s15, v14, v33
	ds_write_b16 v14, v13 offset:34816
	ds_write_b16 v18, v11 offset:49776
	v_cvt_pk_bf16_f32 v11, v27, s0
	ds_write_b16 v18, v11 offset:50048
	global_load_dwordx4 v[12:15], v[6:7], off offset:48
	global_load_dwordx4 v[52:55], v[6:7], off offset:32
	v_readlane_b32 s52, v252, 2
	v_readlane_b32 s53, v252, 3
	v_readlane_b32 s54, v252, 4
	s_waitcnt vmcnt(14)
	v_fmac_f32_e32 v83, v58, v82
	v_cvt_pk_bf16_f32 v11, v83, s0
	ds_write_b16 v19, v11 offset:34816
	v_mul_u32_u24_e32 v19, 0x110, v88
	v_add3_u32 v19, s15, v19, v33
	v_or_b32_e32 v58, 35, v34
	s_waitcnt vmcnt(12)
	v_fmac_f32_e32 v85, v56, v84
	v_cvt_pk_bf16_f32 v11, v85, s0
	v_or_b32_e32 v56, 34, v34
	ds_write_b16 v19, v11 offset:34816
	v_lshlrev_b32_e32 v11, 2, v56
	v_lshlrev_b32_e32 v19, 2, v58
	global_load_dword v39, v11, s[16:17]
	s_nop 0
	global_load_dword v11, v11, s[20:21]
	s_nop 0
	global_load_dword v89, v19, s[16:17]
	global_load_dword v96, v19, s[20:21]
	ds_write_b16 v18, v16 offset:50864
	v_cvt_pk_bf16_f32 v16, v21, s0
	s_waitcnt vmcnt(14)
	v_fmac_f32_e32 v92, v91, v64
	ds_write_b16 v18, v16 offset:51136
	v_cvt_pk_bf16_f32 v16, v92, s0
	ds_write_b16 v17, v16 offset:34816
	s_waitcnt vmcnt(12)
	v_fmac_f32_e32 v95, v94, v63
	v_mul_u32_u24_e32 v17, 0x110, v93
	v_cvt_pk_bf16_f32 v16, v95, s0
	v_add3_u32 v17, s15, v17, v33
	ds_write_b16 v17, v16 offset:34816
	s_waitcnt vmcnt(10)
	v_fmac_f32_e32 v99, v69, v98
	v_mul_u32_u24_e32 v17, 0x110, v97
	v_cvt_pk_bf16_f32 v16, v99, s0
	v_add3_u32 v17, s15, v17, v33
	ds_write_b16 v17, v16 offset:34816
	s_waitcnt vmcnt(8)
	v_fmac_f32_e32 v102, v68, v101
	v_mul_u32_u24_e32 v17, 0x110, v100
	v_cvt_pk_bf16_f32 v16, v102, s0
	v_add3_u32 v17, s15, v17, v33
	ds_write_b16 v17, v16 offset:34816
	s_waitcnt vmcnt(6)
	v_cndmask_b32_e32 v16, 0, v45, vcc
	v_cmp_le_u32_e32 vcc, v34, v31
	v_or_b32_e32 v63, 38, v34
	v_or_b32_e32 v69, 39, v34
	v_cndmask_b32_e32 v17, 0, v44, vcc
	v_cvt_pk_bf16_f32 v16, v17, v16
	v_lshlrev_b32_e32 v17, 2, v63
	global_load_dword v64, v17, s[16:17]
	global_load_dword v68, v17, s[20:21]
	v_lshlrev_b32_e32 v18, 2, v69
	global_load_dword v91, v18, s[16:17]
	global_load_dword v92, v18, s[20:21]
	v_cvt_pk_bf16_f32 v17, v46, v47
	v_cmp_le_u32_e32 vcc, v76, v31
	global_load_dwordx4 v[44:47], v[6:7], off offset:80
	global_load_dwordx4 v[82:85], v[6:7], off offset:64
	v_cndmask_b32_e32 v18, 0, v17, vcc
	v_lshrrev_b32_e32 v17, 16, v17
	v_cmp_le_u32_e32 vcc, v77, v31
	v_or_b32_e32 v76, 47, v34
	v_readlane_b32 s55, v252, 5
	v_cndmask_b32_e32 v17, 0, v17, vcc
	v_cmp_gt_u32_e32 vcc, v31, v35
	v_perm_b32 v17, v17, v18, s19
	s_waitcnt vmcnt(8)
	v_fmac_f32_e32 v11, v39, v73
	v_cndmask_b32_e32 v18, 0, v23, vcc
	v_cmp_le_u32_e32 vcc, v35, v31
	v_cvt_pk_bf16_f32 v11, v11, s0
	v_or_b32_e32 v35, 42, v34
	v_cndmask_b32_e32 v19, 0, v22, vcc
	v_cvt_pk_bf16_f32 v18, v19, v18
	v_cvt_pk_bf16_f32 v19, v24, v25
	v_cmp_le_u32_e32 vcc, v65, v31
	s_waitcnt vmcnt(6)
	v_fmac_f32_e32 v96, v89, v72
	s_waitcnt vmcnt(4)
	v_fmac_f32_e32 v68, v71, v64
	v_cndmask_b32_e32 v20, 0, v19, vcc
	v_lshrrev_b32_e32 v19, 16, v19
	v_cmp_le_u32_e32 vcc, v78, v31
	s_waitcnt vmcnt(2)
	v_fmac_f32_e32 v92, v70, v91
	v_cndmask_b32_e32 v19, 0, v19, vcc
	v_perm_b32 v19, v19, v20, s19
	ds_write_b128 v0, v[16:19]
	global_load_dwordx4 v[20:23], v[6:7], off offset:112
	global_load_dwordx4 v[24:27], v[6:7], off offset:96
	v_cmp_gt_u32_e32 vcc, v31, v36
	s_nop 1
	v_cndmask_b32_e32 v16, 0, v53, vcc
	v_cmp_le_u32_e32 vcc, v36, v31
	s_nop 1
	v_cndmask_b32_e32 v17, 0, v52, vcc
	v_cvt_pk_bf16_f32 v16, v17, v16
	v_cvt_pk_bf16_f32 v17, v54, v55
	v_cmp_le_u32_e32 vcc, v80, v31
	v_or_b32_e32 v54, 43, v34
	v_lshlrev_b32_e32 v19, 2, v54
	v_cndmask_b32_e32 v18, 0, v17, vcc
	v_lshrrev_b32_e32 v17, 16, v17
	v_cmp_le_u32_e32 vcc, v79, v31
	s_nop 1
	v_cndmask_b32_e32 v17, 0, v17, vcc
	v_perm_b32 v17, v17, v18, s19
	v_mul_u32_u24_e32 v18, 0x110, v56
	v_add3_u32 v18, s15, v18, v33
	ds_write_b16 v18, v11 offset:34816
	v_lshlrev_b32_e32 v18, 2, v35
	global_load_dword v52, v18, s[16:17]
	global_load_dword v53, v18, s[20:21]
	v_mul_u32_u24_e32 v18, 0x110, v58
	v_cvt_pk_bf16_f32 v11, v96, s0
	v_add3_u32 v18, s15, v18, v33
	v_cmp_gt_u32_e32 vcc, v31, v37
	global_load_dword v55, v19, s[16:17]
	global_load_dword v65, v19, s[20:21]
	ds_write_b16 v18, v11 offset:34816
	v_cndmask_b32_e32 v11, 0, v13, vcc
	v_cmp_le_u32_e32 vcc, v37, v31
	s_waitcnt vmcnt(2)
	v_fmac_f32_e32 v53, v52, v67
	v_cndmask_b32_e32 v12, 0, v12, vcc
	v_cvt_pk_bf16_f32 v18, v12, v11
	v_cvt_pk_bf16_f32 v11, v14, v15
	v_cmp_le_u32_e32 vcc, v59, v31
	v_or_b32_e32 v59, 46, v34
	s_waitcnt vmcnt(0)
	v_fmac_f32_e32 v65, v55, v66
	v_cndmask_b32_e32 v12, 0, v11, vcc
	v_lshrrev_b32_e32 v11, 16, v11
	v_cmp_le_u32_e32 vcc, v10, v31
	v_or_b32_e32 v52, 54, v34
	s_nop 0
	v_cndmask_b32_e32 v10, 0, v11, vcc
	v_perm_b32 v19, v10, v12, s19
	v_lshlrev_b32_e32 v10, 2, v59
	global_load_dword v72, v10, s[16:17]
	global_load_dword v73, v10, s[20:21]
	ds_write_b128 v0, v[16:19] offset:16
	v_lshlrev_b32_e32 v10, 2, v76
	v_mul_u32_u24_e32 v11, 0x110, v63
	global_load_dword v77, v10, s[16:17]
	global_load_dword v78, v10, s[20:21]
	v_cvt_pk_bf16_f32 v10, v68, s0
	v_add3_u32 v11, s15, v11, v33
	ds_write_b16 v11, v10 offset:34816
	global_load_dwordx4 v[10:13], v[6:7], off offset:144
	global_load_dwordx4 v[14:17], v[6:7], off offset:128
	v_mul_u32_u24_e32 v19, 0x110, v69
	v_cvt_pk_bf16_f32 v18, v92, s0
	v_add3_u32 v19, s15, v19, v33
	v_cmp_gt_u32_e32 vcc, v31, v38
	ds_write_b16 v19, v18 offset:34816
	s_waitcnt vmcnt(4)
	v_fmac_f32_e32 v73, v75, v72
	v_cndmask_b32_e32 v18, 0, v83, vcc
	v_cmp_le_u32_e32 vcc, v38, v31
	s_waitcnt vmcnt(2)
	v_fmac_f32_e32 v78, v74, v77
	v_cndmask_b32_e32 v19, 0, v82, vcc
	v_cvt_pk_bf16_f32 v36, v19, v18
	v_cvt_pk_bf16_f32 v18, v84, v85
	v_cmp_le_u32_e32 vcc, v81, v31
	s_nop 1
	v_cndmask_b32_e32 v19, 0, v18, vcc
	v_lshrrev_b32_e32 v18, 16, v18
	v_cmp_le_u32_e32 vcc, v86, v31
	s_nop 1
	v_cndmask_b32_e32 v18, 0, v18, vcc
	v_cmp_gt_u32_e32 vcc, v31, v40
	v_perm_b32 v37, v18, v19, s19
	s_nop 0
	v_cndmask_b32_e32 v18, 0, v45, vcc
	v_cmp_le_u32_e32 vcc, v40, v31
	s_nop 1
	v_cndmask_b32_e32 v19, 0, v44, vcc
	v_cvt_pk_bf16_f32 v38, v19, v18
	v_cvt_pk_bf16_f32 v18, v46, v47
	v_cmp_le_u32_e32 vcc, v87, v31
	s_nop 1
	v_cndmask_b32_e32 v19, 0, v18, vcc
	v_lshrrev_b32_e32 v18, 16, v18
	v_cmp_le_u32_e32 vcc, v88, v31
	s_nop 1
	v_cndmask_b32_e32 v18, 0, v18, vcc
	v_cmp_gt_u32_e32 vcc, v31, v41
	v_perm_b32 v39, v18, v19, s19
	ds_write_b128 v0, v[36:39] offset:32
	v_cndmask_b32_e32 v18, 0, v25, vcc
	v_cmp_le_u32_e32 vcc, v41, v31
	v_mul_u32_u24_e32 v41, 0x110, v35
	v_add3_u32 v41, s15, v41, v33
	v_cndmask_b32_e32 v19, 0, v24, vcc
	v_cvt_pk_bf16_f32 v18, v19, v18
	v_cvt_pk_bf16_f32 v19, v26, v27
	global_load_dwordx4 v[24:27], v[6:7], off offset:176
	global_load_dwordx4 v[36:39], v[6:7], off offset:160
	v_cmp_le_u32_e32 vcc, v90, v31
	s_nop 1
	v_cndmask_b32_e32 v40, 0, v19, vcc
	v_lshrrev_b32_e32 v19, 16, v19
	v_cmp_le_u32_e32 vcc, v93, v31
	s_nop 1
	v_cndmask_b32_e32 v19, 0, v19, vcc
	v_cmp_gt_u32_e32 vcc, v31, v42
	v_perm_b32 v19, v19, v40, s19
	v_cvt_pk_bf16_f32 v40, v53, s0
	v_cndmask_b32_e32 v21, 0, v21, vcc
	v_cmp_le_u32_e32 vcc, v42, v31
	ds_write_b16 v41, v40 offset:34816
	v_mul_u32_u24_e32 v41, 0x110, v54
	v_cndmask_b32_e32 v20, 0, v20, vcc
	v_cvt_pk_bf16_f32 v20, v20, v21
	v_cvt_pk_bf16_f32 v21, v22, v23
	v_cmp_le_u32_e32 vcc, v97, v31
	v_cvt_pk_bf16_f32 v40, v65, s0
	v_add3_u32 v41, s15, v41, v33
	v_cndmask_b32_e32 v22, 0, v21, vcc
	v_lshrrev_b32_e32 v21, 16, v21
	v_cmp_le_u32_e32 vcc, v100, v31
	ds_write_b16 v41, v40 offset:34816
	v_mul_u32_u24_e32 v23, 0x110, v76
	v_cndmask_b32_e32 v21, 0, v21, vcc
	v_perm_b32 v21, v21, v22, s19
	ds_write_b128 v0, v[18:21] offset:48
	v_mul_u32_u24_e32 v19, 0x110, v59
	v_cvt_pk_bf16_f32 v18, v73, s0
	v_add3_u32 v19, s15, v19, v33
	v_cmp_gt_u32_e32 vcc, v31, v43
	ds_write_b16 v19, v18 offset:34816
	v_cvt_pk_bf16_f32 v22, v78, s0
	v_add3_u32 v23, s15, v23, v33
	s_waitcnt vmcnt(2)
	v_cndmask_b32_e32 v15, 0, v15, vcc
	v_cmp_le_u32_e32 vcc, v43, v31
	global_load_dwordx4 v[18:21], v[6:7], off offset:208
	global_load_dwordx4 v[44:47], v[6:7], off offset:192
	ds_write_b16 v23, v22 offset:34816
	v_cndmask_b32_e32 v14, 0, v14, vcc
	v_or_b32_e32 v23, 50, v34
	v_cvt_pk_bf16_f32 v14, v14, v15
	v_cvt_pk_bf16_f32 v15, v16, v17
	v_or_b32_e32 v22, 51, v34
	v_lshlrev_b32_e32 v17, 2, v23
	v_cmp_le_u32_e32 vcc, v56, v31
	global_load_dword v40, v17, s[16:17]
	global_load_dword v41, v17, s[20:21]
	v_lshlrev_b32_e32 v17, 2, v22
	v_cndmask_b32_e32 v16, 0, v15, vcc
	v_lshrrev_b32_e32 v15, 16, v15
	global_load_dword v42, v17, s[16:17]
	global_load_dword v43, v17, s[20:21]
	v_cmp_le_u32_e32 vcc, v58, v31
	s_waitcnt vmcnt(2)
	v_fmac_f32_e32 v41, v40, v62
	v_cndmask_b32_e32 v15, 0, v15, vcc
	v_cmp_gt_u32_e32 vcc, v31, v48
	v_perm_b32 v15, v15, v16, s19
	s_waitcnt vmcnt(0)
	v_fmac_f32_e32 v43, v42, v61
	v_cndmask_b32_e32 v11, 0, v11, vcc
	v_cmp_le_u32_e32 vcc, v48, v31
	v_or_b32_e32 v48, 55, v34
	s_nop 0
	v_cndmask_b32_e32 v10, 0, v10, vcc
	v_cvt_pk_bf16_f32 v16, v10, v11
	v_cvt_pk_bf16_f32 v10, v12, v13
	v_cmp_le_u32_e32 vcc, v63, v31
	s_nop 1
	v_cndmask_b32_e32 v11, 0, v10, vcc
	v_lshrrev_b32_e32 v10, 16, v10
	v_cmp_le_u32_e32 vcc, v69, v31
	s_nop 1
	v_cndmask_b32_e32 v10, 0, v10, vcc
	v_perm_b32 v17, v10, v11, s19
	v_lshlrev_b32_e32 v10, 2, v52
	global_load_dword v53, v10, s[16:17]
	global_load_dword v55, v10, s[20:21]
	v_lshlrev_b32_e32 v10, 2, v48
	global_load_dword v56, v10, s[16:17]
	global_load_dword v58, v10, s[20:21]
	v_cmp_gt_u32_e32 vcc, v31, v49
	ds_write_b128 v0, v[14:17] offset:64
	s_waitcnt vmcnt(2)
	v_fmac_f32_e32 v55, v9, v53
	v_cndmask_b32_e32 v10, 0, v37, vcc
	v_cmp_le_u32_e32 vcc, v49, v31
	v_or_b32_e32 v49, 58, v34
	v_cvt_pk_bf16_f32 v9, v55, s0
	v_cndmask_b32_e32 v11, 0, v36, vcc
	v_cvt_pk_bf16_f32 v10, v11, v10
	v_cvt_pk_bf16_f32 v11, v38, v39
	v_cmp_le_u32_e32 vcc, v35, v31
	global_load_dwordx4 v[14:17], v[6:7], off offset:240
	global_load_dwordx4 v[36:39], v[6:7], off offset:224
	v_cndmask_b32_e32 v12, 0, v11, vcc
	v_lshrrev_b32_e32 v11, 16, v11
	v_cmp_le_u32_e32 vcc, v54, v31
	v_or_b32_e32 v35, 59, v34
	s_waitcnt vmcnt(2)
	v_fmac_f32_e32 v58, v8, v56
	v_cndmask_b32_e32 v6, 0, v11, vcc
	v_perm_b32 v11, v6, v12, s19
	v_lshlrev_b32_e32 v6, 2, v49
	global_load_dword v54, v6, s[16:17]
	global_load_dword v63, v6, s[20:21]
	v_lshlrev_b32_e32 v6, 2, v35
	v_cmp_gt_u32_e32 vcc, v31, v51
	global_load_dword v64, v6, s[16:17]
	global_load_dword v65, v6, s[20:21]
	v_cndmask_b32_e32 v6, 0, v25, vcc
	v_cmp_le_u32_e32 vcc, v51, v31
	s_waitcnt vmcnt(2)
	v_fmac_f32_e32 v63, v54, v2
	v_cndmask_b32_e32 v7, 0, v24, vcc
	v_cvt_pk_bf16_f32 v12, v7, v6
	v_cvt_pk_bf16_f32 v6, v26, v27
	v_cmp_le_u32_e32 vcc, v59, v31
	v_mul_u32_u24_e32 v26, 0x110, v22
	v_cvt_pk_bf16_f32 v27, v41, s0
	v_cndmask_b32_e32 v7, 0, v6, vcc
	v_lshrrev_b32_e32 v6, 16, v6
	v_cmp_le_u32_e32 vcc, v76, v31
	v_add3_u32 v26, s15, v26, v33
	v_cvt_pk_bf16_f32 v2, v63, s0
	v_cndmask_b32_e32 v6, 0, v6, vcc
	v_perm_b32 v13, v6, v7, s19
	ds_write_b128 v0, v[10:13] offset:80
	v_or_b32_e32 v11, 62, v34
	v_or_b32_e32 v10, 63, v34
	v_lshlrev_b32_e32 v7, 2, v11
	global_load_dword v12, v7, s[16:17]
	global_load_dword v13, v7, s[20:21]
	v_lshlrev_b32_e32 v7, 2, v10
	global_load_dword v24, v7, s[16:17]
	global_load_dword v25, v7, s[20:21]
	v_cmp_gt_u32_e32 vcc, v31, v57
	s_waitcnt vmcnt(4)
	v_fmac_f32_e32 v65, v64, v3
	v_and_or_b32 v76, v30, 64, v32
	v_cndmask_b32_e32 v6, 0, v45, vcc
	v_cmp_le_u32_e32 vcc, v57, v31
	s_waitcnt vmcnt(2)
	v_fmac_f32_e32 v13, v5, v12
	v_cndmask_b32_e32 v7, 0, v44, vcc
	v_cvt_pk_bf16_f32 v6, v7, v6
	v_mul_u32_u24_e32 v7, 0x110, v23
	v_add3_u32 v7, s15, v7, v33
	ds_write_b16 v7, v27 offset:34816
	v_cvt_pk_bf16_f32 v7, v43, s0
	ds_write_b16 v26, v7 offset:34816
	v_cvt_pk_bf16_f32 v7, v46, v47
	v_cmp_le_u32_e32 vcc, v23, v31
	v_cvt_pk_bf16_f32 v5, v13, s0
	s_waitcnt vmcnt(0)
	v_fmac_f32_e32 v25, v4, v24
	v_cndmask_b32_e32 v23, 0, v7, vcc
	v_lshrrev_b32_e32 v7, 16, v7
	v_cmp_le_u32_e32 vcc, v22, v31
	s_nop 1
	v_cndmask_b32_e32 v7, 0, v7, vcc
	v_perm_b32 v7, v7, v23, s19
	v_cmp_gt_u32_e32 vcc, v31, v60
	ds_write_b64 v0, v[6:7] offset:96
	s_nop 0
	v_cndmask_b32_e32 v6, 0, v19, vcc
	v_cmp_le_u32_e32 vcc, v60, v31
	s_nop 1
	v_cndmask_b32_e32 v7, 0, v18, vcc
	v_cvt_pk_bf16_f32 v6, v7, v6
	v_mul_u32_u24_e32 v7, 0x110, v52
	v_add3_u32 v7, s15, v7, v33
	v_mul_u32_u24_e32 v18, 0x110, v48
	v_add3_u32 v18, s15, v18, v33
	ds_write_b16 v7, v9 offset:34816
	v_cvt_pk_bf16_f32 v7, v58, s0
	ds_write_b16 v18, v7 offset:34816
	v_cvt_pk_bf16_f32 v7, v20, v21
	v_cmp_le_u32_e32 vcc, v52, v31
	s_nop 1
	v_cndmask_b32_e32 v8, 0, v7, vcc
	v_lshrrev_b32_e32 v7, 16, v7
	v_cmp_le_u32_e32 vcc, v48, v31
	s_nop 1
	v_cndmask_b32_e32 v7, 0, v7, vcc
	v_perm_b32 v7, v7, v8, s19
	v_cmp_gt_u32_e32 vcc, v31, v29
	ds_write_b64 v0, v[6:7] offset:104
	v_mul_u32_u24_e32 v8, 0x110, v35
	v_cndmask_b32_e32 v6, 0, v37, vcc
	v_cmp_le_u32_e32 vcc, v29, v31
	v_add3_u32 v8, s15, v8, v33
	s_nop 0
	v_cndmask_b32_e32 v7, 0, v36, vcc
	v_cvt_pk_bf16_f32 v6, v7, v6
	v_mul_u32_u24_e32 v7, 0x110, v49
	v_add3_u32 v7, s15, v7, v33
	ds_write_b16 v7, v2 offset:34816
	v_cvt_pk_bf16_f32 v2, v65, s0
	ds_write_b16 v8, v2 offset:34816
	v_cvt_pk_bf16_f32 v2, v38, v39
	v_cmp_le_u32_e32 vcc, v49, v31
	s_nop 1
	v_cndmask_b32_e32 v3, 0, v2, vcc
	v_lshrrev_b32_e32 v2, 16, v2
	v_cmp_le_u32_e32 vcc, v35, v31
	s_nop 1
	v_cndmask_b32_e32 v2, 0, v2, vcc
	v_cmp_gt_u32_e32 vcc, v31, v28
	v_perm_b32 v7, v2, v3, s19
	ds_write_b64 v0, v[6:7] offset:112
	v_cndmask_b32_e32 v2, 0, v15, vcc
	v_cmp_le_u32_e32 vcc, v28, v31
	v_mul_u32_u24_e32 v6, 0x110, v10
	v_add3_u32 v6, s15, v6, v33
	v_cndmask_b32_e32 v3, 0, v14, vcc
	v_cvt_pk_bf16_f32 v2, v3, v2
	v_mul_u32_u24_e32 v3, 0x110, v11
	v_add3_u32 v3, s15, v3, v33
	ds_write_b16 v3, v5 offset:34816
	v_cvt_pk_bf16_f32 v3, v25, s0
	ds_write_b16 v6, v3 offset:34816
	v_cvt_pk_bf16_f32 v3, v16, v17
	v_cmp_le_u32_e32 vcc, v11, v31
	v_mul_u32_u24_e32 v7, 0x88, v76
	s_mov_b64 s[0:1], 0x1f000
	v_cndmask_b32_e32 v4, 0, v3, vcc
	v_lshrrev_b32_e32 v3, 16, v3
	v_cmp_le_u32_e32 vcc, v10, v31
	s_nop 1
	v_cndmask_b32_e32 v3, 0, v3, vcc
	v_perm_b32 v3, v3, v4, s19
	ds_write_b64 v0, v[2:3] offset:120
	v_bfe_u32 v0, v50, 4, 2
	v_and_b32_e32 v2, 0x4f, v50
	v_lshl_add_u32 v6, v0, 4, s15
	v_mul_u32_u24_e32 v2, 0x88, v2
	v_lshl_add_u32 v51, v2, 1, v6
	s_waitcnt lgkmcnt(0)
	s_barrier
	ds_read_b128 v[2:5], v51 offset:34816
	ds_read_b128 v[72:75], v51 offset:34880
	ds_read_b128 v[14:17], v51 offset:39168
	ds_read_b128 v[78:81], v51 offset:39232
	ds_read_b128 v[22:25], v51 offset:43520
	ds_read_b128 v[82:85], v51 offset:43584
	ds_read_b128 v[30:33], v51 offset:47872
	ds_read_b128 v[86:89], v51 offset:47936
	v_lshl_add_u32 v77, v7, 1, v6
	ds_read_b128 v[6:9], v77
	ds_read_b128 v[34:37], v77 offset:4352
	ds_read_b128 v[52:55], v77 offset:8704
	ds_read_b128 v[68:71], v77 offset:13056
	s_waitcnt lgkmcnt(3)
	v_mfma_f32_16x16x32_bf16 v[10:13], v[2:5], v[6:9], 0
	ds_read_b128 v[98:101], v51 offset:48000
	v_mfma_f32_16x16x32_bf16 v[18:21], v[14:17], v[6:9], 0
	v_mfma_f32_16x16x32_bf16 v[26:29], v[22:25], v[6:9], 0
	v_mfma_f32_16x16x32_bf16 v[6:9], v[30:33], v[6:9], 0
	s_waitcnt lgkmcnt(3)
	v_mfma_f32_16x16x32_bf16 v[38:41], v[2:5], v[34:37], 0
	v_mfma_f32_16x16x32_bf16 v[42:45], v[14:17], v[34:37], 0
	v_mfma_f32_16x16x32_bf16 v[46:49], v[22:25], v[34:37], 0
	v_mfma_f32_16x16x32_bf16 v[34:37], v[30:33], v[34:37], 0
	s_waitcnt lgkmcnt(2)
	v_mfma_f32_16x16x32_bf16 v[56:59], v[2:5], v[52:55], 0
	v_mfma_f32_16x16x32_bf16 v[60:63], v[14:17], v[52:55], 0
	v_mfma_f32_16x16x32_bf16 v[64:67], v[22:25], v[52:55], 0
	v_mfma_f32_16x16x32_bf16 v[52:55], v[30:33], v[52:55], 0
	s_waitcnt lgkmcnt(1)
	v_mfma_f32_16x16x32_bf16 v[2:5], v[2:5], v[68:71], 0
	v_mfma_f32_16x16x32_bf16 v[14:17], v[14:17], v[68:71], 0
	v_mfma_f32_16x16x32_bf16 v[22:25], v[22:25], v[68:71], 0
	v_mfma_f32_16x16x32_bf16 v[30:33], v[30:33], v[68:71], 0
	ds_read_b128 v[68:71], v77 offset:64
	s_waitcnt lgkmcnt(0)
	v_mfma_f32_16x16x32_bf16 v[10:13], v[72:75], v[68:71], v[10:13]
	v_mfma_f32_16x16x32_bf16 v[18:21], v[78:81], v[68:71], v[18:21]
	v_mfma_f32_16x16x32_bf16 v[26:29], v[82:85], v[68:71], v[26:29]
	v_mfma_f32_16x16x32_bf16 v[6:9], v[86:89], v[68:71], v[6:9]
	ds_read_b128 v[68:71], v77 offset:4416
	s_waitcnt lgkmcnt(0)
	v_mfma_f32_16x16x32_bf16 v[38:41], v[72:75], v[68:71], v[38:41]
	v_mfma_f32_16x16x32_bf16 v[42:45], v[78:81], v[68:71], v[42:45]
	v_mfma_f32_16x16x32_bf16 v[46:49], v[82:85], v[68:71], v[46:49]
	v_mfma_f32_16x16x32_bf16 v[34:37], v[86:89], v[68:71], v[34:37]
	ds_read_b128 v[68:71], v77 offset:8768
	s_waitcnt lgkmcnt(0)
	v_mfma_f32_16x16x32_bf16 v[90:93], v[78:81], v[68:71], v[60:63]
	s_nop 2
	ds_read_b128 v[60:63], v77 offset:13120
	v_mfma_f32_16x16x32_bf16 v[56:59], v[72:75], v[68:71], v[56:59]
	v_mfma_f32_16x16x32_bf16 v[94:97], v[82:85], v[68:71], v[64:67]
	v_mfma_f32_16x16x32_bf16 v[52:55], v[86:89], v[68:71], v[52:55]
	s_nop 1
	ds_read_b128 v[66:69], v51 offset:34944
	s_waitcnt lgkmcnt(1)
	v_mfma_f32_16x16x32_bf16 v[2:5], v[72:75], v[60:63], v[2:5]
	v_mfma_f32_16x16x32_bf16 v[70:73], v[86:89], v[60:63], v[30:33]
	s_nop 2
	ds_read_b128 v[30:33], v77 offset:128
	v_mfma_f32_16x16x32_bf16 v[14:17], v[78:81], v[60:63], v[14:17]
	s_waitcnt lgkmcnt(0)
	v_mfma_f32_16x16x32_bf16 v[78:81], v[66:69], v[30:33], v[10:13]
	s_nop 2
	ds_read_b128 v[10:13], v51 offset:39296
	v_mfma_f32_16x16x32_bf16 v[22:25], v[82:85], v[60:63], v[22:25]
	v_mfma_f32_16x16x32_bf16 v[102:105], v[98:101], v[30:33], v[6:9]
	s_nop 2
	ds_read_b128 v[6:9], v77 offset:4480
	s_waitcnt lgkmcnt(1)
	v_mfma_f32_16x16x32_bf16 v[82:85], v[10:13], v[30:33], v[18:21]
	s_nop 2
	ds_read_b128 v[18:21], v51 offset:43648
	s_waitcnt lgkmcnt(1)
	v_mfma_f32_16x16x32_bf16 v[106:109], v[66:69], v[6:9], v[38:41]
	v_mfma_f32_16x16x32_bf16 v[110:113], v[10:13], v[6:9], v[42:45]
	s_waitcnt lgkmcnt(0)
	v_mfma_f32_16x16x32_bf16 v[114:117], v[18:21], v[6:9], v[46:49]
	v_mfma_f32_16x16x32_bf16 v[62:65], v[98:101], v[6:9], v[34:37]
	ds_read_b128 v[6:9], v77 offset:8832
	s_waitcnt lgkmcnt(0)
	v_mfma_f32_16x16x32_bf16 v[42:45], v[98:101], v[6:9], v[52:55]
	s_nop 2
	ds_read_b128 v[52:55], v77 offset:13184
	v_mfma_f32_16x16x32_bf16 v[86:89], v[18:21], v[30:33], v[26:29]
	ds_read_b128 v[30:33], v51 offset:35008
	s_waitcnt lgkmcnt(1)
	v_mfma_f32_16x16x32_bf16 v[26:29], v[66:69], v[52:55], v[2:5]
	v_mfma_f32_16x16x32_bf16 v[2:5], v[18:21], v[52:55], v[22:25]
	s_nop 2
	v_and_b32_e32 v22, 64, v50
	v_mfma_f32_16x16x32_bf16 v[38:41], v[66:69], v[6:9], v[56:59]
	v_lshlrev_b32_e32 v66, 3, v0
	v_lshlrev_b32_e32 v0, 1, v22
	v_or_b32_e32 v24, s4, v76
	v_lshl_add_u64 v[22:23], s[6:7], 0, v[0:1]
	v_mov_b32_e32 v67, v1
	v_mfma_f32_16x16x32_bf16 v[34:37], v[10:13], v[6:9], v[90:93]
	v_lshl_add_u64 v[22:23], v[22:23], 0, v[66:67]
	v_lshlrev_b32_e32 v76, 2, v76
	s_mov_b32 s4, 0x3e000
	v_mfma_f32_16x16x32_bf16 v[46:49], v[18:21], v[6:9], v[94:97]
	v_mfma_f32_16x16x32_bf16 v[6:9], v[10:13], v[52:55], v[14:17]
	v_mfma_f32_16x16x32_bf16 v[10:13], v[98:101], v[52:55], v[70:73]
	ds_read_b128 v[52:55], v77 offset:192
	s_nop 0
	ds_read_b128 v[14:17], v51 offset:39360
	ds_read_b128 v[18:21], v51 offset:43712
	v_mul_u32_u24_e32 v72, 0x1f00, v24
	v_mov_b32_e32 v73, v1
	v_lshl_add_u64 v[68:69], v[22:23], 0, v[72:73]
	global_load_dwordx2 v[98:99], v[68:69], off
	global_load_dwordx2 v[100:101], v[68:69], off offset:32
	ds_read_b128 v[94:97], v77 offset:4544
	s_waitcnt lgkmcnt(0)
	v_mfma_f32_16x16x32_bf16 v[58:61], v[30:33], v[94:97], v[106:109]
	s_nop 2
	global_load_dword v106, v76, s[12:13]
	ds_read_b128 v[22:25], v51 offset:48064
	v_lshl_add_u64 v[72:73], s[46:47], 0, v[72:73]
	s_waitcnt lgkmcnt(0)
	v_mfma_f32_16x16x32_bf16 v[90:93], v[22:25], v[52:55], v[102:105]
	s_nop 2
	global_load_dwordx2 v[102:103], v[68:69], off offset:64
	global_load_dwordx2 v[104:105], v[68:69], off offset:96
	v_lshl_add_u64 v[72:73], v[72:73], 0, s[8:9]
	v_lshl_add_u64 v[72:73], v[72:73], 0, v[0:1]
	v_mfma_f32_16x16x32_bf16 v[78:81], v[30:33], v[52:55], v[78:81]
	v_lshl_add_u64 v[66:67], v[72:73], 0, v[66:67]
	v_add_co_u32_e32 v70, vcc, s2, v68
	v_mfma_f32_16x16x32_bf16 v[82:85], v[14:17], v[52:55], v[82:85]
	s_nop 0
	v_addc_co_u32_e32 v71, vcc, 0, v69, vcc
	s_waitcnt vmcnt(4)
	v_lshlrev_b32_e32 v107, 16, v98
	v_and_b32_e32 v98, 0xffff0000, v98
	v_mul_f32_e32 v75, v98, v98
	v_mul_f32_e32 v74, v107, v107
	v_fmamk_f32 v75, v75, 0xbdd2d3e7, v129
	v_fmamk_f32 v74, v74, 0xbdd2d3e7, v129
	v_mul_f32_e32 v75, v75, v98
	v_mul_f32_e32 v74, v74, v107
	v_exp_f32_e32 v108, v75
	v_exp_f32_e32 v74, v74
	s_waitcnt vmcnt(2)
	v_add_f32_e32 v79, v79, v106
	v_add_f32_e32 v78, v78, v106
	v_add_f32_e32 v108, 1.0, v108
	v_add_f32_e32 v74, 1.0, v74
	v_rcp_f32_e32 v108, v108
	v_rcp_f32_e32 v109, v74
	v_add_f32_e32 v80, v80, v106
	v_add_f32_e32 v81, v81, v106
	v_mul_f32_e32 v98, v108, v98
	v_mul_f32_e32 v107, v109, v107
	v_mul_f32_e32 v79, v98, v79
	v_lshlrev_b32_e32 v98, 16, v99
	v_and_b32_e32 v99, 0xffff0000, v99
	v_mul_f32_e32 v78, v107, v78
	v_mul_f32_e32 v107, v98, v98
	v_mul_f32_e32 v108, v99, v99
	v_fmamk_f32 v107, v107, 0xbdd2d3e7, v129
	v_fmamk_f32 v108, v108, 0xbdd2d3e7, v129
	v_mul_f32_e32 v107, v107, v98
	v_mul_f32_e32 v108, v108, v99
	v_exp_f32_e32 v107, v107
	v_exp_f32_e32 v108, v108
	v_cvt_pk_bf16_f32 v78, v78, v79
	v_lshlrev_b32_e32 v0, 16, v100
	v_add_f32_e32 v107, 1.0, v107
	v_add_f32_e32 v79, 1.0, v108
	v_rcp_f32_e32 v107, v107
	v_rcp_f32_e32 v79, v79
	v_mul_f32_e32 v72, v0, v0
	v_and_b32_e32 v73, 0xffff0000, v100
	v_mul_f32_e32 v98, v107, v98
	v_mul_f32_e32 v79, v79, v99
	v_mul_f32_e32 v80, v98, v80
	v_mul_f32_e32 v79, v79, v81
	v_cvt_pk_bf16_f32 v79, v80, v79
	v_fmamk_f32 v72, v72, 0xbdd2d3e7, v129
	v_mul_f32_e32 v80, v73, v73
	v_mul_f32_e32 v72, v72, v0
	v_fmamk_f32 v80, v80, 0xbdd2d3e7, v129
	v_mul_f32_e32 v80, v80, v73
	v_exp_f32_e32 v72, v72
	v_exp_f32_e32 v80, v80
	global_store_dwordx2 v[66:67], v[78:79], off
	v_add_f32_e32 v72, 1.0, v72
	v_rcp_f32_e32 v72, v72
	v_add_f32_e32 v78, 1.0, v80
	v_rcp_f32_e32 v78, v78
	v_and_b32_e32 v79, 0xffff0000, v101
	v_mul_f32_e32 v0, v72, v0
	v_add_f32_e32 v72, v82, v106
	v_mul_f32_e32 v0, v0, v72
	v_mul_f32_e32 v72, v78, v73
	v_add_f32_e32 v73, v83, v106
	v_mul_f32_e32 v72, v72, v73
	v_lshlrev_b32_e32 v73, 16, v101
	v_mul_f32_e32 v78, v73, v73
	v_fmamk_f32 v78, v78, 0xbdd2d3e7, v129
	v_mul_f32_e32 v80, v79, v79
	v_mul_f32_e32 v78, v78, v73
	v_fmamk_f32 v80, v80, 0xbdd2d3e7, v129
	v_mul_f32_e32 v80, v80, v79
	v_exp_f32_e32 v78, v78
	v_exp_f32_e32 v80, v80
	v_cvt_pk_bf16_f32 v72, v0, v72
	v_add_f32_e32 v78, 1.0, v78
	v_rcp_f32_e32 v78, v78
	v_add_f32_e32 v0, 1.0, v80
	v_rcp_f32_e32 v0, v0
	v_mfma_f32_16x16x32_bf16 v[86:89], v[18:21], v[52:55], v[86:89]
	v_mul_f32_e32 v73, v78, v73
	v_add_f32_e32 v78, v84, v106
	v_mul_f32_e32 v73, v73, v78
	v_mul_f32_e32 v0, v0, v79
	v_add_f32_e32 v78, v85, v106
	v_mul_f32_e32 v0, v0, v78
	v_cvt_pk_bf16_f32 v73, v73, v0
	s_waitcnt vmcnt(2)
	v_lshlrev_b32_e32 v0, 16, v102
	v_mul_f32_e32 v78, v0, v0
	v_and_b32_e32 v79, 0xffff0000, v102
	v_fmamk_f32 v78, v78, 0xbdd2d3e7, v129
	v_mul_f32_e32 v80, v79, v79
	v_mul_f32_e32 v78, v78, v0
	v_fmamk_f32 v80, v80, 0xbdd2d3e7, v129
	v_mul_f32_e32 v80, v80, v79
	v_exp_f32_e32 v78, v78
	v_exp_f32_e32 v80, v80
	global_store_dwordx2 v[66:67], v[72:73], off offset:32
	v_add_f32_e32 v78, 1.0, v78
	v_rcp_f32_e32 v78, v78
	v_add_f32_e32 v72, 1.0, v80
	v_rcp_f32_e32 v72, v72
	v_add_f32_e32 v73, v86, v106
	v_mul_f32_e32 v0, v78, v0
	v_mul_f32_e32 v0, v0, v73
	v_mul_f32_e32 v72, v72, v79
	v_add_f32_e32 v73, v87, v106
	v_mul_f32_e32 v72, v72, v73
	v_lshlrev_b32_e32 v73, 16, v103
	v_mul_f32_e32 v78, v73, v73
	v_and_b32_e32 v79, 0xffff0000, v103
	v_fmamk_f32 v78, v78, 0xbdd2d3e7, v129
	v_mul_f32_e32 v80, v79, v79
	v_mul_f32_e32 v78, v78, v73
	v_fmamk_f32 v80, v80, 0xbdd2d3e7, v129
	v_mul_f32_e32 v80, v80, v79
	v_exp_f32_e32 v78, v78
	v_exp_f32_e32 v80, v80
	v_cvt_pk_bf16_f32 v72, v0, v72
	v_add_f32_e32 v78, 1.0, v78
	v_rcp_f32_e32 v78, v78
	v_add_f32_e32 v0, 1.0, v80
	v_rcp_f32_e32 v0, v0
	global_load_dwordx2 v[74:75], v[70:71], off
	global_load_dwordx2 v[82:83], v[70:71], off offset:32
	v_mul_f32_e32 v73, v78, v73
	v_add_f32_e32 v78, v88, v106
	v_mul_f32_e32 v73, v73, v78
	v_mul_f32_e32 v0, v0, v79
	v_add_f32_e32 v78, v89, v106
	v_mul_f32_e32 v0, v0, v78
	v_cvt_pk_bf16_f32 v73, v73, v0
	s_waitcnt vmcnt(4)
	v_lshlrev_b32_e32 v0, 16, v104
	v_mul_f32_e32 v78, v0, v0
	v_and_b32_e32 v79, 0xffff0000, v104
	v_fmamk_f32 v78, v78, 0xbdd2d3e7, v129
	v_mul_f32_e32 v80, v79, v79
	v_mul_f32_e32 v78, v78, v0
	v_fmamk_f32 v80, v80, 0xbdd2d3e7, v129
	v_mul_f32_e32 v80, v80, v79
	v_exp_f32_e32 v78, v78
	v_exp_f32_e32 v80, v80
	global_store_dwordx2 v[66:67], v[72:73], off offset:64
	v_add_f32_e32 v78, 1.0, v78
	v_rcp_f32_e32 v78, v78
	v_add_f32_e32 v72, 1.0, v80
	v_rcp_f32_e32 v72, v72
	v_add_f32_e32 v73, v90, v106
	v_mul_f32_e32 v0, v78, v0
	v_mul_f32_e32 v0, v0, v73
	v_mul_f32_e32 v72, v72, v79
	v_add_f32_e32 v73, v91, v106
	v_mul_f32_e32 v72, v72, v73
	v_lshlrev_b32_e32 v73, 16, v105
	v_mul_f32_e32 v78, v73, v73
	v_and_b32_e32 v79, 0xffff0000, v105
	v_fmamk_f32 v78, v78, 0xbdd2d3e7, v129
	v_mul_f32_e32 v80, v79, v79
	v_mul_f32_e32 v78, v78, v73
	v_fmamk_f32 v80, v80, 0xbdd2d3e7, v129
	v_mul_f32_e32 v80, v80, v79
	v_exp_f32_e32 v78, v78
	v_exp_f32_e32 v80, v80
	v_cvt_pk_bf16_f32 v72, v0, v72
	v_add_f32_e32 v78, 1.0, v78
	v_rcp_f32_e32 v78, v78
	v_add_f32_e32 v0, 1.0, v80
	v_rcp_f32_e32 v0, v0
	v_mfma_f32_16x16x32_bf16 v[54:57], v[14:17], v[94:97], v[110:113]
	v_mul_f32_e32 v73, v78, v73
	v_add_f32_e32 v78, v92, v106
	v_mul_f32_e32 v73, v78, v73
	v_mul_f32_e32 v0, v0, v79
	v_add_f32_e32 v78, v93, v106
	v_mul_f32_e32 v0, v78, v0
	v_cvt_pk_bf16_f32 v73, v73, v0
	global_store_dwordx2 v[66:67], v[72:73], off offset:96
	global_load_dword v0, v76, s[12:13] offset:64
	ds_read_b128 v[78:81], v77 offset:8896
	global_load_dwordx2 v[84:85], v[70:71], off offset:64
	global_load_dwordx2 v[86:87], v[70:71], off offset:96
	v_add_co_u32_e32 v72, vcc, s4, v68
	v_mfma_f32_16x16x32_bf16 v[50:53], v[18:21], v[94:97], v[114:117]
	s_nop 0
	v_addc_co_u32_e32 v73, vcc, 0, v69, vcc
	s_waitcnt vmcnt(6)
	v_lshlrev_b32_e32 v88, 16, v74
	v_and_b32_e32 v74, 0xffff0000, v74
	v_mul_f32_e32 v71, v74, v74
	v_mul_f32_e32 v70, v88, v88
	v_fmamk_f32 v71, v71, 0xbdd2d3e7, v129
	v_fmamk_f32 v70, v70, 0xbdd2d3e7, v129
	v_mul_f32_e32 v71, v71, v74
	v_mul_f32_e32 v70, v70, v88
	v_exp_f32_e32 v89, v71
	v_exp_f32_e32 v70, v70
	v_mfma_f32_16x16x32_bf16 v[62:65], v[22:25], v[94:97], v[62:65]
	v_add_f32_e32 v89, 1.0, v89
	v_add_f32_e32 v70, 1.0, v70
	v_rcp_f32_e32 v89, v89
	v_rcp_f32_e32 v90, v70
	global_load_dwordx2 v[70:71], v[72:73], off
	s_waitcnt lgkmcnt(0)
	v_mfma_f32_16x16x32_bf16 v[38:41], v[30:33], v[78:81], v[38:41]
	v_mul_f32_e32 v74, v89, v74
	v_mul_f32_e32 v88, v90, v88
	s_waitcnt vmcnt(3)
	v_add_f32_e32 v59, v59, v0
	v_add_f32_e32 v58, v58, v0
	v_mul_f32_e32 v59, v74, v59
	v_lshlrev_b32_e32 v74, 16, v75
	v_mul_f32_e32 v58, v88, v58
	v_mul_f32_e32 v88, v74, v74
	v_fmamk_f32 v88, v88, 0xbdd2d3e7, v129
	v_mul_f32_e32 v88, v88, v74
	v_exp_f32_e32 v88, v88
	v_and_b32_e32 v75, 0xffff0000, v75
	v_mul_f32_e32 v89, v75, v75
	v_fmamk_f32 v89, v89, 0xbdd2d3e7, v129
	v_mul_f32_e32 v89, v89, v75
	v_add_f32_e32 v88, 1.0, v88
	v_rcp_f32_e32 v88, v88
	v_exp_f32_e32 v89, v89
	v_cvt_pk_bf16_f32 v58, v58, v59
	v_mul_f32_e32 v74, v88, v74
	v_lshlrev_b32_e32 v88, 16, v82
	v_and_b32_e32 v82, 0xffff0000, v82
	v_mul_f32_e32 v90, v82, v82
	v_add_f32_e32 v59, 1.0, v89
	v_mul_f32_e32 v89, v88, v88
	v_fmamk_f32 v90, v90, 0xbdd2d3e7, v129
	v_rcp_f32_e32 v59, v59
	v_fmamk_f32 v89, v89, 0xbdd2d3e7, v129
	v_mul_f32_e32 v90, v90, v82
	v_mul_f32_e32 v89, v89, v88
	v_exp_f32_e32 v90, v90
	v_add_f32_e32 v60, v60, v0
	v_mul_f32_e32 v59, v59, v75
	v_add_f32_e32 v61, v61, v0
	v_exp_f32_e32 v89, v89
	v_mul_f32_e32 v60, v74, v60
	v_mul_f32_e32 v59, v59, v61
	v_add_co_u32_e32 v74, vcc, s2, v66
	v_cvt_pk_bf16_f32 v59, v60, v59
	s_nop 0
	v_addc_co_u32_e32 v75, vcc, 0, v67, vcc
	global_store_dwordx2 v[74:75], v[58:59], off
	v_add_f32_e32 v58, 1.0, v90
	v_add_f32_e32 v89, 1.0, v89
	v_rcp_f32_e32 v58, v58
	v_rcp_f32_e32 v89, v89
	v_add_f32_e32 v55, v55, v0
	v_add_f32_e32 v54, v54, v0
	v_mul_f32_e32 v58, v58, v82
	v_mul_f32_e32 v59, v89, v88
	v_mul_f32_e32 v55, v58, v55
	v_lshlrev_b32_e32 v58, 16, v83
	v_and_b32_e32 v74, 0xffff0000, v83
	v_mul_f32_e32 v54, v59, v54
	v_mul_f32_e32 v59, v58, v58
	v_mul_f32_e32 v75, v74, v74
	v_fmamk_f32 v59, v59, 0xbdd2d3e7, v129
	v_fmamk_f32 v75, v75, 0xbdd2d3e7, v129
	v_mul_f32_e32 v59, v59, v58
	v_mul_f32_e32 v75, v75, v74
	v_exp_f32_e32 v59, v59
	v_exp_f32_e32 v75, v75
	v_cvt_pk_bf16_f32 v54, v54, v55
	v_add_f32_e32 v56, v56, v0
	v_add_f32_e32 v59, 1.0, v59
	v_add_f32_e32 v55, 1.0, v75
	v_rcp_f32_e32 v59, v59
	v_rcp_f32_e32 v55, v55
	v_add_f32_e32 v57, v57, v0
	v_lshl_add_u64 v[60:61], v[66:67], 0, s[0:1]
	v_mul_f32_e32 v58, v59, v58
	v_mul_f32_e32 v55, v55, v74
	v_mul_f32_e32 v56, v58, v56
	v_mul_f32_e32 v55, v55, v57
	s_waitcnt vmcnt(3)
	v_and_b32_e32 v58, 0xffff0000, v84
	v_cvt_pk_bf16_f32 v55, v56, v55
	v_lshlrev_b32_e32 v56, 16, v84
	v_mul_f32_e32 v59, v58, v58
	v_mul_f32_e32 v57, v56, v56
	v_fmamk_f32 v59, v59, 0xbdd2d3e7, v129
	v_fmamk_f32 v57, v57, 0xbdd2d3e7, v129
	v_mul_f32_e32 v59, v59, v58
	v_mul_f32_e32 v57, v57, v56
	v_exp_f32_e32 v59, v59
	v_exp_f32_e32 v57, v57
	global_store_dwordx2 v[60:61], v[54:55], off offset:32
	v_add_f32_e32 v51, v51, v0
	v_add_f32_e32 v54, 1.0, v59
	v_add_f32_e32 v57, 1.0, v57
	v_rcp_f32_e32 v54, v54
	v_rcp_f32_e32 v57, v57
	v_add_f32_e32 v50, v50, v0
	v_add_f32_e32 v52, v52, v0
	v_mul_f32_e32 v54, v54, v58
	v_mul_f32_e32 v55, v57, v56
	v_mul_f32_e32 v51, v54, v51
	v_lshlrev_b32_e32 v54, 16, v85
	v_and_b32_e32 v56, 0xffff0000, v85
	v_mul_f32_e32 v50, v55, v50
	v_mul_f32_e32 v55, v54, v54
	v_mul_f32_e32 v57, v56, v56
	v_fmamk_f32 v55, v55, 0xbdd2d3e7, v129
	v_fmamk_f32 v57, v57, 0xbdd2d3e7, v129
	v_mul_f32_e32 v55, v55, v54
	v_mul_f32_e32 v57, v57, v56
	v_exp_f32_e32 v55, v55
	v_exp_f32_e32 v57, v57
	v_cvt_pk_bf16_f32 v50, v50, v51
	v_add_f32_e32 v53, v53, v0
	v_add_f32_e32 v55, 1.0, v55
	v_add_f32_e32 v51, 1.0, v57
	v_rcp_f32_e32 v55, v55
	v_rcp_f32_e32 v51, v51
	s_mov_b32 s2, 0x5d000
	v_mfma_f32_16x16x32_bf16 v[34:37], v[14:17], v[78:81], v[34:37]
	v_mul_f32_e32 v54, v55, v54
	v_mul_f32_e32 v51, v51, v56
	v_mul_f32_e32 v52, v54, v52
	v_mul_f32_e32 v51, v51, v53
	v_cvt_pk_bf16_f32 v51, v52, v51
	s_waitcnt vmcnt(3)
	v_lshlrev_b32_e32 v52, 16, v86
	v_mul_f32_e32 v53, v52, v52
	v_and_b32_e32 v54, 0xffff0000, v86
	v_fmamk_f32 v53, v53, 0xbdd2d3e7, v129
	v_mul_f32_e32 v55, v54, v54
	v_mul_f32_e32 v53, v53, v52
	v_fmamk_f32 v55, v55, 0xbdd2d3e7, v129
	v_mul_f32_e32 v55, v55, v54
	v_exp_f32_e32 v53, v53
	v_exp_f32_e32 v55, v55
	global_store_dwordx2 v[60:61], v[50:51], off offset:64
	v_add_f32_e32 v53, 1.0, v53
	v_rcp_f32_e32 v53, v53
	v_add_f32_e32 v50, 1.0, v55
	v_rcp_f32_e32 v50, v50
	s_mov_b64 s[0:1], 0x3e000
	v_mul_f32_e32 v51, v53, v52
	v_add_f32_e32 v52, v62, v0
	v_mul_f32_e32 v51, v51, v52
	v_mul_f32_e32 v50, v50, v54
	v_add_f32_e32 v52, v63, v0
	v_mul_f32_e32 v50, v50, v52
	v_lshlrev_b32_e32 v52, 16, v87
	v_and_b32_e32 v54, 0xffff0000, v87
	v_mul_f32_e32 v53, v52, v52
	v_mul_f32_e32 v55, v54, v54
	v_fmamk_f32 v53, v53, 0xbdd2d3e7, v129
	v_fmamk_f32 v55, v55, 0xbdd2d3e7, v129
	v_mul_f32_e32 v53, v53, v52
	v_mul_f32_e32 v55, v55, v54
	v_exp_f32_e32 v53, v53
	v_exp_f32_e32 v55, v55
	v_cvt_pk_bf16_f32 v50, v51, v50
	v_mfma_f32_16x16x32_bf16 v[46:49], v[18:21], v[78:81], v[46:49]
	v_add_f32_e32 v53, 1.0, v53
	v_add_f32_e32 v51, 1.0, v55
	v_rcp_f32_e32 v53, v53
	v_rcp_f32_e32 v51, v51
	v_mfma_f32_16x16x32_bf16 v[42:45], v[22:25], v[78:81], v[42:45]
	v_mul_f32_e32 v52, v53, v52
	v_add_f32_e32 v53, v64, v0
	v_mul_f32_e32 v51, v51, v54
	v_add_f32_e32 v0, v65, v0
	v_mul_f32_e32 v52, v52, v53
	v_mul_f32_e32 v0, v51, v0
	v_cvt_pk_bf16_f32 v51, v52, v0
	global_store_dwordx2 v[60:61], v[50:51], off offset:96
	global_load_dword v0, v76, s[12:13] offset:128
	global_load_dwordx2 v[54:55], v[72:73], off offset:32
	ds_read_b128 v[50:53], v77 offset:13248
	global_load_dwordx2 v[56:57], v[72:73], off offset:64
	global_load_dwordx2 v[58:59], v[72:73], off offset:96
	s_waitcnt vmcnt(8)
	v_lshlrev_b32_e32 v60, 16, v70
	s_waitcnt lgkmcnt(0)
	v_mfma_f32_16x16x32_bf16 v[26:29], v[30:33], v[50:53], v[26:29]
	v_mul_f32_e32 v30, v60, v60
	v_and_b32_e32 v61, 0xffff0000, v70
	v_fmamk_f32 v30, v30, 0xbdd2d3e7, v129
	v_mul_f32_e32 v31, v61, v61
	v_mul_f32_e32 v30, v30, v60
	v_fmamk_f32 v31, v31, 0xbdd2d3e7, v129
	v_mul_f32_e32 v31, v31, v61
	v_exp_f32_e32 v30, v30
	v_exp_f32_e32 v62, v31
	v_add_co_u32_e32 v32, vcc, s2, v68
	v_add_f32_e32 v30, 1.0, v30
	v_rcp_f32_e32 v63, v30
	v_add_f32_e32 v62, 1.0, v62
	v_rcp_f32_e32 v62, v62
	v_addc_co_u32_e32 v33, vcc, 0, v69, vcc
	v_mul_f32_e32 v60, v63, v60
	global_load_dwordx2 v[30:31], v[32:33], off
	v_mfma_f32_16x16x32_bf16 v[6:9], v[14:17], v[50:53], v[6:9]
	global_load_dwordx2 v[14:15], v[32:33], off offset:32
	s_waitcnt vmcnt(5)
	v_add_f32_e32 v38, v38, v0
	v_mul_f32_e32 v38, v60, v38
	v_mul_f32_e32 v60, v62, v61
	v_and_b32_e32 v62, 0xffff0000, v71
	v_mul_f32_e32 v63, v62, v62
	v_fmamk_f32 v63, v63, 0xbdd2d3e7, v129
	v_mul_f32_e32 v63, v63, v62
	v_add_f32_e32 v39, v39, v0
	v_exp_f32_e32 v63, v63
	v_mul_f32_e32 v39, v60, v39
	v_lshlrev_b32_e32 v60, 16, v71
	v_mul_f32_e32 v61, v60, v60
	v_fmamk_f32 v61, v61, 0xbdd2d3e7, v129
	v_mul_f32_e32 v61, v61, v60
	v_cvt_pk_bf16_f32 v38, v38, v39
	v_add_f32_e32 v39, 1.0, v63
	v_rcp_f32_e32 v39, v39
	v_exp_f32_e32 v61, v61
	v_add_f32_e32 v40, v40, v0
	v_mul_f32_e32 v39, v39, v62
	s_waitcnt vmcnt(4)
	v_lshlrev_b32_e32 v62, 16, v54
	v_and_b32_e32 v54, 0xffff0000, v54
	v_mul_f32_e32 v64, v54, v54
	v_add_f32_e32 v61, 1.0, v61
	v_mul_f32_e32 v63, v62, v62
	v_fmamk_f32 v64, v64, 0xbdd2d3e7, v129
	v_rcp_f32_e32 v61, v61
	v_fmamk_f32 v63, v63, 0xbdd2d3e7, v129
	v_mul_f32_e32 v64, v64, v54
	v_mul_f32_e32 v63, v63, v62
	v_exp_f32_e32 v64, v64
	v_mul_f32_e32 v60, v61, v60
	v_add_f32_e32 v41, v41, v0
	v_exp_f32_e32 v63, v63
	v_mul_f32_e32 v40, v60, v40
	v_mul_f32_e32 v39, v39, v41
	v_add_co_u32_e32 v60, vcc, s4, v66
	v_cvt_pk_bf16_f32 v39, v40, v39
	s_nop 0
	v_addc_co_u32_e32 v61, vcc, 0, v67, vcc
	global_store_dwordx2 v[60:61], v[38:39], off
	v_add_f32_e32 v38, 1.0, v64
	v_add_f32_e32 v63, 1.0, v63
	v_rcp_f32_e32 v38, v38
	v_rcp_f32_e32 v63, v63
	v_add_f32_e32 v35, v35, v0
	v_add_f32_e32 v34, v34, v0
	v_mul_f32_e32 v38, v38, v54
	v_mul_f32_e32 v39, v63, v62
	v_mul_f32_e32 v35, v38, v35
	v_lshlrev_b32_e32 v38, 16, v55
	v_and_b32_e32 v54, 0xffff0000, v55
	v_mul_f32_e32 v34, v39, v34
	v_mul_f32_e32 v39, v38, v38
	v_mul_f32_e32 v55, v54, v54
	v_fmamk_f32 v39, v39, 0xbdd2d3e7, v129
	v_fmamk_f32 v55, v55, 0xbdd2d3e7, v129
	v_mul_f32_e32 v39, v39, v38
	v_mul_f32_e32 v55, v55, v54
	v_exp_f32_e32 v39, v39
	v_exp_f32_e32 v55, v55
	v_cvt_pk_bf16_f32 v34, v34, v35
	v_add_f32_e32 v36, v36, v0
	v_add_f32_e32 v39, 1.0, v39
	v_add_f32_e32 v35, 1.0, v55
	v_rcp_f32_e32 v39, v39
	v_rcp_f32_e32 v35, v35
	v_add_f32_e32 v37, v37, v0
	v_lshl_add_u64 v[40:41], v[66:67], 0, s[0:1]
	v_mul_f32_e32 v38, v39, v38
	v_mul_f32_e32 v35, v35, v54
	v_mul_f32_e32 v36, v38, v36
	v_mul_f32_e32 v35, v35, v37
	v_cvt_pk_bf16_f32 v35, v36, v35
	s_waitcnt vmcnt(4)
	v_lshlrev_b32_e32 v36, 16, v56
	v_mul_f32_e32 v37, v36, v36
	v_and_b32_e32 v38, 0xffff0000, v56
	v_fmamk_f32 v37, v37, 0xbdd2d3e7, v129
	v_mul_f32_e32 v39, v38, v38
	v_mul_f32_e32 v37, v37, v36
	v_fmamk_f32 v39, v39, 0xbdd2d3e7, v129
	v_mul_f32_e32 v39, v39, v38
	v_exp_f32_e32 v37, v37
	v_exp_f32_e32 v39, v39
	global_store_dwordx2 v[40:41], v[34:35], off offset:32
	v_add_f32_e32 v37, 1.0, v37
	v_rcp_f32_e32 v37, v37
	v_add_f32_e32 v34, 1.0, v39
	v_rcp_f32_e32 v34, v34
	v_mfma_f32_16x16x32_bf16 v[2:5], v[18:21], v[50:53], v[2:5]
	v_mul_f32_e32 v35, v37, v36
	v_add_f32_e32 v36, v46, v0
	v_mul_f32_e32 v35, v35, v36
	v_mul_f32_e32 v34, v34, v38
	v_add_f32_e32 v36, v47, v0
	v_mul_f32_e32 v34, v34, v36
	v_lshlrev_b32_e32 v36, 16, v57
	v_mul_f32_e32 v37, v36, v36
	v_and_b32_e32 v38, 0xffff0000, v57
	v_fmamk_f32 v37, v37, 0xbdd2d3e7, v129
	v_mul_f32_e32 v39, v38, v38
	v_mul_f32_e32 v37, v37, v36
	v_fmamk_f32 v39, v39, 0xbdd2d3e7, v129
	v_mul_f32_e32 v39, v39, v38
	v_exp_f32_e32 v37, v37
	v_exp_f32_e32 v39, v39
	v_cvt_pk_bf16_f32 v34, v35, v34
	v_add_f32_e32 v37, 1.0, v37
	v_rcp_f32_e32 v37, v37
	v_add_f32_e32 v35, 1.0, v39
	v_rcp_f32_e32 v35, v35
	s_waitcnt vmcnt(3)
	v_lshlrev_b32_e32 v20, 16, v30
	v_mul_f32_e32 v36, v37, v36
	v_add_f32_e32 v37, v48, v0
	v_mul_f32_e32 v36, v36, v37
	v_mul_f32_e32 v35, v35, v38
	v_add_f32_e32 v37, v49, v0
	v_mul_f32_e32 v35, v35, v37
	v_cvt_pk_bf16_f32 v35, v36, v35
	v_lshlrev_b32_e32 v36, 16, v58
	v_mul_f32_e32 v37, v36, v36
	v_and_b32_e32 v38, 0xffff0000, v58
	v_fmamk_f32 v37, v37, 0xbdd2d3e7, v129
	v_mul_f32_e32 v39, v38, v38
	v_mul_f32_e32 v37, v37, v36
	v_fmamk_f32 v39, v39, 0xbdd2d3e7, v129
	v_mul_f32_e32 v39, v39, v38
	v_exp_f32_e32 v37, v37
	v_exp_f32_e32 v39, v39
	global_store_dwordx2 v[40:41], v[34:35], off offset:64
	v_add_f32_e32 v37, 1.0, v37
	v_rcp_f32_e32 v37, v37
	v_add_f32_e32 v34, 1.0, v39
	v_rcp_f32_e32 v34, v34
	v_mul_f32_e32 v21, v20, v20
	v_mul_f32_e32 v35, v37, v36
	v_add_f32_e32 v36, v42, v0
	v_mul_f32_e32 v35, v35, v36
	v_mul_f32_e32 v34, v34, v38
	v_add_f32_e32 v36, v43, v0
	v_mul_f32_e32 v34, v34, v36
	v_lshlrev_b32_e32 v36, 16, v59
	v_and_b32_e32 v38, 0xffff0000, v59
	v_mul_f32_e32 v37, v36, v36
	v_mul_f32_e32 v39, v38, v38
	v_fmamk_f32 v37, v37, 0xbdd2d3e7, v129
	v_fmamk_f32 v39, v39, 0xbdd2d3e7, v129
	v_mul_f32_e32 v37, v37, v36
	v_mul_f32_e32 v39, v39, v38
	v_exp_f32_e32 v37, v37
	v_exp_f32_e32 v39, v39
	v_cvt_pk_bf16_f32 v34, v35, v34
	v_and_b32_e32 v30, 0xffff0000, v30
	v_add_f32_e32 v37, 1.0, v37
	v_add_f32_e32 v35, 1.0, v39
	v_rcp_f32_e32 v37, v37
	v_rcp_f32_e32 v35, v35
	v_fmamk_f32 v21, v21, 0xbdd2d3e7, v129
	v_mul_f32_e32 v21, v21, v20
	v_mul_f32_e32 v36, v37, v36
	v_add_f32_e32 v37, v44, v0
	v_mul_f32_e32 v35, v35, v38
	v_add_f32_e32 v0, v45, v0
	v_mul_f32_e32 v36, v36, v37
	v_mul_f32_e32 v0, v35, v0
	v_cvt_pk_bf16_f32 v35, v36, v0
	global_store_dwordx2 v[40:41], v[34:35], off offset:96
	global_load_dword v0, v76, s[12:13] offset:192
	global_load_dwordx2 v[16:17], v[32:33], off offset:64
	global_load_dwordx2 v[18:19], v[32:33], off offset:96
	v_mul_f32_e32 v32, v30, v30
	v_fmamk_f32 v32, v32, 0xbdd2d3e7, v129
	v_mul_f32_e32 v32, v32, v30
	v_exp_f32_e32 v21, v21
	v_exp_f32_e32 v32, v32
	v_mfma_f32_16x16x32_bf16 v[10:13], v[22:25], v[50:53], v[10:13]
	v_add_f32_e32 v21, 1.0, v21
	v_rcp_f32_e32 v21, v21
	v_add_f32_e32 v22, 1.0, v32
	v_rcp_f32_e32 v22, v22
	v_and_b32_e32 v24, 0xffff0000, v31
	v_mul_f32_e32 v20, v21, v20
	v_mul_f32_e32 v25, v24, v24
	v_fmamk_f32 v25, v25, 0xbdd2d3e7, v129
	v_mul_f32_e32 v25, v25, v24
	v_exp_f32_e32 v25, v25
	s_mov_b64 s[0:1], 0x5d000
	s_waitcnt vmcnt(2)
	v_add_f32_e32 v21, v26, v0
	v_mul_f32_e32 v20, v20, v21
	v_mul_f32_e32 v21, v22, v30
	v_add_f32_e32 v22, v27, v0
	v_mul_f32_e32 v21, v21, v22
	v_lshlrev_b32_e32 v22, 16, v31
	v_mul_f32_e32 v23, v22, v22
	v_fmamk_f32 v23, v23, 0xbdd2d3e7, v129
	v_mul_f32_e32 v23, v23, v22
	v_exp_f32_e32 v23, v23
	v_lshlrev_b32_e32 v26, 16, v14
	v_and_b32_e32 v14, 0xffff0000, v14
	v_cvt_pk_bf16_f32 v20, v20, v21
	v_add_f32_e32 v23, 1.0, v23
	v_rcp_f32_e32 v23, v23
	v_add_f32_e32 v21, 1.0, v25
	v_mul_f32_e32 v27, v26, v26
	v_rcp_f32_e32 v21, v21
	v_mul_f32_e32 v22, v23, v22
	v_add_f32_e32 v23, v28, v0
	v_mul_f32_e32 v28, v14, v14
	v_fmamk_f32 v28, v28, 0xbdd2d3e7, v129
	v_fmamk_f32 v27, v27, 0xbdd2d3e7, v129
	v_mul_f32_e32 v28, v28, v14
	v_mul_f32_e32 v27, v27, v26
	v_exp_f32_e32 v28, v28
	v_mul_f32_e32 v22, v22, v23
	v_mul_f32_e32 v21, v21, v24
	v_add_f32_e32 v23, v29, v0
	v_exp_f32_e32 v27, v27
	v_mul_f32_e32 v21, v21, v23
	v_add_co_u32_e32 v24, vcc, s2, v66
	v_cvt_pk_bf16_f32 v21, v22, v21
	s_nop 0
	v_addc_co_u32_e32 v25, vcc, 0, v67, vcc
	global_store_dwordx2 v[24:25], v[20:21], off
	v_add_f32_e32 v20, 1.0, v28
	v_add_f32_e32 v27, 1.0, v27
	v_rcp_f32_e32 v20, v20
	v_rcp_f32_e32 v27, v27
	v_add_f32_e32 v7, v7, v0
	v_add_f32_e32 v6, v6, v0
	v_mul_f32_e32 v14, v20, v14
	v_mul_f32_e32 v21, v27, v26
	v_mul_f32_e32 v7, v14, v7
	v_lshlrev_b32_e32 v14, 16, v15
	v_and_b32_e32 v15, 0xffff0000, v15
	v_mul_f32_e32 v6, v21, v6
	v_mul_f32_e32 v20, v14, v14
	v_mul_f32_e32 v21, v15, v15
	v_fmamk_f32 v20, v20, 0xbdd2d3e7, v129
	v_fmamk_f32 v21, v21, 0xbdd2d3e7, v129
	v_mul_f32_e32 v20, v20, v14
	v_mul_f32_e32 v21, v21, v15
	v_exp_f32_e32 v20, v20
	v_exp_f32_e32 v21, v21
	v_cvt_pk_bf16_f32 v6, v6, v7
	v_add_f32_e32 v8, v8, v0
	v_add_f32_e32 v20, 1.0, v20
	v_add_f32_e32 v7, 1.0, v21
	v_rcp_f32_e32 v20, v20
	v_rcp_f32_e32 v7, v7
	v_add_f32_e32 v9, v9, v0
	v_lshl_add_u64 v[22:23], v[66:67], 0, s[0:1]
	v_mul_f32_e32 v14, v20, v14
	v_mul_f32_e32 v7, v7, v15
	v_mul_f32_e32 v8, v14, v8
	v_mul_f32_e32 v7, v7, v9
	s_waitcnt vmcnt(2)
	v_and_b32_e32 v14, 0xffff0000, v16
	v_cvt_pk_bf16_f32 v7, v8, v7
	v_lshlrev_b32_e32 v8, 16, v16
	v_mul_f32_e32 v15, v14, v14
	v_mul_f32_e32 v9, v8, v8
	v_fmamk_f32 v15, v15, 0xbdd2d3e7, v129
	v_fmamk_f32 v9, v9, 0xbdd2d3e7, v129
	v_mul_f32_e32 v15, v15, v14
	v_mul_f32_e32 v9, v9, v8
	v_exp_f32_e32 v15, v15
	v_exp_f32_e32 v9, v9
	global_store_dwordx2 v[22:23], v[6:7], off offset:32
	v_add_f32_e32 v3, v3, v0
	v_add_f32_e32 v6, 1.0, v15
	v_add_f32_e32 v9, 1.0, v9
	v_rcp_f32_e32 v6, v6
	v_rcp_f32_e32 v9, v9
	v_add_f32_e32 v2, v2, v0
	v_add_f32_e32 v4, v4, v0
	v_mul_f32_e32 v6, v6, v14
	v_mul_f32_e32 v7, v9, v8
	v_mul_f32_e32 v3, v6, v3
	v_lshlrev_b32_e32 v6, 16, v17
	v_and_b32_e32 v8, 0xffff0000, v17
	v_mul_f32_e32 v2, v7, v2
	v_mul_f32_e32 v7, v6, v6
	v_mul_f32_e32 v9, v8, v8
	v_fmamk_f32 v7, v7, 0xbdd2d3e7, v129
	v_fmamk_f32 v9, v9, 0xbdd2d3e7, v129
	v_mul_f32_e32 v7, v7, v6
	v_mul_f32_e32 v9, v9, v8
	v_exp_f32_e32 v7, v7
	v_exp_f32_e32 v9, v9
	v_cvt_pk_bf16_f32 v2, v2, v3
	v_add_f32_e32 v5, v5, v0
	v_add_f32_e32 v7, 1.0, v7
	v_add_f32_e32 v3, 1.0, v9
	v_rcp_f32_e32 v7, v7
	v_rcp_f32_e32 v3, v3
	s_lshl_b32 s0, s38, 6
	s_and_b32 s2, s0, 0x3fc0
	v_mul_f32_e32 v6, v7, v6
	v_mul_f32_e32 v3, v3, v8
	v_mul_f32_e32 v4, v6, v4
	v_mul_f32_e32 v3, v3, v5
	v_cvt_pk_bf16_f32 v3, v4, v3
	s_waitcnt vmcnt(2)
	v_lshlrev_b32_e32 v4, 16, v18
	v_mul_f32_e32 v5, v4, v4
	v_and_b32_e32 v6, 0xffff0000, v18
	v_fmamk_f32 v5, v5, 0xbdd2d3e7, v129
	v_mul_f32_e32 v7, v6, v6
	v_mul_f32_e32 v5, v5, v4
	v_fmamk_f32 v7, v7, 0xbdd2d3e7, v129
	v_mul_f32_e32 v7, v7, v6
	v_exp_f32_e32 v5, v5
	v_exp_f32_e32 v7, v7
	global_store_dwordx2 v[22:23], v[2:3], off offset:64
	v_add_f32_e32 v5, 1.0, v5
	v_rcp_f32_e32 v5, v5
	v_add_f32_e32 v2, 1.0, v7
	v_rcp_f32_e32 v2, v2
	s_lshr_b32 s0, s38, 2
	v_mul_f32_e32 v3, v5, v4
	v_add_f32_e32 v4, v10, v0
	v_mul_f32_e32 v3, v3, v4
	v_mul_f32_e32 v2, v2, v6
	v_add_f32_e32 v4, v11, v0
	v_mul_f32_e32 v2, v2, v4
	v_lshlrev_b32_e32 v4, 16, v19
	v_and_b32_e32 v6, 0xffff0000, v19
	v_mul_f32_e32 v5, v4, v4
	v_mul_f32_e32 v7, v6, v6
	v_fmamk_f32 v5, v5, 0xbdd2d3e7, v129
	v_fmamk_f32 v7, v7, 0xbdd2d3e7, v129
	v_mul_f32_e32 v5, v5, v4
	v_mul_f32_e32 v7, v7, v6
	v_exp_f32_e32 v5, v5
	v_exp_f32_e32 v7, v7
	v_cvt_pk_bf16_f32 v2, v3, v2
	s_and_b32 s4, s0, 64
	v_add_f32_e32 v5, 1.0, v5
	v_add_f32_e32 v3, 1.0, v7
	v_rcp_f32_e32 v5, v5
	v_rcp_f32_e32 v3, v3
	s_lshl_b32 s88, s4, 1
	s_mov_b64 s[0:1], 0x1b00
	v_mul_f32_e32 v4, v5, v4
	v_add_f32_e32 v5, v12, v0
	v_mul_f32_e32 v3, v3, v6
	v_add_f32_e32 v0, v13, v0
	v_mul_f32_e32 v4, v4, v5
	v_mul_f32_e32 v0, v3, v0
	v_cvt_pk_bf16_f32 v3, v4, v0
	v_mov_b32_e32 v0, v194
	global_store_dwordx2 v[22:23], v[2:3], off offset:96
	s_barrier
	s_nop 0
	v_bfe_u32 v12, v0, 2, 6
	v_lshlrev_b32_e32 v0, 4, v0
	v_and_b32_e32 v10, 48, v0
	v_or_b32_e32 v0, s2, v12
	v_mul_u32_u24_e32 v0, 0xf80, v0
	v_lshlrev_b32_e32 v0, 1, v0
	v_lshl_add_u64 v[2:3], s[46:47], 0, v[0:1]
	v_lshl_add_u64 v[2:3], v[2:3], 0, s[88:89]
	v_lshlrev_b32_e32 v0, 1, v10
	v_lshl_add_u64 v[6:7], v[2:3], 0, v[0:1]
	v_add_co_u32_e32 v2, vcc, s68, v6
	v_mul_u32_u24_e32 v10, 0x48, v10
	s_nop 0
	v_addc_co_u32_e32 v3, vcc, 0, v7, vcc
	global_load_dwordx4 v[2:5], v[2:3], off offset:2816
	v_lshl_add_u64 v[6:7], v[6:7], 0, s[0:1]
	global_load_dwordx4 v[6:9], v[6:7], off offset:16
	v_lshlrev_b32_e32 v10, 1, v10
	v_lshlrev_b32_e32 v11, 1, v12
	v_add3_u32 v13, s15, v10, v11
	v_add3_u32 v10, s15, v11, v10
	s_lshl_b32 s88, s2, 1
	s_waitcnt vmcnt(1)
	ds_write_b16 v13, v2
	ds_write_b16_d16_hi v10, v2 offset:144
	ds_write_b16 v13, v3 offset:288
	ds_write_b16_d16_hi v10, v3 offset:432
	ds_write_b16 v13, v4 offset:576
	ds_write_b16_d16_hi v10, v4 offset:720
	ds_write_b16 v13, v5 offset:864
	ds_write_b16_d16_hi v10, v5 offset:1008
	s_waitcnt vmcnt(0)
	ds_write_b16 v13, v6 offset:1152
	ds_write_b16_d16_hi v10, v6 offset:1296
	ds_write_b16 v13, v7 offset:1440
	ds_write_b16_d16_hi v10, v7 offset:1584
	ds_write_b16 v13, v8 offset:1728
	ds_write_b16_d16_hi v10, v8 offset:1872
	ds_write_b16 v13, v9 offset:2016
	ds_write_b16_d16_hi v10, v9 offset:2160
	v_or_b32_e32 v2, s4, v12
	v_lshlrev_b32_e32 v2, 15, v2
	v_mov_b32_e32 v3, v1
	v_lshl_add_u64 v[10:11], s[48:49], 0, v[2:3]
	v_mul_u32_u24_e32 v2, 0x90, v12
	v_add3_u32 v6, s15, v2, v0
	s_waitcnt lgkmcnt(0)
	s_barrier
	ds_read_b128 v[2:5], v6
	ds_read_b128 v[6:9], v6 offset:16
	v_lshl_add_u64 v[10:11], v[10:11], 0, s[88:89]
	v_lshl_add_u64 v[10:11], v[10:11], 0, v[0:1]
	s_mov_b64 s[4:5], -1
	s_waitcnt lgkmcnt(1)
	global_store_dwordx4 v[10:11], v[2:5], off
	s_waitcnt lgkmcnt(0)
	global_store_dwordx4 v[10:11], v[6:9], off offset:16
	s_barrier
